# attention loop: K-fragment LDS prefetch + counted lgkmcnt in PV; waves 4-7 run reordered body; rows_qk: 8 heads batched (loads hoisted, interleaved reductions)
# speedup vs baseline: 1.0250x; 1.0250x over previous
; __device__ __forceinline__ void unpack8(u32x4 w, float* f) { f[0] = bflo(w.x); f[1] = bfhi(w.x); f[2] = bflo(w.y); f[3] = bfhi(w.y); f[4] = bflo(w.z); f[5] = bfhi(w.z); f[6] = bflo(w.w); f[7] = bfhi(w.w); }
; __device__ __forceinline__ void attn_body2(const bf16_t* __restrict__ Qb, const bf16_t* __restrict__ Kh, const bf16_t* __restrict__ Vh, ...
;     ...
;   { float csv[16], snv[16];
;     { const float posf = (float)(pos0 + wid * 32 + r32);
; #pragma unroll
;       for (int k = 0; k < 16; ++k) { const int i = 16 * (k >> 3) + 8 * hi + (k & 7);
;         const float inv = __expf(-(float)(2 * i) * (1.f / 64.f) * 9.210340371976184f);
;         sincosf(posf * inv, &snv[k], &csv[k]); asm volatile("" : "+v"(snv[k]), "+v"(csv[k])); } }
;     const bf16_t* Qw = Qb + (long)(wid * 32 + r32) * LDQ + hi * 8;
;     float xf[12][8]; float ss = 0.f;
; #pragma unroll
;     for (int d0 = 0; d0 < 12; ++d0) { unpack8(*reinterpret_cast<const u32x4*>(Qw + d0 * 16), xf[d0]);
; #pragma unroll
;       for (int e = 0; e < 8; ++e) ss += xf[d0][e] * xf[d0][e]; }
.LBB0_316:
	s_or_b64 exec, exec, s[0:1]
	v_mul_f32_e32 v4, v2, v2
	v_fmamk_f32 v5, v4, 0xb94c1982, v226
	v_fmaak_f32 v5, v4, v5, 0xbe2aaa9d
	v_mul_f32_e32 v5, v4, v5
	v_fmac_f32_e32 v2, v2, v5
	v_fmamk_f32 v5, v4, 0x37d75334, v227
	s_lshl_b32 s2, s28, s78
	v_fmaak_f32 v5, v4, v5, 0x3d2aabf7
	s_add_i32 s0, s12, s2
	v_fmaak_f32 v5, v4, v5, 0xbf000004
	s_and_b32 s3, s51, 7
	s_ashr_i32 s1, s0, 31
	s_mul_i32 s26, s0, 0xc00
	v_fma_f32 v4, v4, v5, 1.0
	v_lshlrev_b32_e32 v5, 30, v3
	v_and_b32_e32 v3, 1, v3
	s_mul_hi_i32 s12, s0, 0xc00
	s_add_u32 s26, s34, s26
	v_cmp_eq_u32_e32 vcc, 0, v3
	s_addc_u32 s12, s35, s12
	s_mul_i32 s30, s3, 0x180
	v_cndmask_b32_e32 v3, v4, v2, vcc
	v_xor_b32_e32 v1, v1, v0
	v_xor_b32_e32 v2, 0x80000000, v2
	s_add_u32 s26, s26, s30
	v_and_b32_e32 v6, 0x80000000, v5
	v_xor_b32_e32 v1, v1, v3
	v_cndmask_b32_e32 v2, v2, v4, vcc
	s_addc_u32 s27, s12, 0
	v_xor_b32_e32 v1, v1, v6
	v_bitop3_b32 v2, v2, v5, s31 bitop3:0x78
	v_cmp_class_f32_e64 vcc, v0, s52
	v_mov_b32_e32 v129, v133
	v_lshlrev_b32_e32 v132, 5, v247
	v_cndmask_b32_e32 v123, v240, v2, vcc
	v_cndmask_b32_e32 v121, v240, v1, vcc
	v_or_b32_e32 v2, s42, v246
	v_mov_b64_e32 v[0:1], s[26:27]
	v_mad_i64_i32 v[0:1], s[26:27], v2, s19, v[0:1]
	v_cmp_lt_i32_e32 vcc, v232, v231
	v_lshl_add_u64 v[16:17], v[0:1], 0, v[128:129]
	global_load_dwordx4 v[64:67], v[16:17], off offset:352
	global_load_dwordx4 v[88:91], v[16:17], off offset:256
	global_load_dwordx4 v[124:127], v[16:17], off offset:320
	global_load_dwordx4 v[144:147], v[16:17], off offset:224
	v_cndmask_b32_e32 v0, v228, v232, vcc
	global_load_dwordx4 v[152:155], v[16:17], off offset:192
	v_lshlrev_b32_e32 v198, 2, v0
	global_load_dwordx4 v[160:163], v[16:17], off offset:160
	global_load_dwordx4 v[56:59], v132, s[24:25] offset:16
	global_load_dwordx4 v[60:63], v132, s[24:25]
	global_load_dwordx4 v[40:43], v132, s[24:25] offset:80
	global_load_dwordx4 v[52:55], v132, s[24:25] offset:64
	global_load_dwordx4 v[24:27], v132, s[24:25] offset:144
	global_load_dwordx4 v[36:39], v132, s[24:25] offset:128
	global_load_dwordx4 v[0:3], v132, s[24:25] offset:208
	global_load_dwordx4 v[4:7], v132, s[24:25] offset:192
	global_load_dwordx4 v[168:171], v[16:17], off offset:128
	global_load_dwordx4 v[12:15], v132, s[24:25] offset:512
	global_load_dwordx4 v[8:11], v132, s[24:25] offset:528
	global_load_dwordx4 v[190:193], v[16:17], off offset:64
	global_load_dwordx4 v[194:197], v[16:17], off offset:96
	global_load_dwordx4 v[218:221], v[16:17], off
	global_load_dwordx4 v[200:203], v[16:17], off offset:32
	global_load_dwordx4 v[68:71], v[16:17], off offset:288
	global_load_dwordx4 v[48:51], v132, s[24:25] offset:576
	global_load_dwordx4 v[44:47], v132, s[24:25] offset:592
	global_load_dwordx4 v[32:35], v132, s[24:25] offset:640
	global_load_dwordx4 v[28:31], v132, s[24:25] offset:656
	global_load_dwordx4 v[20:23], v132, s[24:25] offset:704
	global_load_dwordx4 v[16:19], v132, s[24:25] offset:720
	v_readlane_b32 s26, v255, 27
	s_add_u32 s30, s26, s30
	s_addc_u32 s31, s53, 0
	s_lshl_b32 s43, s3, 7
	s_lshl_b32 s3, s3, 8
	s_add_u32 s26, s72, s3
	s_addc_u32 s27, s73, 0
	s_and_b32 s3, s56, 0x3fffffc0
	s_lshl_b32 s36, s29, 12
	v_and_b32_e32 v129, 63, v248
	s_lshl_b32 s37, s3, 2
	s_add_i32 s3, s36, 0
	v_lshlrev_b32_e32 v250, 4, v129
	s_add_i32 s3, s3, 0x14800
	s_mul_i32 s36, s29, 0xc0
	s_mov_b32 s52, 0x2aaaaaab
	s_movk_i32 s56, 0xffe8
	s_add_i32 s87, s37, 0
	s_lshl_b32 s28, s28, 8
	s_add_i32 s83, s28, 0x4000
	s_add_i32 s87, s87, 0x14000
	s_mov_b32 s58, s57
	s_mov_b32 s59, s57
	s_mov_b32 s60, s57
	s_mov_b32 s61, s57
	s_mov_b32 s62, s57
	s_mov_b32 s63, s57
	s_mov_b32 s64, s57
	s_mov_b32 s65, s57
	s_mov_b32 s66, s57
	s_mov_b32 s67, s57
	s_mov_b32 s68, s57
	s_mov_b32 s69, s57
	s_mov_b32 s70, s57
	s_mov_b32 s71, s57
	s_mov_b32 s12, 2
	s_waitcnt vmcnt(0)
	v_lshlrev_b32_e32 v156, 16, v162
	v_and_b32_e32 v157, 0xffff0000, v162
	v_lshlrev_b32_e32 v158, 16, v160
	v_and_b32_e32 v159, 0xffff0000, v160
	v_and_b32_e32 v130, 0xffff0000, v65
	v_lshlrev_b32_e32 v131, 16, v65
	v_lshlrev_b32_e32 v174, 16, v127
	v_and_b32_e32 v175, 0xffff0000, v127
	v_lshlrev_b32_e32 v178, 16, v126
	v_and_b32_e32 v179, 0xffff0000, v126
	s_waitcnt vmcnt(8)
	v_lshlrev_b32_e32 v244, 16, v218
	v_and_b32_e32 v245, 0xffff0000, v218
	v_lshlrev_b32_e32 v180, 16, v125
	v_and_b32_e32 v181, 0xffff0000, v125
	v_lshlrev_b32_e32 v186, 16, v124
	v_and_b32_e32 v187, 0xffff0000, v124
	v_lshlrev_b32_e32 v124, 16, v147
	v_and_b32_e32 v125, 0xffff0000, v147
	v_lshlrev_b32_e32 v140, 16, v146
	v_and_b32_e32 v141, 0xffff0000, v146
	v_lshlrev_b32_e32 v126, 16, v145
	v_and_b32_e32 v127, 0xffff0000, v145
	v_lshlrev_b32_e32 v142, 16, v144
	v_and_b32_e32 v143, 0xffff0000, v144
	v_lshlrev_b32_e32 v144, 16, v155
	v_and_b32_e32 v145, 0xffff0000, v155
	v_lshlrev_b32_e32 v146, 16, v154
	v_and_b32_e32 v147, 0xffff0000, v154
	v_lshlrev_b32_e32 v148, 16, v153
	v_and_b32_e32 v149, 0xffff0000, v153
	v_lshlrev_b32_e32 v150, 16, v152
	v_and_b32_e32 v151, 0xffff0000, v152
	v_lshlrev_b32_e32 v152, 16, v163
	v_and_b32_e32 v153, 0xffff0000, v163
	v_lshlrev_b32_e32 v154, 16, v161
	v_and_b32_e32 v155, 0xffff0000, v161
	v_lshlrev_b32_e32 v160, 16, v171
	v_and_b32_e32 v161, 0xffff0000, v171
	v_lshlrev_b32_e32 v164, 16, v170
	v_and_b32_e32 v165, 0xffff0000, v170
	v_lshlrev_b32_e32 v162, 16, v169
	v_and_b32_e32 v163, 0xffff0000, v169
	v_lshlrev_b32_e32 v166, 16, v168
	v_and_b32_e32 v167, 0xffff0000, v168
	v_lshlrev_b32_e32 v168, 16, v197
	v_and_b32_e32 v169, 0xffff0000, v197
	v_lshlrev_b32_e32 v206, 16, v196
	v_and_b32_e32 v207, 0xffff0000, v196
	v_lshlrev_b32_e32 v170, 16, v195
	v_and_b32_e32 v171, 0xffff0000, v195
	v_lshlrev_b32_e32 v208, 16, v194
	v_and_b32_e32 v209, 0xffff0000, v194
	v_lshlrev_b32_e32 v210, 16, v193
	v_and_b32_e32 v211, 0xffff0000, v193
	v_lshlrev_b32_e32 v212, 16, v192
	v_and_b32_e32 v213, 0xffff0000, v192
	v_lshlrev_b32_e32 v214, 16, v191
	v_and_b32_e32 v215, 0xffff0000, v191
	v_lshlrev_b32_e32 v216, 16, v190
	v_and_b32_e32 v217, 0xffff0000, v190
	s_waitcnt vmcnt(7)
; __device__ __forceinline__ void unpack8(u32x4 w, float* f) { f[0] = bflo(w.x); f[1] = bfhi(w.x); f[2] = bflo(w.y); f[3] = bfhi(w.y); f[4] = bflo(w.z); f[5] = bfhi(w.z); f[6] = bflo(w.w); f[7] = bfhi(w.w); }
; __device__ __forceinline__ void attn_body2(const bf16_t* __restrict__ Qb, const bf16_t* __restrict__ Kh, const bf16_t* __restrict__ Vh, ...
;     ...
;     float xf[12][8]; float ss = 0.f;
; #pragma unroll
;     for (int d0 = 0; d0 < 12; ++d0) { unpack8(*reinterpret_cast<const u32x4*>(Qw + d0 * 16), xf[d0]);
; #pragma unroll
;       for (int e = 0; e < 8; ++e) ss += xf[d0][e] * xf[d0][e]; }
;     ss += __shfl_xor(ss, 32);
;     const float rs = rsqrtf(ss * (1.f / 192.f) + EPS);
; #pragma unroll
;     for (int d0 = 0; d0 < 12; ++d0) { const f32x4 g0 = *(const f32x4*)(qn + d0 * 16 + hi * 8), g1 = *(const f32x4*)(qn + d0 * 16 + hi * 8 + 4);
	v_lshlrev_b32_e32 v196, 16, v203
	v_and_b32_e32 v197, 0xffff0000, v203
	v_lshlrev_b32_e32 v192, 16, v202
	v_and_b32_e32 v193, 0xffff0000, v202
	v_lshlrev_b32_e32 v194, 16, v201
	v_and_b32_e32 v195, 0xffff0000, v201
	v_lshlrev_b32_e32 v190, 16, v200
	v_and_b32_e32 v191, 0xffff0000, v200
	v_lshlrev_b32_e32 v204, 16, v221
	v_and_b32_e32 v205, 0xffff0000, v221
	v_lshlrev_b32_e32 v200, 16, v220
	v_and_b32_e32 v201, 0xffff0000, v220
	v_lshlrev_b32_e32 v202, 16, v219
	v_and_b32_e32 v203, 0xffff0000, v219
	s_waitcnt vmcnt(6)
	v_lshlrev_b32_e32 v218, 16, v71
	v_and_b32_e32 v219, 0xffff0000, v71
	v_lshlrev_b32_e32 v220, 16, v70
	v_and_b32_e32 v221, 0xffff0000, v70
	v_pk_mul_f32 v[70:71], v[244:245], v[244:245]
	v_lshlrev_b32_e32 v224, 16, v64
	v_add_f32_e32 v199, v70, v71
	v_pk_mul_f32 v[70:71], v[202:203], v[202:203]
	v_and_b32_e32 v225, 0xffff0000, v64
	v_add_f32_e32 v70, v70, v199
	v_add_f32_e32 v199, v71, v70
	v_pk_mul_f32 v[70:71], v[200:201], v[200:201]
	v_pk_mul_f32 v[64:65], v[126:127], v[126:127]
	v_add_f32_e32 v70, v70, v199
	v_add_f32_e32 v199, v71, v70
	v_pk_mul_f32 v[70:71], v[204:205], v[204:205]
	v_lshlrev_b32_e32 v222, 16, v69
	v_add_f32_e32 v70, v70, v199
	v_add_f32_e32 v199, v71, v70
	v_pk_mul_f32 v[70:71], v[190:191], v[190:191]
	v_and_b32_e32 v223, 0xffff0000, v69
	v_add_f32_e32 v70, v70, v199
	v_add_f32_e32 v199, v71, v70
	v_pk_mul_f32 v[70:71], v[194:195], v[194:195]
	v_lshlrev_b32_e32 v234, 16, v68
	v_add_f32_e32 v70, v70, v199
	v_add_f32_e32 v199, v71, v70
	v_pk_mul_f32 v[70:71], v[192:193], v[192:193]
	v_and_b32_e32 v235, 0xffff0000, v68
	v_add_f32_e32 v70, v70, v199
	v_add_f32_e32 v199, v71, v70
	v_pk_mul_f32 v[70:71], v[196:197], v[196:197]
	v_pk_mul_f32 v[68:69], v[140:141], v[140:141]
	v_add_f32_e32 v70, v70, v199
	v_add_f32_e32 v199, v71, v70
	v_pk_mul_f32 v[70:71], v[216:217], v[216:217]
	v_pk_mul_f32 v[172:173], v[124:125], v[124:125]
	v_add_f32_e32 v70, v70, v199
	v_add_f32_e32 v199, v71, v70
	v_pk_mul_f32 v[70:71], v[214:215], v[214:215]
	v_lshlrev_b32_e32 v188, 16, v88
	v_add_f32_e32 v70, v70, v199
	v_add_f32_e32 v199, v71, v70
	v_pk_mul_f32 v[70:71], v[212:213], v[212:213]
	v_and_b32_e32 v189, 0xffff0000, v88
	v_add_f32_e32 v70, v70, v199
	v_add_f32_e32 v199, v71, v70
	v_pk_mul_f32 v[70:71], v[210:211], v[210:211]
	v_lshlrev_b32_e32 v176, 16, v91
	v_add_f32_e32 v70, v70, v199
	v_add_f32_e32 v199, v71, v70
	v_pk_mul_f32 v[70:71], v[208:209], v[208:209]
	v_and_b32_e32 v177, 0xffff0000, v91
	v_add_f32_e32 v70, v70, v199
	v_add_f32_e32 v199, v71, v70
	v_pk_mul_f32 v[70:71], v[170:171], v[170:171]
	v_lshlrev_b32_e32 v182, 16, v90
	v_add_f32_e32 v70, v70, v199
	v_add_f32_e32 v199, v71, v70
	v_pk_mul_f32 v[70:71], v[206:207], v[206:207]
	v_and_b32_e32 v183, 0xffff0000, v90
	v_add_f32_e32 v70, v70, v199
	v_add_f32_e32 v199, v71, v70
	v_pk_mul_f32 v[70:71], v[168:169], v[168:169]
	v_pk_mul_f32 v[90:91], v[188:189], v[188:189]
	v_add_f32_e32 v70, v70, v199
	v_add_f32_e32 v199, v71, v70
	v_pk_mul_f32 v[70:71], v[166:167], v[166:167]
	v_lshlrev_b32_e32 v184, 16, v89
	v_add_f32_e32 v70, v70, v199
	v_add_f32_e32 v199, v71, v70
	v_pk_mul_f32 v[70:71], v[162:163], v[162:163]
	v_and_b32_e32 v185, 0xffff0000, v89
	v_add_f32_e32 v70, v70, v199
	v_add_f32_e32 v199, v71, v70
	v_pk_mul_f32 v[70:71], v[164:165], v[164:165]
	v_pk_mul_f32 v[86:87], v[184:185], v[184:185]
	v_add_f32_e32 v70, v70, v199
	v_add_f32_e32 v199, v71, v70
	v_pk_mul_f32 v[70:71], v[160:161], v[160:161]
	v_pk_mul_f32 v[82:83], v[182:183], v[182:183]
	v_add_f32_e32 v70, v70, v199
	v_add_f32_e32 v199, v71, v70
	v_pk_mul_f32 v[70:71], v[158:159], v[158:159]
	v_pk_mul_f32 v[78:79], v[176:177], v[176:177]
	v_add_f32_e32 v70, v70, v199
	v_add_f32_e32 v199, v71, v70
	v_pk_mul_f32 v[70:71], v[154:155], v[154:155]
	v_pk_mul_f32 v[88:89], v[186:187], v[186:187]
	v_add_f32_e32 v70, v70, v199
	v_add_f32_e32 v199, v71, v70
	v_pk_mul_f32 v[70:71], v[156:157], v[156:157]
	v_pk_mul_f32 v[84:85], v[180:181], v[180:181]
	v_add_f32_e32 v70, v70, v199
	v_add_f32_e32 v199, v71, v70
	v_pk_mul_f32 v[70:71], v[152:153], v[152:153]
	v_pk_mul_f32 v[80:81], v[178:179], v[178:179]
	v_add_f32_e32 v70, v70, v199
	v_add_f32_e32 v199, v71, v70
	v_pk_mul_f32 v[70:71], v[150:151], v[150:151]
	v_pk_mul_f32 v[76:77], v[174:175], v[174:175]
	v_add_f32_e32 v70, v70, v199
	v_add_f32_e32 v199, v71, v70
	v_pk_mul_f32 v[70:71], v[148:149], v[148:149]
	v_pk_mul_f32 v[74:75], v[130:131], v[130:131]
	v_add_f32_e32 v70, v70, v199
	v_add_f32_e32 v199, v71, v70
	v_pk_mul_f32 v[70:71], v[146:147], v[146:147]
	v_and_b32_e32 v138, 0xffff0000, v66
	v_add_f32_e32 v70, v70, v199
	v_add_f32_e32 v199, v71, v70
	v_pk_mul_f32 v[70:71], v[144:145], v[144:145]
	v_lshlrev_b32_e32 v139, 16, v66
	v_add_f32_e32 v70, v70, v199
	v_add_f32_e32 v199, v71, v70
	v_pk_mul_f32 v[70:71], v[142:143], v[142:143]
	v_pk_mul_f32 v[72:73], v[138:139], v[138:139]
	v_add_f32_e32 v70, v70, v199
	v_add_f32_e32 v199, v71, v70
	v_add_f32_e32 v64, v64, v199
	v_add_f32_e32 v199, v65, v64
	v_add_f32_e32 v68, v68, v199
	v_add_f32_e32 v199, v69, v68
	v_add_f32_e32 v172, v172, v199
	v_add_f32_e32 v199, v173, v172
	v_add_f32_e32 v90, v90, v199
	v_add_f32_e32 v199, v91, v90
	v_add_f32_e32 v86, v86, v199
	v_add_f32_e32 v86, v87, v86
	v_add_f32_e32 v82, v82, v86
	v_add_f32_e32 v82, v83, v82
	v_add_f32_e32 v78, v78, v82
	v_pk_mul_f32 v[172:173], v[234:235], v[234:235]
	v_add_f32_e32 v78, v79, v78
	v_add_f32_e32 v78, v172, v78
	v_pk_mul_f32 v[68:69], v[222:223], v[222:223]
	v_add_f32_e32 v78, v173, v78
	v_add_f32_e32 v68, v68, v78
	v_pk_mul_f32 v[64:65], v[220:221], v[220:221]
	v_add_f32_e32 v68, v69, v68
	v_add_f32_e32 v64, v64, v68
	v_pk_mul_f32 v[70:71], v[218:219], v[218:219]
	v_add_f32_e32 v64, v65, v64
	v_add_f32_e32 v64, v70, v64
	v_add_f32_e32 v64, v71, v64
	v_add_f32_e32 v64, v88, v64
	v_add_f32_e32 v64, v89, v64
	v_add_f32_e32 v64, v84, v64
	v_add_f32_e32 v64, v85, v64
	v_add_f32_e32 v64, v80, v64
	v_add_f32_e32 v64, v81, v64
	v_add_f32_e32 v64, v76, v64
	v_pk_mul_f32 v[90:91], v[224:225], v[224:225]
	v_add_f32_e32 v64, v77, v64
	v_add_f32_e32 v64, v90, v64
	v_add_f32_e32 v64, v91, v64
	v_add_f32_e32 v64, v75, v64
	v_add_f32_e32 v64, v74, v64
	v_and_b32_e32 v136, 0xffff0000, v67
	v_lshlrev_b32_e32 v137, 16, v67
	v_add_f32_e32 v64, v73, v64
	v_pk_mul_f32 v[66:67], v[136:137], v[136:137]
	v_add_f32_e32 v64, v72, v64
	v_add_f32_e32 v64, v67, v64
	v_add_f32_e32 v64, v66, v64
	ds_bpermute_b32 v65, v198, v64
	global_load_dwordx4 v[84:87], v132, s[24:25] offset:272
	global_load_dwordx4 v[88:91], v132, s[24:25] offset:256
	global_load_dwordx4 v[76:79], v132, s[24:25] offset:336
	global_load_dwordx4 v[80:83], v132, s[24:25] offset:320
	global_load_dwordx4 v[68:71], v132, s[24:25] offset:400
	global_load_dwordx4 v[72:75], v132, s[24:25] offset:384
	s_waitcnt lgkmcnt(0)
; __device__ __forceinline__ u32x4 pack8(const float* f) { u32x4 w; w.x = cvtpk(f[0], f[1]); w.y = cvtpk(f[2], f[3]); w.z = cvtpk(f[4], f[5]); w.w = cvtpk(f[6], f[7]); return w; }
; __device__ __forceinline__ void attn_body2(const bf16_t* __restrict__ Qb, const bf16_t* __restrict__ Kh, const bf16_t* __restrict__ Vh, ...
;     ...
;     ss += __shfl_xor(ss, 32);
;     const float rs = rsqrtf(ss * (1.f / 192.f) + EPS);
; #pragma unroll
;     for (int d0 = 0; d0 < 12; ++d0) { const f32x4 g0 = *(const f32x4*)(qn + d0 * 16 + hi * 8), g1 = *(const f32x4*)(qn + d0 * 16 + hi * 8 + 4);
; #pragma unroll
;       for (int e = 0; e < 4; ++e) { xf[d0][e] *= rs * g0[e]; xf[d0][4 + e] *= rs * g1[e]; } }
; #pragma unroll
;     for (int dd = 0; dd < 2; ++dd)
; #pragma unroll
;       for (int e = 0; e < 8; ++e) { const float sn = snv[8 * dd + e], cs = csv[8 * dd + e];
;         const float x1 = xf[8 + dd][e], x2 = xf[10 + dd][e];
;         xf[8 + dd][e] = x1 * cs - x2 * sn; xf[10 + dd][e] = x2 * cs + x1 * sn; }
; #pragma unroll
;     for (int d0 = 0; d0 < 8; ++d0) { const u32x4 w = pack8(xf[d0]); qr[d0] = *reinterpret_cast<const bf16x8*>(&w); }
; #pragma unroll
;     for (int d0 = 8; d0 < 12; ++d0) *reinterpret_cast<u32x4*>(qx + (d0 - 8) * 1024) = pack8(xf[d0]);
	v_add_f32_e32 v64, v64, v65
	v_fmamk_f32 v64, v64, 0x3baaaaab, v134
	v_mul_f32_e32 v65, 0x4b800000, v64
	v_cmp_gt_f32_e32 vcc, s93, v64
	s_nop 1
	v_cndmask_b32_e32 v64, v64, v65, vcc
	v_rsq_f32_e32 v64, v64
	s_nop 0
	v_mul_f32_e32 v65, 0x45800000, v64
	v_cndmask_b32_e32 v172, v64, v65, vcc
	v_pk_mul_f32 v[40:41], v[40:41], v[172:173] op_sel_hi:[1,0]
	s_waitcnt vmcnt(9)
	v_pk_mul_f32 v[32:33], v[32:33], v[172:173] op_sel_hi:[1,0]
	v_pk_mul_f32 v[192:193], v[40:41], v[192:193]
	v_pk_mul_f32 v[40:41], v[54:55], v[172:173] op_sel_hi:[1,0]
	v_pk_mul_f32 v[12:13], v[12:13], v[172:173] op_sel_hi:[1,0]
	v_pk_mul_f32 v[194:195], v[40:41], v[194:195]
	v_pk_mul_f32 v[40:41], v[42:43], v[172:173] op_sel_hi:[1,0]
	v_pk_mul_f32 v[32:33], v[32:33], v[186:187]
	v_pk_mul_f32 v[34:35], v[34:35], v[172:173] op_sel_hi:[1,0]
	v_pk_mul_f32 v[56:57], v[56:57], v[172:173] op_sel_hi:[1,0]
	v_pk_mul_f32 v[196:197], v[40:41], v[196:197]
	v_pk_mul_f32 v[12:13], v[12:13], v[188:189]
	v_pk_mul_f32 v[14:15], v[14:15], v[172:173] op_sel_hi:[1,0]
	s_waitcnt vmcnt(8)
	v_pk_mul_f32 v[28:29], v[28:29], v[172:173] op_sel_hi:[1,0]
	v_pk_mul_f32 v[34:35], v[34:35], v[180:181]
	v_pk_mul_f32 v[40:41], v[92:93], v[32:33]
	v_pk_mul_f32 v[32:33], v[94:95], v[32:33]
	v_pk_mul_f32 v[200:201], v[56:57], v[200:201]
	v_pk_mul_f32 v[56:57], v[62:63], v[172:173] op_sel_hi:[1,0]
	v_pk_mul_f32 v[24:25], v[24:25], v[172:173] op_sel_hi:[1,0]
	v_pk_mul_f32 v[8:9], v[8:9], v[172:173] op_sel_hi:[1,0]
	v_pk_mul_f32 v[14:15], v[14:15], v[184:185]
	v_pk_mul_f32 v[28:29], v[28:29], v[178:179]
	v_pk_mul_f32 v[30:31], v[30:31], v[172:173] op_sel_hi:[1,0]
	v_pk_fma_f32 v[40:41], v[94:95], v[12:13], v[40:41] neg_lo:[0,0,1] neg_hi:[0,0,1]
	v_pk_fma_f32 v[12:13], v[92:93], v[12:13], v[32:33]
	v_pk_mul_f32 v[32:33], v[96:97], v[34:35]
	v_pk_mul_f32 v[34:35], v[98:99], v[34:35]
	v_pk_mul_f32 v[202:203], v[56:57], v[202:203]
	v_pk_mul_f32 v[56:57], v[58:59], v[172:173] op_sel_hi:[1,0]
	v_pk_mul_f32 v[54:55], v[24:25], v[212:213]
	v_pk_mul_f32 v[24:25], v[38:39], v[172:173] op_sel_hi:[1,0]
	v_pk_mul_f32 v[8:9], v[8:9], v[182:183]
	v_pk_mul_f32 v[10:11], v[10:11], v[172:173] op_sel_hi:[1,0]
	v_pk_mul_f32 v[30:31], v[30:31], v[174:175]
	v_pk_fma_f32 v[32:33], v[98:99], v[14:15], v[32:33] neg_lo:[0,0,1] neg_hi:[0,0,1]
	v_pk_fma_f32 v[14:15], v[96:97], v[14:15], v[34:35]
	v_pk_mul_f32 v[34:35], v[100:101], v[28:29]
	v_pk_mul_f32 v[28:29], v[102:103], v[28:29]
	v_pk_mul_f32 v[204:205], v[56:57], v[204:205]
	v_pk_mul_f32 v[56:57], v[24:25], v[214:215]
	v_pk_mul_f32 v[24:25], v[26:27], v[172:173] op_sel_hi:[1,0]
	v_pk_mul_f32 v[10:11], v[10:11], v[176:177]
	s_waitcnt vmcnt(7)
	v_pk_mul_f32 v[20:21], v[20:21], v[172:173] op_sel_hi:[1,0]
	v_pk_fma_f32 v[34:35], v[102:103], v[8:9], v[34:35] neg_lo:[0,0,1] neg_hi:[0,0,1]
	v_pk_fma_f32 v[28:29], v[100:101], v[8:9], v[28:29]
	v_pk_mul_f32 v[8:9], v[104:105], v[30:31]
	v_pk_mul_f32 v[58:59], v[24:25], v[210:211]
	v_pk_mul_f32 v[24:25], v[48:49], v[172:173] op_sel_hi:[1,0]
	v_pk_mul_f32 v[20:21], v[20:21], v[224:225]
	v_pk_fma_f32 v[42:43], v[106:107], v[10:11], v[8:9] neg_lo:[0,0,1] neg_hi:[0,0,1]
	v_pk_mul_f32 v[8:9], v[106:107], v[30:31]
	v_pk_mul_f32 v[52:53], v[52:53], v[172:173] op_sel_hi:[1,0]
	v_pk_mul_f32 v[36:37], v[36:37], v[172:173] op_sel_hi:[1,0]
	v_pk_mul_f32 v[24:25], v[24:25], v[234:235]
	v_pk_mul_f32 v[22:23], v[22:23], v[172:173] op_sel_hi:[1,0]
	v_pk_fma_f32 v[30:31], v[104:105], v[10:11], v[8:9]
	v_pk_mul_f32 v[8:9], v[108:109], v[20:21]
	v_pk_mul_f32 v[190:191], v[52:53], v[190:191]
	v_pk_mul_f32 v[52:53], v[36:37], v[216:217]
	v_pk_mul_f32 v[26:27], v[44:45], v[172:173] op_sel_hi:[1,0]
	v_pk_mul_f32 v[36:37], v[50:51], v[172:173] op_sel_hi:[1,0]
	v_pk_mul_f32 v[22:23], v[22:23], v[130:131] op_sel:[0,1] op_sel_hi:[1,0]
	v_pk_fma_f32 v[44:45], v[110:111], v[24:25], v[8:9] neg_lo:[0,0,1] neg_hi:[0,0,1]
	v_pk_mul_f32 v[8:9], v[110:111], v[20:21]
	v_pk_mul_f32 v[36:37], v[36:37], v[222:223]
	s_waitcnt vmcnt(6)
	v_pk_mul_f32 v[16:17], v[16:17], v[172:173] op_sel_hi:[1,0]
	v_pk_fma_f32 v[20:21], v[108:109], v[24:25], v[8:9]
	v_pk_mul_f32 v[8:9], v[112:113], v[22:23]
	v_pk_mul_f32 v[16:17], v[16:17], v[138:139] op_sel:[0,1] op_sel_hi:[1,0]
	v_pk_fma_f32 v[24:25], v[114:115], v[36:37], v[8:9] neg_lo:[0,0,1] neg_hi:[0,0,1]
	v_pk_mul_f32 v[8:9], v[114:115], v[22:23]
	v_pk_mul_f32 v[26:27], v[26:27], v[220:221]
	v_pk_mul_f32 v[18:19], v[18:19], v[172:173] op_sel_hi:[1,0]
	v_pk_fma_f32 v[22:23], v[112:113], v[36:37], v[8:9]
	v_pk_mul_f32 v[8:9], v[116:117], v[16:17]
	v_pk_mul_f32 v[38:39], v[46:47], v[172:173] op_sel_hi:[1,0]
	v_pk_mul_f32 v[18:19], v[18:19], v[136:137] op_sel:[0,1] op_sel_hi:[1,0]
	v_pk_fma_f32 v[36:37], v[118:119], v[26:27], v[8:9] neg_lo:[0,0,1] neg_hi:[0,0,1]
	v_pk_mul_f32 v[8:9], v[118:119], v[16:17]
	v_pk_mul_f32 v[38:39], v[38:39], v[218:219]
	v_pk_fma_f32 v[16:17], v[116:117], v[26:27], v[8:9]
	v_pk_mul_f32 v[8:9], v[120:121], v[18:19]
	v_pk_mul_f32 v[60:61], v[60:61], v[172:173] op_sel_hi:[1,0]
	v_pk_fma_f32 v[26:27], v[122:123], v[38:39], v[8:9] neg_lo:[0,0,1] neg_hi:[0,0,1]
	v_pk_mul_f32 v[8:9], v[122:123], v[18:19]
	v_pk_mul_f32 v[4:5], v[4:5], v[172:173] op_sel_hi:[1,0]
	v_pk_mul_f32 v[0:1], v[0:1], v[172:173] op_sel_hi:[1,0]
	v_pk_fma_f32 v[18:19], v[120:121], v[38:39], v[8:9]
	v_add_u32_e32 v173, s3, v250
	v_cvt_pk_bf16_f32 v8, v40, v41
	v_cvt_pk_bf16_f32 v9, v32, v33
	v_cvt_pk_bf16_f32 v10, v34, v35
	v_cvt_pk_bf16_f32 v11, v42, v43
	v_pk_mul_f32 v[198:199], v[60:61], v[244:245]
	global_load_dwordx4 v[60:63], v132, s[24:25] offset:464
	global_load_dwordx4 v[64:67], v132, s[24:25] offset:448
	ds_write_b128 v173, v[8:11]
; __device__ __forceinline__ int v_rd_base(int lane) { return ((lane & 3) << 3) | (((lane >> 2) & 3) << 6) | (((lane >> 4) & 1) << 5) | (((lane >> 5) & 1) << 8); }
; #define ISSUE_K(j, stg) do { const long _k0 = TROW(j); const char* _kt = (const char*)Kh + _k0 * (LDK * 2); _Pragma("unroll") for (int _i = 0; _i < 3; ++_i) \
;     __builtin_amdgcn_global_load_lds((const unsigned*)(_kt + okk[_i]), (LAS unsigned*)(ldsL + A2_K + (stg) * SHM_K + (wid * 3 + _i) * 1024), 16, 0, 0); } while (0)
; #define WAITV(n) asm volatile("s_waitcnt vmcnt(" #n ")" ::: "memory")
; __device__ __forceinline__ void qkt(f32x16& p0, f32x16& p1, const char* Ks, const bf16x8* qr, const char* qx, int r32, int hi, int mode) {
;   p0 = f32x16{}; p1 = f32x16{};
; #pragma unroll
;   for (int d0 = 0; d0 < 12; ++d0) { const int cb = (d0 * 16 + hi * 8) * 2;
;     bf16x8 b0 = *reinterpret_cast<const bf16x8*>(Ks + KSWZ(r32, cb));
;     bf16x8 b1 = *reinterpret_cast<const bf16x8*>(Ks + KSWZ(32 + r32, cb));
;     const bf16x8 qf = d0 < 8 ? qr[d0 < 8 ? d0 : 0] : *reinterpret_cast<const bf16x8*>(qx + (d0 - 8) * 1024);
;     p0 = __builtin_amdgcn_mfma_f32_32x32x16_bf16(b0, qf, p0, 0, 0, 0);
;     p1 = __builtin_amdgcn_mfma_f32_32x32x16_bf16(b1, qf, p1, 0, 0, 0); }
; __device__ __forceinline__ void attn_body2(const bf16_t* __restrict__ Qb, const bf16_t* __restrict__ Kh, const bf16_t* __restrict__ Vh, ...
;     ...
;   float m_reg = -1e30f, l_reg = 0; f32x16 o[4] = {};
;   unsigned okk[3], ovv[2];
; #pragma unroll
;   for (int i = 0; i < 3; ++i) { const int sl = (wid * 3 + i) * 64 + lane, row = sl / 24, cp = sl - row * 24, ch = cp ^ (row & 7); okk[i] = (unsigned)(row * (LDK * 2) + ch * 16); }
; #pragma unroll
;   for (int i = 0; i < 2; ++i) { const int sl = (wid * 2 + i) * 64 + lane, sub = sl >> 5, kk = (sub >> 2) * 8 + ((sl & 31) >> 2), c = (sub & 3) * 32 + (sl & 3) * 8;
;     const int k = (kk & ~0xC) | ((kk & 4) << 1) | ((kk & 8) >> 1); ovv[i] = (unsigned)(k * (LDV * 2) + c * 2); }
;   const int vb0 = (int)(uintptr_t)V_lds + v_rd_base(lane);
;   const int NT = ntr + 2;
;     ...
;   f32x16 pA0, pA1, pB0, pB1; float mnA, mnB, alA, alB; bf16x8 pa0, pa1, pa2, pa3;
;   ISSUE_K(0, 0);
;   WAITV(0); ABAR();
;   ISSUE_K(1, 1); ISSUE_V(0, 0);
;   qkt(pA0, pA1, K_lds, qr, qx, r32, hi, 0); partialSM(pA0, pA1, m_reg, mnA, alA);
	v_cvt_pk_bf16_f32 v8, v44, v45
	v_cvt_pk_bf16_f32 v9, v24, v25
	v_cvt_pk_bf16_f32 v10, v36, v37
	v_cvt_pk_bf16_f32 v11, v26, v27
	ds_write_b128 v173, v[8:11] offset:1024
	v_cvt_pk_bf16_f32 v8, v12, v13
	v_cvt_pk_bf16_f32 v9, v14, v15
	v_cvt_pk_bf16_f32 v10, v28, v29
	v_cvt_pk_bf16_f32 v11, v30, v31
	ds_write_b128 v173, v[8:11] offset:2048
	v_cvt_pk_bf16_f32 v8, v20, v21
	v_cvt_pk_bf16_f32 v9, v22, v23
	v_cvt_pk_bf16_f32 v10, v16, v17
	v_cvt_pk_bf16_f32 v11, v18, v19
	ds_write_b128 v173, v[8:11] offset:3072
	v_or_b32_e32 v8, s36, v129
	v_mul_hi_i32 v9, v8, s52
	v_lshrrev_b32_e32 v10, 31, v9
	v_ashrrev_i32_e32 v9, 2, v9
	v_add_u32_e32 v10, v9, v10
	s_mul_i32 s3, s29, 3
	v_mad_u64_u32 v[8:9], s[36:37], v10, s56, v[8:9]
	v_bitop3_b32 v8, v8, v10, 7 bitop3:0x78
	v_mul_lo_u32 v9, v10, s19
	s_add_i32 s38, s3, 1
	v_lshl_add_u32 v132, v8, 4, v9
	v_lshl_or_b32 v8, s38, 6, v129
	v_mul_hi_i32 v9, v8, s52
	v_lshrrev_b32_e32 v10, 31, v9
	v_ashrrev_i32_e32 v9, 2, v9
	v_add_u32_e32 v10, v9, v10
	v_mad_u64_u32 v[8:9], s[36:37], v10, s56, v[8:9]
	v_bitop3_b32 v8, v8, v10, 7 bitop3:0x78
	v_mul_lo_u32 v9, v10, s19
	s_add_i32 s39, s3, 2
	v_lshl_add_u32 v130, v8, 4, v9
	v_lshl_or_b32 v8, s39, 6, v129
	v_mul_hi_i32 v9, v8, s52
	v_lshrrev_b32_e32 v10, 31, v9
	v_ashrrev_i32_e32 v9, 2, v9
	v_add_u32_e32 v10, v9, v10
	v_mad_u64_u32 v[8:9], s[36:37], v10, s56, v[8:9]
	v_bitop3_b32 v8, v8, v10, 7 bitop3:0x78
	v_mul_lo_u32 v9, v10, s19
	v_lshl_add_u32 v136, v8, 4, v9
	s_lshl_b32 s3, s29, 7
	v_and_b32_e32 v9, 32, v248
	v_lshlrev_b32_e32 v10, 3, v248
	s_ashr_i32 s3, s3, 4
	v_and_or_b32 v9, v10, 24, v9
	v_lshrrev_b32_e32 v10, 1, v248
	v_bfe_u32 v8, v248, 2, 2
	s_and_b32 s36, s3, 0x1ffff0
	v_and_b32_e32 v10, 8, v10
	s_lshr_b32 s3, s3, 1
	v_or3_b32 v8, v10, v8, s36
	v_and_or_b32 v8, s3, 4, v8
	s_ashr_i32 s3, s2, 31
	s_mul_i32 s36, s2, 0xc00
	s_mul_hi_i32 s37, s2, 0xc00
	s_add_u32 s36, s30, s36
	s_mul_i32 s52, s29, 0xc00
	s_addc_u32 s37, s31, s37
	s_add_i32 s94, s52, 0
	s_lshl_b32 s38, s38, 10
	s_add_i32 s95, s94, 0x8000
	s_add_i32 s75, s38, 0
	s_lshl_b32 s38, s39, 10
	s_mov_b32 m0, s95
	s_add_i32 s96, s75, 0x8000
	s_add_i32 s76, s38, 0
	global_load_lds_dwordx4 v132, s[36:37]
	s_mov_b32 m0, s96
	s_add_i32 s97, s76, 0x8000
	global_load_lds_dwordx4 v130, s[36:37]
	s_mov_b32 m0, s97
	v_lshlrev_b32_e32 v9, 1, v9
	global_load_lds_dwordx4 v136, s[36:37]
	s_or_b32 s36, s2, 64
	s_mul_hi_i32 s37, s36, 0xc00
	s_mulk_i32 s36, 0xc00
	s_add_u32 s36, s30, s36
	s_waitcnt vmcnt(0)
	s_addc_u32 s37, s31, s37
	s_add_i32 s94, s94, 0xe000
	s_waitcnt lgkmcnt(0)
	s_barrier
	s_mov_b32 m0, s94
	s_add_i32 s75, s75, 0xe000
	global_load_lds_dwordx4 v132, s[36:37]
	s_mov_b32 m0, s75
	s_add_i32 s76, s76, 0xe000
	global_load_lds_dwordx4 v130, s[36:37]
	s_mov_b32 m0, s76
	v_lshl_or_b32 v138, v8, 11, v9
	global_load_lds_dwordx4 v136, s[36:37]
	s_lshl_b64 s[36:37], s[2:3], 11
	s_add_u32 s36, s26, s36
	s_addc_u32 s37, s27, s37
	s_lshl_b32 s3, s29, 11
	s_add_i32 s3, s3, 0
	v_mov_b32_e32 v139, v133
	v_lshl_add_u64 v[8:9], s[36:37], 0, v[138:139]
	s_mov_b32 m0, s3
	s_add_i32 s29, s3, 0x400
	global_load_lds_dwordx4 v138, s[36:37]
	v_lshl_add_u64 v[8:9], v[8:9], 0, s[22:23]
	s_mov_b32 m0, s29
	v_mul_u32_u24_e32 v92, 0x180, v246
	global_load_lds_dwordx4 v[8:9], off
	v_lshlrev_b32_e32 v8, 4, v246
	v_and_b32_e32 v93, 0x70, v8
	v_bitop3_b32 v8, v128, v92, v93 bitop3:0xde
	v_add_u32_e32 v174, 0, v8
	ds_read_b128 v[8:11], v174 offset:32768
	ds_read_b128 v[12:15], v174 offset:45056
	v_pk_mul_f32 v[6:7], v[6:7], v[172:173] op_sel_hi:[1,0]
	v_cvt_pk_bf16_f32 v96, v198, v199
	v_pk_mul_f32 v[48:49], v[6:7], v[170:171]
	s_waitcnt vmcnt(0)
	v_pk_mul_f32 v[6:7], v[88:89], v[172:173] op_sel_hi:[1,0]
	v_cvt_pk_bf16_f32 v97, v202, v203
	v_pk_mul_f32 v[50:51], v[6:7], v[166:167]
	v_bitop3_b32 v6, v249, v92, v93 bitop3:0xde
	v_cvt_pk_bf16_f32 v98, v200, v201
	v_cvt_pk_bf16_f32 v99, v204, v205
	v_add_u32_e32 v166, 0, v6
	v_cvt_pk_bf16_f32 v100, v190, v191
	s_waitcnt lgkmcnt(0)
	v_mfma_f32_32x32x16_bf16 v[32:47], v[8:11], v[96:99], 0
	ds_read_b128 v[6:9], v166 offset:32768
	v_mul_f32_e64 v10, v84, v172
	v_mul_f32_e64 v11, v85, v172
	v_cvt_pk_bf16_f32 v101, v194, v195
	v_cvt_pk_bf16_f32 v102, v192, v193
	v_cvt_pk_bf16_f32 v103, v196, v197
	v_or_b32_e32 v88, 64, v128
	v_pk_mul_f32 v[84:85], v[90:91], v[172:173] op_sel_hi:[1,0]
	v_mfma_f32_32x32x16_bf16 v[16:31], v[12:15], v[96:99], 0
	v_mul_f32_e64 v14, v10, v164
	v_mul_f32_e64 v15, v11, v165
	ds_read_b128 v[10:13], v166 offset:45056
	v_mul_f32_e64 v84, v84, v162
	v_mul_f32_e64 v85, v85, v163
	v_cvt_pk_bf16_f32 v104, v52, v53
	v_cvt_pk_bf16_f32 v105, v56, v57
	v_cvt_pk_bf16_f32 v106, v54, v55
	v_cvt_pk_bf16_f32 v107, v58, v59
	s_waitcnt lgkmcnt(1)
	v_mfma_f32_32x32x16_bf16 v[32:47], v[6:9], v[100:103], v[32:47]
	v_mul_f32_e64 v6, v86, v172
	v_mul_f32_e64 v7, v87, v172
	v_or_b32_e32 v56, 0x60, v128
	v_mul_f32_e64 v86, v6, v160
	v_mul_f32_e64 v87, v7, v161
	v_bitop3_b32 v6, v88, v92, v93 bitop3:0xde
	v_add_u32_e32 v162, 0, v6
	ds_read_b128 v[6:9], v162 offset:32768
	s_movk_i32 s52, 0x80
	s_waitcnt lgkmcnt(1)
	v_mfma_f32_32x32x16_bf16 v[16:31], v[10:13], v[100:103], v[16:31]
	v_mul_f32_e64 v10, v80, v172
	v_mul_f32_e64 v11, v81, v172
	v_mul_f32_e64 v4, v4, v208
	v_mul_f32_e64 v5, v5, v209
	v_mul_f32_e64 v80, v10, v158
	v_mul_f32_e64 v81, v11, v159
	ds_read_b128 v[10:13], v162 offset:45056
	v_pk_mul_f32 v[2:3], v[2:3], v[172:173] op_sel_hi:[1,0]
	v_bitop3_b32 v57, v128, v93, s52 bitop3:0x36
	s_movk_i32 s37, 0x180
	s_waitcnt lgkmcnt(1)
; __device__ __forceinline__ u32x4 pack8(const float* f) { u32x4 w; w.x = cvtpk(f[0], f[1]); w.y = cvtpk(f[2], f[3]); w.z = cvtpk(f[4], f[5]); w.w = cvtpk(f[6], f[7]); return w; }
; __device__ __forceinline__ void qkt(f32x16& p0, f32x16& p1, const char* Ks, const bf16x8* qr, const char* qx, int r32, int hi, int mode) {
;   p0 = f32x16{}; p1 = f32x16{};
; #pragma unroll
;   for (int d0 = 0; d0 < 12; ++d0) { const int cb = (d0 * 16 + hi * 8) * 2;
;     bf16x8 b0 = *reinterpret_cast<const bf16x8*>(Ks + KSWZ(r32, cb));
;     bf16x8 b1 = *reinterpret_cast<const bf16x8*>(Ks + KSWZ(32 + r32, cb));
;     const bf16x8 qf = d0 < 8 ? qr[d0 < 8 ? d0 : 0] : *reinterpret_cast<const bf16x8*>(qx + (d0 - 8) * 1024);
;     p0 = __builtin_amdgcn_mfma_f32_32x32x16_bf16(b0, qf, p0, 0, 0, 0);
;     p1 = __builtin_amdgcn_mfma_f32_32x32x16_bf16(b1, qf, p1, 0, 0, 0); }
; __device__ __forceinline__ void attn_body2(const bf16_t* __restrict__ Qb, const bf16_t* __restrict__ Kh, const bf16_t* __restrict__ Vh, ...
;     ...
; #pragma unroll
;     for (int d0 = 0; d0 < 8; ++d0) { const u32x4 w = pack8(xf[d0]); qr[d0] = *reinterpret_cast<const bf16x8*>(&w); }
; #pragma unroll
;     for (int d0 = 8; d0 < 12; ++d0) *reinterpret_cast<u32x4*>(qx + (d0 - 8) * 1024) = pack8(xf[d0]);
	v_mfma_f32_32x32x16_bf16 v[32:47], v[6:9], v[104:107], v[32:47]
	v_mul_f32_e64 v6, v76, v172
	v_mul_f32_e64 v7, v77, v172
	v_mul_f32_e64 v0, v0, v206
	v_mul_f32_e64 v1, v1, v207
	v_mul_f32_e64 v52, v6, v156
	v_mul_f32_e64 v53, v7, v157
	v_bitop3_b32 v6, v56, v92, v93 bitop3:0xde
	v_add_u32_e32 v163, 0, v6
	ds_read_b128 v[6:9], v163 offset:32768
	v_pk_mul_f32 v[2:3], v[2:3], v[168:169]
	v_cvt_pk_bf16_f32 v108, v4, v5
	v_mad_u32_u24 v4, v246, s37, v57
	v_cvt_pk_bf16_f32 v109, v48, v49
	v_cvt_pk_bf16_f32 v110, v0, v1
	v_cvt_pk_bf16_f32 v111, v2, v3
	v_add_u32_e32 v164, 0, v4
	ds_read_b128 v[0:3], v163 offset:45056
	s_waitcnt lgkmcnt(1)
	v_mfma_f32_32x32x16_bf16 v[32:47], v[6:9], v[108:111], v[32:47]
	ds_read_b128 v[4:7], v164 offset:32768
	v_cvt_pk_bf16_f32 v112, v50, v51
	v_cvt_pk_bf16_f32 v113, v84, v85
	v_cvt_pk_bf16_f32 v114, v14, v15
	v_cvt_pk_bf16_f32 v115, v86, v87
	s_movk_i32 s36, 0xa0
	v_pk_mul_f32 v[48:49], v[68:69], v[172:173] op_sel_hi:[1,0]
	v_mfma_f32_32x32x16_bf16 v[16:31], v[10:13], v[104:107], v[16:31]
	v_bitop3_b32 v68, v128, v93, s36 bitop3:0x36
	v_mul_f32_e64 v14, v48, v146
	v_mul_f32_e64 v15, v49, v147
	v_mul_f32_e64 v54, v82, v172
	v_mul_f32_e64 v55, v83, v172
	v_pk_mul_f32 v[12:13], v[78:79], v[172:173] op_sel_hi:[1,0]
	v_pk_mul_f32 v[10:11], v[54:55], v[154:155]
	v_pk_mul_f32 v[8:9], v[12:13], v[152:153]
	v_cvt_pk_bf16_f32 v116, v80, v81
	s_waitcnt lgkmcnt(1)
	v_mfma_f32_32x32x16_bf16 v[16:31], v[0:3], v[108:111], v[16:31]
	ds_read_b128 v[0:3], v164 offset:45056
	v_cvt_pk_bf16_f32 v117, v10, v11
	v_cvt_pk_bf16_f32 v118, v52, v53
	v_cvt_pk_bf16_f32 v119, v8, v9
	s_movk_i32 s36, 0xc0
	v_pk_mul_f32 v[10:11], v[60:61], v[172:173] op_sel_hi:[1,0]
	v_bitop3_b32 v60, v128, v93, s36 bitop3:0x36
	s_waitcnt lgkmcnt(1)
	v_mfma_f32_32x32x16_bf16 v[32:47], v[4:7], v[112:115], v[32:47]
	v_mul_f32_e64 v4, v74, v172
	v_mul_f32_e64 v5, v75, v172
	v_mul_f32_e64 v12, v72, v172
	v_mul_f32_e64 v13, v73, v172
	v_mul_f32_e64 v48, v4, v148
	v_mul_f32_e64 v49, v5, v149
	v_mad_u32_u24 v4, v246, s37, v68
	v_add_u32_e32 v165, 0, v4
	ds_read_b128 v[4:7], v165 offset:32768
	v_pk_mul_f32 v[12:13], v[12:13], v[150:151]
	s_waitcnt lgkmcnt(1)
	v_mfma_f32_32x32x16_bf16 v[16:31], v[0:3], v[112:115], v[16:31]
	v_mul_f32_e64 v0, v70, v172
	v_mul_f32_e64 v1, v71, v172
	v_cvt_pk_bf16_f32 v120, v12, v13
	v_mul_f32_e64 v50, v0, v144
	v_mul_f32_e64 v51, v1, v145
	ds_read_b128 v[0:3], v165 offset:45056
	v_cvt_pk_bf16_f32 v121, v48, v49
	v_cvt_pk_bf16_f32 v122, v14, v15
	v_cvt_pk_bf16_f32 v123, v50, v51
	s_waitcnt lgkmcnt(1)
	v_mfma_f32_32x32x16_bf16 v[32:47], v[4:7], v[116:119], v[32:47]
	v_mul_f32_e64 v4, v64, v172
	v_mul_f32_e64 v5, v65, v172
	s_movk_i32 s36, 0xe0
	v_mul_f32_e64 v8, v4, v142
	v_mul_f32_e64 v9, v5, v143
	v_mad_u32_u24 v4, v246, s37, v60
	v_add_u32_e32 v167, 0, v4
	ds_read_b128 v[4:7], v167 offset:32768
	v_bitop3_b32 v61, v128, v93, s36 bitop3:0x36
	s_waitcnt lgkmcnt(1)
	v_mfma_f32_32x32x16_bf16 v[16:31], v[0:3], v[116:119], v[16:31]
	ds_read_b128 v[0:3], v167 offset:45056
	v_mul_f32_e64 v52, v66, v172
	v_mul_f32_e64 v53, v67, v172
	v_mul_f32_e64 v10, v10, v140
	v_mul_f32_e64 v11, v11, v141
	v_pk_mul_f32 v[12:13], v[52:53], v[126:127]
	v_cvt_pk_bf16_f32 v126, v10, v11
	s_movk_i32 s36, 0x100
	v_mad_u32_u24 v65, v246, s37, v241
	s_waitcnt lgkmcnt(1)
	v_mfma_f32_32x32x16_bf16 v[32:47], v[4:7], v[120:123], v[32:47]
	v_mul_f32_e64 v4, v62, v172
	v_mul_f32_e64 v5, v63, v172
	v_bitop3_b32 v62, v128, v93, s36 bitop3:0x36
	v_mul_f32_e64 v14, v4, v124
	v_mul_f32_e64 v15, v5, v125
	v_mad_u32_u24 v4, v246, s37, v61
	v_add_u32_e32 v168, 0, v4
	ds_read_b128 v[4:7], v168 offset:32768
	v_cvt_pk_bf16_f32 v124, v8, v9
	s_waitcnt lgkmcnt(1)
	v_mfma_f32_32x32x16_bf16 v[16:31], v[0:3], v[120:123], v[16:31]
	ds_read_b128 v[0:3], v168 offset:45056
	v_cvt_pk_bf16_f32 v125, v12, v13
	v_cvt_pk_bf16_f32 v127, v14, v15
	v_lshlrev_b32_e32 v8, 3, v129
	v_and_b32_e32 v9, 0xc0, v250
	v_and_or_b32 v9, v8, 24, v9
	s_movk_i32 s36, 0x120
	s_waitcnt lgkmcnt(1)
	v_mfma_f32_32x32x16_bf16 v[32:47], v[4:7], v[124:127], v[32:47]
	v_lshlrev_b32_e32 v4, 1, v129
	v_and_b32_e32 v10, 32, v4
	v_mad_u32_u24 v4, v246, s37, v62
	v_add_u32_e32 v169, 0, v4
	ds_read_b128 v[4:7], v169 offset:32768
	v_bitop3_b32 v64, v128, v93, s36 bitop3:0x36
	s_movk_i32 s36, 0x140
	s_waitcnt lgkmcnt(1)
	v_mfma_f32_32x32x16_bf16 v[16:31], v[0:3], v[124:127], v[16:31]
	v_and_b32_e32 v0, 0x100, v8
	v_or3_b32 v63, v9, v10, v0
	ds_read_b128 v[0:3], v173
	ds_read_b128 v[8:11], v169 offset:45056
	ds_read_b128 v[12:15], v173 offset:1024
	v_bitop3_b32 v67, v128, v93, s36 bitop3:0x36
	s_movk_i32 s36, 0x160
	v_bitop3_b32 v69, v128, v93, s36 bitop3:0x36
	s_waitcnt lgkmcnt(2)
	v_mfma_f32_32x32x16_bf16 v[32:47], v[4:7], v[0:3], v[32:47]
	v_mad_u32_u24 v4, v246, s37, v64
	v_add_u32_e32 v170, 0, v4
	ds_read_b128 v[4:7], v170 offset:32768
	v_bitop3_b32 v72, v56, v65, v93 bitop3:0xde
	v_add_u32_e32 v73, v57, v65
	s_cmp_lg_u32 0, -1
	s_cselect_b32 s38, 0, 0
	s_waitcnt lgkmcnt(2)
	v_mfma_f32_32x32x16_bf16 v[16:31], v[8:11], v[0:3], v[16:31]
	ds_read_b128 v[0:3], v170 offset:45056
	s_mov_b32 s56, s57
	v_add_u32_e32 v161, s38, v63
	v_bitop3_b32 v66, v128, v65, v93 bitop3:0xde
	v_bitop3_b32 v70, v249, v65, v93 bitop3:0xde
	v_bitop3_b32 v71, v88, v65, v93 bitop3:0xde
	v_mov_b32_e32 v131, v133
	s_waitcnt lgkmcnt(1)
	v_mfma_f32_32x32x16_bf16 v[32:47], v[4:7], v[12:15], v[32:47]
	v_mad_u32_u24 v4, v246, s37, v67
	v_add_u32_e32 v171, 0, v4
	ds_read_b128 v[4:7], v171 offset:32768
	v_mov_b32_e32 v137, v133
	v_lshl_add_u64 v[140:141], s[26:27], 0, v[138:139]
	v_mov_b32_e32 v158, 0
	s_waitcnt lgkmcnt(1)
	v_mfma_f32_32x32x16_bf16 v[16:31], v[0:3], v[12:15], v[16:31]
	ds_read_b128 v[0:3], v173 offset:2048
	ds_read_b128 v[8:11], v171 offset:45056
	ds_read_b128 v[48:51], v173 offset:3072
	s_waitcnt lgkmcnt(2)
	v_mfma_f32_32x32x16_bf16 v[32:47], v[4:7], v[0:3], v[32:47]
	v_mad_u32_u24 v4, v246, s37, v69
	v_add_u32_e32 v172, 0, v4
	ds_read_b128 v[52:55], v172 offset:32768
	ds_read_b128 v[56:59], v172 offset:45056
	s_waitcnt vmcnt(0)
	s_waitcnt lgkmcnt(0)
	s_barrier
; __device__ __forceinline__ void partialSM(f32x16& p0, f32x16& p1, float& m_reg, float& mn, float& alpha) {
;   constexpr float C = ATT_SCALE * 1.4426950408889634f;
;   float pmax = p0[0];
; #pragma unroll
;   for (int r = 1; r < 16; ++r) pmax = fmaxf(pmax, p0[r]);
; #pragma unroll
;   for (int r = 0; r < 16; ++r) pmax = fmaxf(pmax, p1[r]);
;   { auto rr = __builtin_amdgcn_permlane32_swap(__float_as_uint(pmax), __float_as_uint(pmax), false, false);
;     pmax = fmaxf(__uint_as_float(rr[0]), __uint_as_float(rr[1])); }
;   if (__builtin_expect(__all(pmax - m_reg <= ATT_THR / ATT_SCALE), 1)) { mn = m_reg; alpha = 1.f; }
;   else { mn = fmaxf(m_reg, pmax); alpha = __builtin_amdgcn_exp2f((m_reg - mn) * C); m_reg = mn; }
;   const float mnC = -mn * C;
; #pragma unroll
;   for (int r = 0; r < 16; ++r) p0[r] = fmaf(p0[r], C, mnC);
; #pragma unroll
;   for (int r = 0; r < 16; ++r) p1[r] = fmaf(p1[r], C, mnC);
; #pragma unroll
;   for (int r = 0; r < 16; ++r) p0[r] = __builtin_amdgcn_exp2f(p0[r]);
; }
	s_waitcnt lgkmcnt(3)
	v_mfma_f32_32x32x16_bf16 v[16:31], v[8:11], v[0:3], v[16:31]
	v_mov_b64_e32 v[0:1], s[56:57]
	v_mov_b64_e32 v[14:15], s[70:71]
	v_mov_b64_e32 v[2:3], s[58:59]
	v_mov_b64_e32 v[4:5], s[60:61]
	v_mov_b64_e32 v[6:7], s[62:63]
	v_mov_b64_e32 v[8:9], s[64:65]
	s_waitcnt lgkmcnt(1)
	v_mfma_f32_32x32x16_bf16 v[32:47], v[52:55], v[48:51], v[32:47]
	v_add_u32_e32 v52, v68, v65
	v_add_u32_e32 v53, v60, v65
	v_add_u32_e32 v54, v61, v65
	v_add_u32_e32 v55, v62, v65
	v_add_u32_e32 v60, v64, v65
	v_add_u32_e32 v61, v67, v65
	v_add_u32_e32 v62, v69, v65
	s_waitcnt lgkmcnt(0)
	v_mfma_f32_32x32x16_bf16 v[16:31], v[56:59], v[48:51], v[16:31]
	s_nop 2
	v_max_f32_e32 v48, v33, v33
	v_max_f32_e32 v49, v32, v32
	v_max_f32_e32 v48, v49, v48
	v_max3_f32 v48, v48, v34, v35
	v_max3_f32 v48, v48, v36, v37
	v_max3_f32 v48, v48, v38, v39
	v_max3_f32 v48, v48, v40, v41
	v_max3_f32 v48, v48, v42, v43
	v_max3_f32 v48, v48, v44, v45
	v_max3_f32 v48, v48, v46, v47
	v_max3_f32 v48, v48, v16, v17
	v_max3_f32 v48, v48, v18, v19
	v_max3_f32 v48, v48, v20, v21
	v_max3_f32 v48, v48, v22, v23
	v_max3_f32 v48, v48, v24, v25
	v_max3_f32 v48, v48, v26, v27
	v_max3_f32 v48, v48, v28, v29
	v_max3_f32 v48, v48, v30, v31
	v_mov_b32_e32 v49, v48
	s_nop 1
	v_permlane32_swap_b32_e32 v48, v49
	v_max_f32_e32 v49, v49, v49
	v_max_f32_e32 v48, v48, v48
	v_max_f32_e32 v48, v48, v49
	v_add_f32_e32 v49, 0x7149f2ca, v48
	v_max_f32_e32 v48, 0xf149f2ca, v48
	v_cmp_ge_f32_e32 vcc, s45, v49
	v_sub_f32_e32 v49, 0xf149f2ca, v48
	v_mul_f32_e32 v49, 0x3dd53b94, v49
	v_exp_f32_e32 v49, v49
	s_cmp_eq_u64 vcc, exec
	s_cselect_b64 vcc, -1, 0
	v_cndmask_b32_e32 v160, v48, v229, vcc
	v_mul_f32_e32 v48, 0xbdd53b94, v160
	v_cndmask_b32_e64 v175, v49, 1.0, vcc
	v_mov_b32_e32 v49, v48
	v_fmamk_f32 v32, v32, 0x3dd53b94, v48
	v_fmamk_f32 v33, v33, 0x3dd53b94, v48
	v_fmamk_f32 v34, v34, 0x3dd53b94, v48
	v_fmamk_f32 v35, v35, 0x3dd53b94, v48
	v_fmamk_f32 v36, v36, 0x3dd53b94, v48
	v_fmamk_f32 v37, v37, 0x3dd53b94, v48
	v_fmamk_f32 v38, v38, 0x3dd53b94, v48
	v_fmamk_f32 v39, v39, 0x3dd53b94, v48
	v_fmamk_f32 v40, v40, 0x3dd53b94, v48
	v_fmamk_f32 v41, v41, 0x3dd53b94, v48
	v_fmamk_f32 v42, v42, 0x3dd53b94, v48
	v_fmamk_f32 v43, v43, 0x3dd53b94, v48
	v_fmamk_f32 v44, v44, 0x3dd53b94, v48
	v_fmamk_f32 v45, v45, 0x3dd53b94, v48
	v_fmamk_f32 v46, v46, 0x3dd53b94, v48
	v_fmac_f32_e32 v49, 0x3dd53b94, v47
	v_exp_f32_e32 v199, v32
	v_exp_f32_e32 v200, v33
	v_exp_f32_e32 v201, v34
	v_exp_f32_e32 v203, v35
	v_exp_f32_e32 v204, v36
	v_exp_f32_e32 v206, v37
	v_exp_f32_e32 v202, v38
	v_exp_f32_e32 v205, v39
	v_exp_f32_e32 v191, v40
	v_exp_f32_e32 v193, v41
	v_exp_f32_e32 v194, v42
	v_exp_f32_e32 v197, v43
	v_exp_f32_e32 v192, v44
	v_exp_f32_e32 v195, v45
	v_exp_f32_e32 v196, v46
	v_exp_f32_e32 v198, v49
	s_addk_i32 s38, 0x4000
	v_mov_b64_e32 v[10:11], s[66:67]
	v_mov_b64_e32 v[12:13], s[68:69]
	v_pk_fma_f32 v[142:143], v[30:31], s[18:19], v[48:49] op_sel_hi:[1,0,0]
	v_pk_fma_f32 v[144:145], v[28:29], s[18:19], v[48:49] op_sel_hi:[1,0,0]
	v_pk_fma_f32 v[146:147], v[26:27], s[18:19], v[48:49] op_sel_hi:[1,0,0]
	v_pk_fma_f32 v[148:149], v[24:25], s[18:19], v[48:49] op_sel_hi:[1,0,0]
	v_pk_fma_f32 v[150:151], v[22:23], s[18:19], v[48:49] op_sel_hi:[1,0,0]
	v_pk_fma_f32 v[152:153], v[20:21], s[18:19], v[48:49] op_sel_hi:[1,0,0]
	v_pk_fma_f32 v[154:155], v[18:19], s[18:19], v[48:49] op_sel_hi:[1,0,0]
	v_pk_fma_f32 v[156:157], v[16:17], s[18:19], v[48:49] op_sel_hi:[1,0,0]
	v_add_u32_e32 v159, s38, v63
	v_mov_b64_e32 v[30:31], v[14:15]
	v_mov_b64_e32 v[46:47], v[14:15]
	v_mov_b64_e32 v[62:63], v[14:15]
	v_cmp_gt_u32_e64 s[36:37], 32, v129
	v_lshl_add_u32 v129, v246, 2, s87
	v_mov_b64_e32 v[28:29], v[12:13]
	v_mov_b64_e32 v[26:27], v[10:11]
	v_mov_b64_e32 v[24:25], v[8:9]
	v_mov_b64_e32 v[22:23], v[6:7]
	v_mov_b64_e32 v[20:21], v[4:5]
	v_mov_b64_e32 v[18:19], v[2:3]
	v_mov_b64_e32 v[16:17], v[0:1]
	v_mov_b64_e32 v[44:45], v[12:13]
	v_mov_b64_e32 v[42:43], v[10:11]
	v_mov_b64_e32 v[40:41], v[8:9]
	v_mov_b64_e32 v[38:39], v[6:7]
	v_mov_b64_e32 v[36:37], v[4:5]
	v_mov_b64_e32 v[34:35], v[2:3]
	v_mov_b64_e32 v[32:33], v[0:1]
	v_mov_b64_e32 v[60:61], v[12:13]
	v_mov_b64_e32 v[58:59], v[10:11]
	v_mov_b64_e32 v[56:57], v[8:9]
	v_mov_b64_e32 v[54:55], v[6:7]
	v_mov_b64_e32 v[52:53], v[4:5]
	v_mov_b64_e32 v[50:51], v[2:3]
	v_mov_b64_e32 v[48:49], v[0:1]
	v_add_u32_e32 v174, 0x2000, v174
	v_add_u32_e32 v166, 0x2000, v166
	v_add_u32_e32 v162, 0x2000, v162
	v_add_u32_e32 v163, 0x2000, v163
	v_add_u32_e32 v164, 0x2000, v164
	v_add_u32_e32 v165, 0x2000, v165
	v_add_u32_e32 v167, 0x2000, v167
	v_add_u32_e32 v168, 0x2000, v168
	v_add_u32_e32 v169, 0x2000, v169
	v_add_u32_e32 v170, 0x2000, v170
	v_add_u32_e32 v171, 0x2000, v171
	v_add_u32_e32 v172, 0x2000, v172
	s_cmp_ge_u32 s3, 0x2000
	s_cbranch_scc1 .LattB_317
; #define SBAR() __builtin_amdgcn_sched_barrier(0)
; #define ISSUE_K(j, stg) do { const long _k0 = TROW(j); const char* _kt = (const char*)Kh + _k0 * (LDK * 2); _Pragma("unroll") for (int _i = 0; _i < 3; ++_i) \
;     __builtin_amdgcn_global_load_lds((const unsigned*)(_kt + okk[_i]), (LAS unsigned*)(ldsL + A2_K + (stg) * SHM_K + (wid * 3 + _i) * 1024), 16, 0, 0); } while (0)
; #define ISSUE_V(j, stg) do { const long _k0 = TROW(j); const char* _vt = (const char*)Vh + _k0 * (LDV * 2); _Pragma("unroll") for (int _i = 0; _i < 2; ++_i) \
;     __builtin_amdgcn_global_load_lds((const unsigned*)(_vt + ovv[_i]), (LAS unsigned*)(ldsL + (stg) * SHM_V + (wid * 2 + _i) * 1024), 16, 0, 0); } while (0)
; __device__ __forceinline__ void qkt(f32x16& p0, f32x16& p1, const char* Ks, const bf16x8* qr, const char* qx, int r32, int hi, int mode) {
;   p0 = f32x16{}; p1 = f32x16{};
; #pragma unroll
;   for (int d0 = 0; d0 < 12; ++d0) { const int cb = (d0 * 16 + hi * 8) * 2;
;     bf16x8 b0 = *reinterpret_cast<const bf16x8*>(Ks + KSWZ(r32, cb));
;     bf16x8 b1 = *reinterpret_cast<const bf16x8*>(Ks + KSWZ(32 + r32, cb));
;     const bf16x8 qf = d0 < 8 ? qr[d0 < 8 ? d0 : 0] : *reinterpret_cast<const bf16x8*>(qx + (d0 - 8) * 1024);
;     p0 = __builtin_amdgcn_mfma_f32_32x32x16_bf16(b0, qf, p0, 0, 0, 0);
;     p1 = __builtin_amdgcn_mfma_f32_32x32x16_bf16(b1, qf, p1, 0, 0, 0); }
; __device__ __forceinline__ void attn_body2(const bf16_t* __restrict__ Qb, const bf16_t* __restrict__ Kh, const bf16_t* __restrict__ Vh, ...
;     ...
;     ISSUE_K(j + 1, 0); ISSUE_V(j, 1);
;     SBAR(); qkt(pB0, pB1, K_lds + SHM_K, qr, qx, r32, hi, 0);
.LBB0_317:
	s_cmp_lt_u32 s12, s84
	s_cselect_b32 s38, 0, s84
	s_cselect_b32 s39, s2, s83
	s_lshl_b32 s38, s38, 6
	s_sub_i32 s38, s39, s38
	s_add_i32 s58, s52, s38
	s_mul_i32 s38, s58, 0xc00
	s_mul_hi_i32 s39, s58, 0xc00
	s_add_u32 s38, s30, s38
	s_addc_u32 s39, s31, s39
	s_mov_b32 m0, s95
	v_lshl_add_u64 v[64:65], s[38:39], 0, v[132:133]
	s_add_i32 s63, s12, -1
	global_load_lds_dwordx4 v[64:65], off
	v_lshl_add_u64 v[64:65], s[38:39], 0, v[130:131]
	s_mov_b32 m0, s96
	s_cmp_lt_u32 s63, s84
	global_load_lds_dwordx4 v[64:65], off
	v_lshl_add_u64 v[64:65], s[38:39], 0, v[136:137]
	s_cselect_b32 s38, 0, s84
	s_cselect_b32 s39, s2, s83
	s_lshl_b32 s38, s38, 6
	s_sub_i32 s38, s39, s38
	s_add_i32 s38, s52, s38
	s_sub_i32 s38, s38, 64
	s_ashr_i32 s39, s38, 31
	s_mov_b32 m0, s97
	s_lshl_b64 s[38:39], s[38:39], 11
	s_add_i32 s62, s3, 0x4000
	global_load_lds_dwordx4 v[64:65], off
	v_lshl_add_u64 v[64:65], v[140:141], 0, s[38:39]
	s_mov_b32 m0, s62
	s_add_i32 s56, s3, 0x4400
	global_load_lds_dwordx4 v[64:65], off
	v_lshl_add_u64 v[64:65], v[64:65], 0, s[22:23]
	s_mov_b32 m0, s56
	s_nop 0
	global_load_lds_dwordx4 v[64:65], off
	ds_read_b128 v[64:67], v174 offset:49152
	ds_read_b128 v[68:71], v174 offset:61440
	ds_read_b128 v[208:211], v166 offset:49152
	ds_read_b128 v[212:215], v166 offset:61440
	ds_read_b128 v[176:179], v162 offset:49152
	ds_read_b128 v[180:183], v162 offset:61440
	v_exp_f32_e32 v156, v156
	v_exp_f32_e32 v157, v157
	s_waitcnt lgkmcnt(4)
	v_mfma_f32_32x32x16_bf16 v[80:95], v[64:67], v[96:99], 0
	v_exp_f32_e32 v154, v154
	v_exp_f32_e32 v155, v155
	v_exp_f32_e32 v152, v152
	v_exp_f32_e32 v153, v153
	v_exp_f32_e32 v190, v150
	v_exp_f32_e32 v207, v151
	v_cvt_pk_bf16_f32 v150, v156, v157
	v_mfma_f32_32x32x16_bf16 v[64:79], v[68:71], v[96:99], 0
	v_cvt_pk_bf16_f32 v151, v154, v155
	s_waitcnt lgkmcnt(2)
	v_mfma_f32_32x32x16_bf16 v[64:79], v[212:215], v[100:103], v[64:79]
	v_mfma_f32_32x32x16_bf16 v[80:95], v[208:211], v[100:103], v[80:95]
	ds_read_b128 v[208:211], v163 offset:49152
	ds_read_b128 v[212:215], v163 offset:61440
	s_waitcnt lgkmcnt(2)
	v_mfma_f32_32x32x16_bf16 v[64:79], v[180:183], v[104:107], v[64:79]
	v_mfma_f32_32x32x16_bf16 v[80:95], v[176:179], v[104:107], v[80:95]
	ds_read_b128 v[176:179], v164 offset:49152
	ds_read_b128 v[180:183], v164 offset:61440
	s_waitcnt lgkmcnt(2)
	v_mfma_f32_32x32x16_bf16 v[64:79], v[212:215], v[108:111], v[64:79]
	v_mfma_f32_32x32x16_bf16 v[80:95], v[208:211], v[108:111], v[80:95]
	ds_read_b128 v[208:211], v165 offset:49152
	ds_read_b128 v[212:215], v165 offset:61440
	s_waitcnt lgkmcnt(2)
	v_mfma_f32_32x32x16_bf16 v[64:79], v[180:183], v[112:115], v[64:79]
	v_mfma_f32_32x32x16_bf16 v[80:95], v[176:179], v[112:115], v[80:95]
	ds_read_b128 v[176:179], v167 offset:49152
	ds_read_b128 v[180:183], v167 offset:61440
	s_waitcnt lgkmcnt(2)
	v_mfma_f32_32x32x16_bf16 v[64:79], v[212:215], v[116:119], v[64:79]
	v_mfma_f32_32x32x16_bf16 v[80:95], v[208:211], v[116:119], v[80:95]
	ds_read_b128 v[208:211], v168 offset:49152
	ds_read_b128 v[212:215], v168 offset:61440
	s_waitcnt lgkmcnt(2)
	v_mfma_f32_32x32x16_bf16 v[64:79], v[180:183], v[120:123], v[64:79]
	v_mfma_f32_32x32x16_bf16 v[80:95], v[176:179], v[120:123], v[80:95]
	ds_read_b128 v[176:179], v169 offset:49152
	ds_read_b128 v[180:183], v169 offset:61440
	ds_read_b128 v[184:187], v173
	s_waitcnt lgkmcnt(3)
	v_mfma_f32_32x32x16_bf16 v[64:79], v[212:215], v[124:127], v[64:79]
	v_mfma_f32_32x32x16_bf16 v[80:95], v[208:211], v[124:127], v[80:95]
	ds_read_b128 v[208:211], v170 offset:49152
	ds_read_b128 v[212:215], v170 offset:61440
	ds_read_b128 v[216:219], v173 offset:1024
	s_waitcnt lgkmcnt(3)
	v_mfma_f32_32x32x16_bf16 v[64:79], v[180:183], v[184:187], v[64:79]
	v_mfma_f32_32x32x16_bf16 v[80:95], v[176:179], v[184:187], v[80:95]
	ds_read_b128 v[176:179], v171 offset:49152
	ds_read_b128 v[180:183], v171 offset:61440
	ds_read_b128 v[184:187], v173 offset:2048
	s_waitcnt lgkmcnt(3)
	v_mfma_f32_32x32x16_bf16 v[64:79], v[212:215], v[216:219], v[64:79]
	v_mfma_f32_32x32x16_bf16 v[80:95], v[208:211], v[216:219], v[80:95]
	ds_read_b128 v[208:211], v172 offset:49152
	ds_read_b128 v[212:215], v172 offset:61440
	ds_read_b128 v[216:219], v173 offset:3072
	s_waitcnt lgkmcnt(3)
	v_mfma_f32_32x32x16_bf16 v[64:79], v[180:183], v[184:187], v[64:79]
	v_mfma_f32_32x32x16_bf16 v[80:95], v[176:179], v[184:187], v[80:95]
	s_waitcnt lgkmcnt(0)
; #define SBAR() __builtin_amdgcn_sched_barrier(0)
; __device__ __forceinline__ void finishSM(f32x16& p0, f32x16& p1, float alpha, float& l_reg, bf16x8& pa0, bf16x8& pa1, bf16x8& pa2, bf16x8& pa3) {
; #pragma unroll
;   for (int r = 0; r < 16; ++r) p1[r] = __builtin_amdgcn_exp2f(p1[r]);
;   float ps = 0;
; #pragma unroll
;   for (int r = 0; r < 16; ++r) ps += p0[r];
; #pragma unroll
;   for (int r = 0; r < 16; ++r) ps += p1[r];
;   { auto rr = __builtin_amdgcn_permlane32_swap(__float_as_uint(ps), __float_as_uint(ps), false, false);
;     ps = __uint_as_float(rr[0]) + __uint_as_float(rr[1]); }
;   l_reg = l_reg * alpha + ps;
;     ...
;   PK4(p0, 0, pa0); PK4(p0, 8, pa1); PK4(p1, 0, pa2); PK4(p1, 8, pa3);
;     ...
; }
; template <int D0> __device__ __forceinline__ void pv_one(f32x16& od, int vb, bf16x8 pa0, bf16x8 pa1, bf16x8 pa2, bf16x8 pa3) {
;   const s16x4 l0 = tr_read<v_rd_off(D0, 0, 0)>(vb), h0 = tr_read<v_rd_off(D0, 0, 1)>(vb), l1 = tr_read<v_rd_off(D0, 1, 0)>(vb), h1 = tr_read<v_rd_off(D0, 1, 1)>(vb);
;   const s16x4 l2 = tr_read<v_rd_off(D0, 2, 0)>(vb), h2 = tr_read<v_rd_off(D0, 2, 1)>(vb), l3 = tr_read<v_rd_off(D0, 3, 0)>(vb), h3 = tr_read<v_rd_off(D0, 3, 1)>(vb);
;   asm volatile("s_waitcnt lgkmcnt(0)" ::: "memory"); SBAR();
;     ...
;   od = __builtin_amdgcn_mfma_f32_32x32x16_bf16(pa0, PK(l0, h0), od, 0, 0, 0);
;   od = __builtin_amdgcn_mfma_f32_32x32x16_bf16(pa1, PK(l1, h1), od, 0, 0, 0);
;   od = __builtin_amdgcn_mfma_f32_32x32x16_bf16(pa2, PK(l2, h2), od, 0, 0, 0);
;   od = __builtin_amdgcn_mfma_f32_32x32x16_bf16(pa3, PK(l3, h3), od, 0, 0, 0);
;     ...
; }
; __device__ __forceinline__ void pv_d0(f32x16* o, int vb, bf16x8 pa0, bf16x8 pa1, bf16x8 pa2, bf16x8 pa3) {
;   pv_one<0>(o[0], vb, pa0, pa1, pa2, pa3); pv_one<1>(o[1], vb, pa0, pa1, pa2, pa3); pv_one<2>(o[2], vb, pa0, pa1, pa2, pa3); pv_one<3>(o[3], vb, pa0, pa1, pa2, pa3);
	v_mfma_f32_32x32x16_bf16 v[64:79], v[212:215], v[216:219], v[64:79]
	v_exp_f32_e32 v214, v142
	v_add_f32_e32 v142, 0, v199
	v_add_f32_e32 v142, v200, v142
	v_add_f32_e32 v142, v201, v142
	v_add_f32_e32 v142, v203, v142
	v_add_f32_e32 v142, v204, v142
	v_add_f32_e32 v142, v206, v142
	v_add_f32_e32 v142, v202, v142
	v_add_f32_e32 v142, v205, v142
	v_add_f32_e32 v142, v191, v142
	v_add_f32_e32 v142, v193, v142
	v_add_f32_e32 v142, v194, v142
	v_add_f32_e32 v142, v197, v142
	v_add_f32_e32 v142, v192, v142
	v_add_f32_e32 v142, v195, v142
	v_add_f32_e32 v142, v196, v142
	v_add_f32_e32 v142, v198, v142
	v_add_f32_e32 v142, v156, v142
	v_add_f32_e32 v142, v157, v142
	v_add_f32_e32 v142, v154, v142
	v_add_f32_e32 v142, v155, v142
	v_mfma_f32_32x32x16_bf16 v[80:95], v[208:211], v[216:219], v[80:95]
	v_exp_f32_e32 v208, v148
	v_add_f32_e32 v142, v152, v142
	v_exp_f32_e32 v209, v149
	v_add_f32_e32 v142, v153, v142
	v_exp_f32_e32 v210, v146
	v_add_f32_e32 v142, v190, v142
	v_exp_f32_e32 v211, v147
	v_add_f32_e32 v142, v207, v142
	v_exp_f32_e32 v212, v144
	v_add_f32_e32 v142, v208, v142
	v_exp_f32_e32 v213, v145
	v_add_f32_e32 v142, v209, v142
	v_add_f32_e32 v142, v210, v142
	v_exp_f32_e32 v215, v143
	v_add_f32_e32 v142, v211, v142
	v_add_f32_e32 v142, v212, v142
	v_add_f32_e32 v142, v213, v142
	v_add_f32_e32 v142, v214, v142
	v_add_f32_e32 v188, v215, v142
	v_mov_b32_e32 v189, v188
	v_cvt_pk_bf16_f32 v142, v199, v200
	v_cvt_pk_bf16_f32 v144, v204, v206
	v_permlane32_swap_b32_e32 v188, v189
	v_cvt_pk_bf16_f32 v143, v201, v203
	v_cvt_pk_bf16_f32 v145, v202, v205
	v_permlane32_swap_b32_e32 v142, v144
	v_cvt_pk_bf16_f32 v146, v191, v193
	v_cvt_pk_bf16_f32 v147, v194, v197
	v_cvt_pk_bf16_f32 v148, v192, v195
	v_cvt_pk_bf16_f32 v149, v196, v198
	v_cvt_pk_bf16_f32 v152, v152, v153
	v_cvt_pk_bf16_f32 v153, v190, v207
	v_cvt_pk_bf16_f32 v154, v208, v209
	v_cvt_pk_bf16_f32 v155, v210, v211
	v_cvt_pk_bf16_f32 v156, v212, v213
	v_cvt_pk_bf16_f32 v157, v214, v215
	v_permlane32_swap_b32_e32 v143, v145
	v_permlane32_swap_b32_e32 v146, v148
	v_permlane32_swap_b32_e32 v147, v149
	v_permlane32_swap_b32_e32 v150, v152
	v_permlane32_swap_b32_e32 v151, v153
	v_permlane32_swap_b32_e32 v154, v156
	v_permlane32_swap_b32_e32 v155, v157
	ds_read_b64_tr_b16 v[190:191], v161 offset:0
	ds_read_b64_tr_b16 v[192:193], v161 offset:0x800
	ds_read_b64_tr_b16 v[194:195], v161 offset:0x1000
	ds_read_b64_tr_b16 v[196:197], v161 offset:0x1800
	ds_read_b64_tr_b16 v[198:199], v161 offset:0x2000
	ds_read_b64_tr_b16 v[200:201], v161 offset:0x2800
	ds_read_b64_tr_b16 v[202:203], v161 offset:0x3000
	ds_read_b64_tr_b16 v[204:205], v161 offset:0x3800
	s_waitcnt lgkmcnt(6)
	s_nop 0
	v_mfma_f32_32x32x16_bf16 v[48:63], v[142:145], v[190:193], v[48:63]
	ds_read_b64_tr_b16 v[190:191], v161 offset:0x200
	ds_read_b64_tr_b16 v[192:193], v161 offset:0xa00
	s_waitcnt lgkmcnt(6)
	v_mfma_f32_32x32x16_bf16 v[48:63], v[146:149], v[194:197], v[48:63]
	ds_read_b64_tr_b16 v[194:195], v161 offset:0x1200
	ds_read_b64_tr_b16 v[196:197], v161 offset:0x1a00
	s_waitcnt lgkmcnt(6)
	v_mfma_f32_32x32x16_bf16 v[48:63], v[150:153], v[198:201], v[48:63]
	ds_read_b64_tr_b16 v[198:199], v161 offset:0x2200
	ds_read_b64_tr_b16 v[200:201], v161 offset:0x2a00
	s_waitcnt lgkmcnt(6)
	v_mfma_f32_32x32x16_bf16 v[48:63], v[154:157], v[202:205], v[48:63]
	ds_read_b64_tr_b16 v[202:203], v161 offset:0x3200
	ds_read_b64_tr_b16 v[204:205], v161 offset:0x3a00
	s_waitcnt lgkmcnt(6)
	v_mfma_f32_32x32x16_bf16 v[32:47], v[142:145], v[190:193], v[32:47]
	ds_read_b64_tr_b16 v[190:191], v161 offset:0x400
	ds_read_b64_tr_b16 v[192:193], v161 offset:0xc00
	s_waitcnt lgkmcnt(6)
	v_mfma_f32_32x32x16_bf16 v[32:47], v[146:149], v[194:197], v[32:47]
	ds_read_b64_tr_b16 v[194:195], v161 offset:0x1400
	ds_read_b64_tr_b16 v[196:197], v161 offset:0x1c00
	s_waitcnt lgkmcnt(6)
	v_mfma_f32_32x32x16_bf16 v[32:47], v[150:153], v[198:201], v[32:47]
	ds_read_b64_tr_b16 v[198:199], v161 offset:0x2400
	ds_read_b64_tr_b16 v[200:201], v161 offset:0x2c00
	s_waitcnt lgkmcnt(6)
	v_mfma_f32_32x32x16_bf16 v[32:47], v[154:157], v[202:205], v[32:47]
	ds_read_b64_tr_b16 v[202:203], v161 offset:0x3400
	ds_read_b64_tr_b16 v[204:205], v161 offset:0x3c00
	s_waitcnt lgkmcnt(6)
	v_mfma_f32_32x32x16_bf16 v[16:31], v[142:145], v[190:193], v[16:31]
	ds_read_b64_tr_b16 v[190:191], v161 offset:0x600
	ds_read_b64_tr_b16 v[192:193], v161 offset:0xe00
	s_waitcnt lgkmcnt(6)
	v_mfma_f32_32x32x16_bf16 v[16:31], v[146:149], v[194:197], v[16:31]
	ds_read_b64_tr_b16 v[194:195], v161 offset:0x1600
	ds_read_b64_tr_b16 v[196:197], v161 offset:0x1e00
	s_waitcnt lgkmcnt(6)
	v_mfma_f32_32x32x16_bf16 v[16:31], v[150:153], v[198:201], v[16:31]
	ds_read_b64_tr_b16 v[198:199], v161 offset:0x2600
	ds_read_b64_tr_b16 v[200:201], v161 offset:0x2e00
	s_waitcnt lgkmcnt(6)
	v_mfma_f32_32x32x16_bf16 v[16:31], v[154:157], v[202:205], v[16:31]
	ds_read_b64_tr_b16 v[202:203], v161 offset:0x3600
	ds_read_b64_tr_b16 v[204:205], v161 offset:0x3e00
	s_waitcnt lgkmcnt(6)
	v_mfma_f32_32x32x16_bf16 v[0:15], v[142:145], v[190:193], v[0:15]
	v_max_f32_e32 v142, v81, v81
	v_max_f32_e32 v143, v80, v80
	v_max_f32_e32 v142, v143, v142
	v_max3_f32 v142, v142, v82, v83
	v_max3_f32 v142, v142, v84, v85
	v_max3_f32 v142, v142, v86, v87
	v_max3_f32 v142, v142, v88, v89
	v_max3_f32 v142, v142, v90, v91
	v_max3_f32 v142, v142, v92, v93
	s_waitcnt lgkmcnt(4)
	v_mfma_f32_32x32x16_bf16 v[0:15], v[146:149], v[194:197], v[0:15]
	v_max3_f32 v142, v142, v94, v95
	v_max3_f32 v142, v142, v64, v65
	v_max3_f32 v142, v142, v66, v67
	v_max3_f32 v142, v142, v68, v69
	v_max3_f32 v142, v142, v70, v71
	v_max3_f32 v142, v142, v72, v73
	v_max3_f32 v142, v142, v74, v75
	v_max3_f32 v142, v142, v76, v77
	s_waitcnt lgkmcnt(2)
	v_mfma_f32_32x32x16_bf16 v[0:15], v[150:153], v[198:201], v[0:15]
	v_max3_f32 v142, v142, v78, v79
	v_mov_b32_e32 v143, v142
	s_nop 1
	v_permlane32_swap_b32_e32 v142, v143
	v_max_f32_e32 v143, v143, v143
	v_max_f32_e32 v142, v142, v142
	v_max_f32_e32 v142, v142, v143
	v_sub_f32_e32 v143, v142, v160
	v_cmp_ge_f32_e32 vcc, s45, v143
	v_max_f32_e32 v143, v160, v160
	v_max_f32_e32 v142, v143, v142
	s_waitcnt lgkmcnt(0)
	v_mfma_f32_32x32x16_bf16 v[0:15], v[154:157], v[202:205], v[0:15]
	v_sub_f32_e32 v143, v160, v142
	v_mul_f32_e32 v143, 0x3dd53b94, v143
	v_exp_f32_e32 v143, v143
	s_cmp_eq_u64 vcc, exec
	s_cselect_b64 s[38:39], -1, 0
	v_cndmask_b32_e64 v190, v143, 1.0, s[38:39]
	v_cmp_gt_f32_e32 vcc, 1.0, v190
	s_cbranch_vccz .LBB0_321
; #define SBAR() __builtin_amdgcn_sched_barrier(0)
; #define RESC(a) do { if (__any((a) < 1.f)) { if (hi == 0) al_l[r32] = (a); asm volatile("s_waitcnt lgkmcnt(0)" ::: "memory"); \
;     for (int d = 0; d < 4; ++d) for (int r = 0; r < 16; ++r) o[d][r] *= al_l[crow(r, hi)]; } } while (0)
; #define ISSUE_K(j, stg) do { const long _k0 = TROW(j); const char* _kt = (const char*)Kh + _k0 * (LDK * 2); _Pragma("unroll") for (int _i = 0; _i < 3; ++_i) \
;     __builtin_amdgcn_global_load_lds((const unsigned*)(_kt + okk[_i]), (LAS unsigned*)(ldsL + A2_K + (stg) * SHM_K + (wid * 3 + _i) * 1024), 16, 0, 0); } while (0)
; #define ISSUE_V(j, stg) do { const long _k0 = TROW(j); const char* _vt = (const char*)Vh + _k0 * (LDV * 2); _Pragma("unroll") for (int _i = 0; _i < 2; ++_i) \
;     __builtin_amdgcn_global_load_lds((const unsigned*)(_vt + ovv[_i]), (LAS unsigned*)(ldsL + (stg) * SHM_V + (wid * 2 + _i) * 1024), 16, 0, 0); } while (0)
; #define WAITV(n) asm volatile("s_waitcnt vmcnt(" #n ")" ::: "memory")
; #define ABAR() do { asm volatile("s_waitcnt lgkmcnt(0)" ::: "memory"); __builtin_amdgcn_s_barrier(); asm volatile("" ::: "memory"); } while (0)
; #define RESC(a) do { if (__any((a) < 1.f)) { if (hi == 0) al_l[r32] = (a); asm volatile("s_waitcnt lgkmcnt(0)" ::: "memory"); \
;     for (int d = 0; d < 4; ++d) for (int r = 0; r < 16; ++r) o[d][r] *= al_l[crow(r, hi)]; } } while (0)
; __device__ __forceinline__ void attn_body2(const bf16_t* __restrict__ Qb, const bf16_t* __restrict__ Kh, const bf16_t* __restrict__ Vh, ...
;     ...
;     RESC(alB); WAITV(0); ABAR();
;     ISSUE_K(j + 2, 1); ISSUE_V(j + 1, 0);
;     SBAR(); qkt(pA0, pA1, K_lds, qr, qx, r32, hi, (j + 1 == ntr) ? 1 : 0);
	s_and_saveexec_b64 s[60:61], s[36:37]
	ds_write_b32 v129, v190 offset:128
	s_or_b64 exec, exec, s[60:61]
	s_waitcnt lgkmcnt(0)
	v_add_u32_e32 v143, s87, v128
	ds_read_b128 v[144:147], v143 offset:224
	ds_read_b128 v[148:151], v143 offset:192
	ds_read_b128 v[152:155], v143 offset:160
	ds_read_b128 v[192:195], v143 offset:128
	s_waitcnt lgkmcnt(0)
	v_pk_mul_f32 v[60:61], v[60:61], v[144:145]
	v_pk_mul_f32 v[56:57], v[56:57], v[148:149]
	v_pk_mul_f32 v[52:53], v[52:53], v[152:153]
	v_pk_mul_f32 v[62:63], v[62:63], v[146:147]
	v_pk_mul_f32 v[58:59], v[58:59], v[150:151]
	v_pk_mul_f32 v[54:55], v[54:55], v[154:155]
	v_pk_mul_f32 v[50:51], v[50:51], v[194:195]
	v_pk_mul_f32 v[48:49], v[48:49], v[192:193]
	v_pk_mul_f32 v[44:45], v[44:45], v[144:145]
	v_pk_mul_f32 v[40:41], v[40:41], v[148:149]
	v_pk_mul_f32 v[36:37], v[36:37], v[152:153]
	v_pk_mul_f32 v[46:47], v[46:47], v[146:147]
	v_pk_mul_f32 v[42:43], v[42:43], v[150:151]
	v_pk_mul_f32 v[38:39], v[38:39], v[154:155]
	v_pk_mul_f32 v[34:35], v[34:35], v[194:195]
	v_pk_mul_f32 v[32:33], v[32:33], v[192:193]
	v_pk_mul_f32 v[28:29], v[28:29], v[144:145]
	v_pk_mul_f32 v[24:25], v[24:25], v[148:149]
	v_pk_mul_f32 v[20:21], v[20:21], v[152:153]
	v_pk_mul_f32 v[30:31], v[30:31], v[146:147]
	v_pk_mul_f32 v[26:27], v[26:27], v[150:151]
	v_pk_mul_f32 v[22:23], v[22:23], v[154:155]
	v_pk_mul_f32 v[18:19], v[18:19], v[194:195]
	v_pk_mul_f32 v[16:17], v[16:17], v[192:193]
	v_pk_mul_f32 v[12:13], v[12:13], v[144:145]
	v_pk_mul_f32 v[8:9], v[8:9], v[148:149]
	v_pk_mul_f32 v[4:5], v[4:5], v[152:153]
	v_pk_mul_f32 v[14:15], v[14:15], v[146:147]
	v_pk_mul_f32 v[10:11], v[10:11], v[150:151]
	v_pk_mul_f32 v[6:7], v[6:7], v[154:155]
	v_pk_mul_f32 v[2:3], v[2:3], v[194:195]
	v_pk_mul_f32 v[0:1], v[0:1], v[192:193]
.LBB0_321:
	s_ashr_i32 s59, s58, 31
	s_add_i32 s63, s63, 2
	s_cmp_lt_u32 s63, s84
	v_cndmask_b32_e64 v160, v142, v160, s[38:39]
	s_cselect_b32 s38, 0, s84
	s_cselect_b32 s39, s2, s83
	s_lshl_b32 s38, s38, 6
	s_sub_i32 s38, s39, s38
	s_add_i32 s38, s52, s38
	s_add_i32 s38, s38, 64
	s_mul_hi_i32 s39, s38, 0xc00
	s_mulk_i32 s38, 0xc00
	s_add_u32 s38, s30, s38
	v_mul_f32_e32 v142, 0xbdd53b94, v160
	s_waitcnt vmcnt(0)
	s_addc_u32 s39, s31, s39
	v_fmamk_f32 v192, v64, 0x3dd53b94, v142
	v_fmamk_f32 v193, v65, 0x3dd53b94, v142
	s_waitcnt lgkmcnt(0)
	s_barrier
	v_lshl_add_u64 v[64:65], s[38:39], 0, v[132:133]
	s_mov_b32 m0, s94
	v_fmamk_f32 v80, v80, 0x3dd53b94, v142
	global_load_lds_dwordx4 v[64:65], off
	v_lshl_add_u64 v[64:65], s[38:39], 0, v[130:131]
	s_mov_b32 m0, s75
	v_fmamk_f32 v81, v81, 0x3dd53b94, v142
	global_load_lds_dwordx4 v[64:65], off
	v_lshl_add_u64 v[64:65], s[38:39], 0, v[136:137]
	s_mov_b32 m0, s76
	s_lshl_b64 s[38:39], s[58:59], 11
	global_load_lds_dwordx4 v[64:65], off
	v_lshl_add_u64 v[64:65], v[140:141], 0, s[38:39]
	s_mov_b32 m0, s3
	v_fmamk_f32 v82, v82, 0x3dd53b94, v142
	global_load_lds_dwordx4 v[64:65], off
	v_lshl_add_u64 v[64:65], v[64:65], 0, s[22:23]
	s_mov_b32 m0, s29
	v_fmamk_f32 v83, v83, 0x3dd53b94, v142
	global_load_lds_dwordx4 v[64:65], off
	v_fmamk_f32 v84, v84, 0x3dd53b94, v142
	v_fmamk_f32 v85, v85, 0x3dd53b94, v142
	v_fmamk_f32 v86, v86, 0x3dd53b94, v142
	v_fmamk_f32 v87, v87, 0x3dd53b94, v142
	v_fmamk_f32 v88, v88, 0x3dd53b94, v142
	v_fmamk_f32 v89, v89, 0x3dd53b94, v142
	v_fmamk_f32 v90, v90, 0x3dd53b94, v142
	v_fmamk_f32 v91, v91, 0x3dd53b94, v142
	v_fmamk_f32 v92, v92, 0x3dd53b94, v142
	v_fmamk_f32 v93, v93, 0x3dd53b94, v142
	v_fmamk_f32 v94, v94, 0x3dd53b94, v142
	v_fmamk_f32 v95, v95, 0x3dd53b94, v142
	v_fmamk_f32 v194, v66, 0x3dd53b94, v142
	v_fmamk_f32 v195, v67, 0x3dd53b94, v142
	v_fmamk_f32 v196, v68, 0x3dd53b94, v142
	v_fmamk_f32 v197, v69, 0x3dd53b94, v142
	v_fmamk_f32 v198, v70, 0x3dd53b94, v142
	v_fmamk_f32 v199, v71, 0x3dd53b94, v142
	v_fmamk_f32 v200, v72, 0x3dd53b94, v142
	v_fmamk_f32 v201, v73, 0x3dd53b94, v142
	v_fmamk_f32 v202, v74, 0x3dd53b94, v142
	v_fmamk_f32 v203, v75, 0x3dd53b94, v142
	v_fmamk_f32 v204, v76, 0x3dd53b94, v142
	v_fmamk_f32 v205, v77, 0x3dd53b94, v142
	v_fmamk_f32 v206, v78, 0x3dd53b94, v142
	v_fmamk_f32 v207, v79, 0x3dd53b94, v142
	v_exp_f32_e32 v151, v80
	v_exp_f32_e32 v152, v81
	v_exp_f32_e32 v153, v82
	v_exp_f32_e32 v154, v83
	v_exp_f32_e32 v155, v84
	v_exp_f32_e32 v156, v85
	v_exp_f32_e32 v157, v86
	v_exp_f32_e32 v191, v87
	v_exp_f32_e32 v143, v88
	v_exp_f32_e32 v144, v89
	v_exp_f32_e32 v145, v90
	v_exp_f32_e32 v146, v91
	v_exp_f32_e32 v147, v92
	v_exp_f32_e32 v148, v93
	v_exp_f32_e32 v149, v94
	v_exp_f32_e32 v150, v95
	ds_read_b128 v[64:67], v174 offset:24576
	ds_read_b128 v[80:83], v174 offset:36864
	ds_read_b128 v[208:211], v166 offset:24576
	ds_read_b128 v[212:215], v166 offset:36864
	ds_read_b128 v[176:179], v162 offset:24576
	ds_read_b128 v[180:183], v162 offset:36864
	s_cmp_eq_u32 s12, s84
	s_cselect_b64 vcc, -1, 0
	s_waitcnt lgkmcnt(4)
	v_mfma_f32_32x32x16_bf16 v[64:79], v[64:67], v[96:99], 0
	v_mfma_f32_32x32x16_bf16 v[80:95], v[80:83], v[96:99], 0
	s_waitcnt lgkmcnt(2)
	v_mfma_f32_32x32x16_bf16 v[64:79], v[208:211], v[100:103], v[64:79]
	v_mfma_f32_32x32x16_bf16 v[80:95], v[212:215], v[100:103], v[80:95]
	ds_read_b128 v[208:211], v163 offset:24576
	ds_read_b128 v[212:215], v163 offset:36864
	s_waitcnt lgkmcnt(2)
	v_mfma_f32_32x32x16_bf16 v[64:79], v[176:179], v[104:107], v[64:79]
	v_mfma_f32_32x32x16_bf16 v[80:95], v[180:183], v[104:107], v[80:95]
	ds_read_b128 v[176:179], v164 offset:24576
	ds_read_b128 v[180:183], v164 offset:36864
	s_waitcnt lgkmcnt(2)
	v_mfma_f32_32x32x16_bf16 v[64:79], v[208:211], v[108:111], v[64:79]
	v_mfma_f32_32x32x16_bf16 v[80:95], v[212:215], v[108:111], v[80:95]
	ds_read_b128 v[208:211], v165 offset:24576
	ds_read_b128 v[212:215], v165 offset:36864
	s_waitcnt lgkmcnt(2)
; __device__ __forceinline__ void finishSM(f32x16& p0, f32x16& p1, float alpha, float& l_reg, bf16x8& pa0, bf16x8& pa1, bf16x8& pa2, bf16x8& pa3) {
; #pragma unroll
;   for (int r = 0; r < 16; ++r) p1[r] = __builtin_amdgcn_exp2f(p1[r]);
;   float ps = 0;
; #pragma unroll
;   for (int r = 0; r < 16; ++r) ps += p0[r];
; #pragma unroll
;   for (int r = 0; r < 16; ++r) ps += p1[r];
;   { auto rr = __builtin_amdgcn_permlane32_swap(__float_as_uint(ps), __float_as_uint(ps), false, false);
;     ps = __uint_as_float(rr[0]) + __uint_as_float(rr[1]); }
;   l_reg = l_reg * alpha + ps;
;     ...
;   PK4(p0, 0, pa0); PK4(p0, 8, pa1); PK4(p1, 0, pa2); PK4(p1, 8, pa3);
;     ...
; }
; __device__ __forceinline__ void qkt(f32x16& p0, f32x16& p1, const char* Ks, const bf16x8* qr, const char* qx, int r32, int hi, int mode) {
;   p0 = f32x16{}; p1 = f32x16{};
; #pragma unroll
;   for (int d0 = 0; d0 < 12; ++d0) { const int cb = (d0 * 16 + hi * 8) * 2;
;     bf16x8 b0 = *reinterpret_cast<const bf16x8*>(Ks + KSWZ(r32, cb));
;     bf16x8 b1 = *reinterpret_cast<const bf16x8*>(Ks + KSWZ(32 + r32, cb));
;     const bf16x8 qf = d0 < 8 ? qr[d0 < 8 ? d0 : 0] : *reinterpret_cast<const bf16x8*>(qx + (d0 - 8) * 1024);
;     p0 = __builtin_amdgcn_mfma_f32_32x32x16_bf16(b0, qf, p0, 0, 0, 0);
;     p1 = __builtin_amdgcn_mfma_f32_32x32x16_bf16(b1, qf, p1, 0, 0, 0); }
;   if (mode != 0) {
;     constexpr float NEG = -1e30f;
; #pragma unroll
;     for (int r = 0; r < 16; ++r) p1[r] = NEG;
; #pragma unroll
;     for (int r = 8; r < 16; ++r) p0[r] = NEG;
;     if (mode == 2) {
; #pragma unroll
;       for (int r = 0; r < 8; ++r) p0[r] = NEG; }
;   }
	v_mfma_f32_32x32x16_bf16 v[64:79], v[176:179], v[112:115], v[64:79]
	v_mfma_f32_32x32x16_bf16 v[80:95], v[180:183], v[112:115], v[80:95]
	ds_read_b128 v[176:179], v167 offset:24576
	ds_read_b128 v[180:183], v167 offset:36864
	s_waitcnt lgkmcnt(2)
	v_mfma_f32_32x32x16_bf16 v[64:79], v[208:211], v[116:119], v[64:79]
	v_mfma_f32_32x32x16_bf16 v[80:95], v[212:215], v[116:119], v[80:95]
	ds_read_b128 v[208:211], v168 offset:24576
	ds_read_b128 v[212:215], v168 offset:36864
	s_waitcnt lgkmcnt(2)
	v_mfma_f32_32x32x16_bf16 v[64:79], v[176:179], v[120:123], v[64:79]
	v_mfma_f32_32x32x16_bf16 v[80:95], v[180:183], v[120:123], v[80:95]
	ds_read_b128 v[176:179], v169 offset:24576
	ds_read_b128 v[180:183], v169 offset:36864
	ds_read_b128 v[184:187], v173
	s_waitcnt lgkmcnt(3)
	v_mfma_f32_32x32x16_bf16 v[64:79], v[208:211], v[124:127], v[64:79]
	v_mfma_f32_32x32x16_bf16 v[80:95], v[212:215], v[124:127], v[80:95]
	ds_read_b128 v[208:211], v170 offset:24576
	ds_read_b128 v[212:215], v170 offset:36864
	ds_read_b128 v[216:219], v173 offset:1024
	s_waitcnt lgkmcnt(3)
	v_mfma_f32_32x32x16_bf16 v[64:79], v[176:179], v[184:187], v[64:79]
	v_mfma_f32_32x32x16_bf16 v[80:95], v[180:183], v[184:187], v[80:95]
	ds_read_b128 v[176:179], v171 offset:24576
	ds_read_b128 v[180:183], v171 offset:36864
	ds_read_b128 v[184:187], v173 offset:2048
	s_waitcnt lgkmcnt(3)
	v_mfma_f32_32x32x16_bf16 v[64:79], v[208:211], v[216:219], v[64:79]
	v_mfma_f32_32x32x16_bf16 v[80:95], v[212:215], v[216:219], v[80:95]
	ds_read_b128 v[208:211], v172 offset:24576
	ds_read_b128 v[212:215], v172 offset:36864
	ds_read_b128 v[216:219], v173 offset:3072
	s_waitcnt lgkmcnt(3)
	v_mfma_f32_32x32x16_bf16 v[64:79], v[176:179], v[184:187], v[64:79]
	v_mfma_f32_32x32x16_bf16 v[80:95], v[180:183], v[184:187], v[80:95]
	s_waitcnt lgkmcnt(0)
	v_mfma_f32_32x32x16_bf16 v[64:79], v[208:211], v[216:219], v[64:79]
	v_mfma_f32_32x32x16_bf16 v[80:95], v[212:215], v[216:219], v[80:95]
	s_nop 10
	v_cndmask_b32_e32 v208, v79, v229, vcc
	v_cndmask_b32_e32 v209, v78, v229, vcc
	v_cndmask_b32_e32 v210, v77, v229, vcc
	v_cndmask_b32_e32 v211, v76, v229, vcc
	v_cndmask_b32_e32 v212, v75, v229, vcc
	v_cndmask_b32_e32 v213, v74, v229, vcc
	v_cndmask_b32_e32 v214, v73, v229, vcc
	v_cndmask_b32_e32 v79, v89, v229, vcc
	v_add_f32_e32 v89, 0, v151
	v_add_f32_e32 v89, v152, v89
	v_add_f32_e32 v89, v153, v89
	v_add_f32_e32 v89, v154, v89
	v_add_f32_e32 v89, v155, v89
	v_add_f32_e32 v89, v156, v89
	v_add_f32_e32 v89, v157, v89
	v_add_f32_e32 v89, v191, v89
	v_add_f32_e32 v89, v143, v89
	v_add_f32_e32 v89, v144, v89
	v_add_f32_e32 v89, v145, v89
	v_add_f32_e32 v89, v146, v89
	v_cndmask_b32_e32 v78, v88, v229, vcc
	v_exp_f32_e32 v88, v192
	v_add_f32_e32 v89, v147, v89
	v_cndmask_b32_e32 v77, v91, v229, vcc
	v_exp_f32_e32 v91, v193
	v_add_f32_e32 v89, v148, v89
	v_exp_f32_e32 v192, v194
	v_add_f32_e32 v89, v149, v89
	v_exp_f32_e32 v193, v195
	v_add_f32_e32 v89, v150, v89
	v_exp_f32_e32 v194, v196
	v_add_f32_e32 v89, v88, v89
	v_exp_f32_e32 v195, v197
	v_add_f32_e32 v89, v91, v89
	v_exp_f32_e32 v196, v198
	v_add_f32_e32 v89, v192, v89
	v_exp_f32_e32 v197, v199
	v_add_f32_e32 v89, v193, v89
	v_exp_f32_e32 v198, v200
	v_add_f32_e32 v89, v194, v89
	v_exp_f32_e32 v199, v201
	v_add_f32_e32 v89, v195, v89
	v_exp_f32_e32 v200, v202
	v_add_f32_e32 v89, v196, v89
	v_exp_f32_e32 v201, v203
	v_add_f32_e32 v89, v197, v89
	v_exp_f32_e32 v202, v204
	v_add_f32_e32 v89, v198, v89
	v_exp_f32_e32 v203, v205
	v_add_f32_e32 v89, v199, v89
	v_exp_f32_e32 v204, v206
	v_add_f32_e32 v89, v200, v89
	v_exp_f32_e32 v205, v207
	v_add_f32_e32 v89, v201, v89
	v_add_f32_e32 v89, v202, v89
	v_add_f32_e32 v89, v203, v89
	v_add_f32_e32 v89, v204, v89
	v_add_f32_e32 v89, v205, v89
	v_cndmask_b32_e32 v76, v90, v229, vcc
	v_mov_b32_e32 v90, v89
	v_cndmask_b32_e32 v215, v72, v229, vcc
	v_cndmask_b32_e32 v73, v95, v229, vcc
	v_cndmask_b32_e32 v72, v94, v229, vcc
	v_cndmask_b32_e32 v75, v93, v229, vcc
	v_cndmask_b32_e32 v74, v92, v229, vcc
	v_cndmask_b32_e32 v87, v87, v229, vcc
	v_cndmask_b32_e32 v86, v86, v229, vcc
	v_cndmask_b32_e32 v85, v85, v229, vcc
	v_cndmask_b32_e32 v84, v84, v229, vcc
	v_cndmask_b32_e32 v83, v83, v229, vcc
	v_cndmask_b32_e32 v82, v82, v229, vcc
	v_cndmask_b32_e32 v81, v81, v229, vcc
	v_cndmask_b32_e32 v80, v80, v229, vcc
	v_permlane32_swap_b32_e32 v89, v90
	v_cvt_pk_bf16_f32 v92, v151, v152
	v_cvt_pk_bf16_f32 v93, v153, v154
	v_cvt_pk_bf16_f32 v94, v155, v156
	v_cvt_pk_bf16_f32 v95, v157, v191
	v_cvt_pk_bf16_f32 v144, v143, v144
	v_cvt_pk_bf16_f32 v145, v145, v146
	v_cvt_pk_bf16_f32 v146, v147, v148
	v_cvt_pk_bf16_f32 v147, v149, v150
	v_cvt_pk_bf16_f32 v148, v88, v91
	v_cvt_pk_bf16_f32 v149, v192, v193
	v_cvt_pk_bf16_f32 v150, v194, v195
	v_cvt_pk_bf16_f32 v151, v196, v197
	v_cvt_pk_bf16_f32 v152, v198, v199
	v_cvt_pk_bf16_f32 v153, v200, v201
	v_cvt_pk_bf16_f32 v154, v202, v203
	v_cvt_pk_bf16_f32 v155, v204, v205
	v_permlane32_swap_b32_e32 v92, v94
	v_permlane32_swap_b32_e32 v93, v95
	v_permlane32_swap_b32_e32 v144, v146
	v_permlane32_swap_b32_e32 v145, v147
	v_permlane32_swap_b32_e32 v148, v150
	v_permlane32_swap_b32_e32 v149, v151
	v_permlane32_swap_b32_e32 v152, v154
	v_permlane32_swap_b32_e32 v153, v155
	ds_read_b64_tr_b16 v[192:193], v159 offset:0
	ds_read_b64_tr_b16 v[194:195], v159 offset:0x800
	ds_read_b64_tr_b16 v[196:197], v159 offset:0x1000
	ds_read_b64_tr_b16 v[198:199], v159 offset:0x1800
	ds_read_b64_tr_b16 v[200:201], v159 offset:0x2000
	ds_read_b64_tr_b16 v[202:203], v159 offset:0x2800
	ds_read_b64_tr_b16 v[204:205], v159 offset:0x3000
	ds_read_b64_tr_b16 v[206:207], v159 offset:0x3800
	s_waitcnt lgkmcnt(6)
; #define SBAR() __builtin_amdgcn_sched_barrier(0)
; __device__ __forceinline__ void partialSM(f32x16& p0, f32x16& p1, float& m_reg, float& mn, float& alpha) {
;   constexpr float C = ATT_SCALE * 1.4426950408889634f;
;   float pmax = p0[0];
; #pragma unroll
;   for (int r = 1; r < 16; ++r) pmax = fmaxf(pmax, p0[r]);
; #pragma unroll
;   for (int r = 0; r < 16; ++r) pmax = fmaxf(pmax, p1[r]);
;   { auto rr = __builtin_amdgcn_permlane32_swap(__float_as_uint(pmax), __float_as_uint(pmax), false, false);
;     pmax = fmaxf(__uint_as_float(rr[0]), __uint_as_float(rr[1])); }
;   if (__builtin_expect(__all(pmax - m_reg <= ATT_THR / ATT_SCALE), 1)) { mn = m_reg; alpha = 1.f; }
;   else { mn = fmaxf(m_reg, pmax); alpha = __builtin_amdgcn_exp2f((m_reg - mn) * C); m_reg = mn; }
; template <int D0> __device__ __forceinline__ void pv_one(f32x16& od, int vb, bf16x8 pa0, bf16x8 pa1, bf16x8 pa2, bf16x8 pa3) {
;   const s16x4 l0 = tr_read<v_rd_off(D0, 0, 0)>(vb), h0 = tr_read<v_rd_off(D0, 0, 1)>(vb), l1 = tr_read<v_rd_off(D0, 1, 0)>(vb), h1 = tr_read<v_rd_off(D0, 1, 1)>(vb);
;   const s16x4 l2 = tr_read<v_rd_off(D0, 2, 0)>(vb), h2 = tr_read<v_rd_off(D0, 2, 1)>(vb), l3 = tr_read<v_rd_off(D0, 3, 0)>(vb), h3 = tr_read<v_rd_off(D0, 3, 1)>(vb);
;   asm volatile("s_waitcnt lgkmcnt(0)" ::: "memory"); SBAR();
;     ...
;   od = __builtin_amdgcn_mfma_f32_32x32x16_bf16(pa0, PK(l0, h0), od, 0, 0, 0);
;   od = __builtin_amdgcn_mfma_f32_32x32x16_bf16(pa1, PK(l1, h1), od, 0, 0, 0);
;   od = __builtin_amdgcn_mfma_f32_32x32x16_bf16(pa2, PK(l2, h2), od, 0, 0, 0);
;   od = __builtin_amdgcn_mfma_f32_32x32x16_bf16(pa3, PK(l3, h3), od, 0, 0, 0);
;     ...
; }
; __device__ __forceinline__ void pv_d0(f32x16* o, int vb, bf16x8 pa0, bf16x8 pa1, bf16x8 pa2, bf16x8 pa3) {
;   pv_one<0>(o[0], vb, pa0, pa1, pa2, pa3); pv_one<1>(o[1], vb, pa0, pa1, pa2, pa3); pv_one<2>(o[2], vb, pa0, pa1, pa2, pa3); pv_one<3>(o[3], vb, pa0, pa1, pa2, pa3);
	s_nop 0
	v_mfma_f32_32x32x16_bf16 v[48:63], v[92:95], v[192:195], v[48:63]
	ds_read_b64_tr_b16 v[192:193], v159 offset:0x200
	ds_read_b64_tr_b16 v[194:195], v159 offset:0xa00
	s_waitcnt lgkmcnt(6)
	v_mfma_f32_32x32x16_bf16 v[48:63], v[144:147], v[196:199], v[48:63]
	ds_read_b64_tr_b16 v[196:197], v159 offset:0x1200
	ds_read_b64_tr_b16 v[198:199], v159 offset:0x1a00
	s_waitcnt lgkmcnt(6)
	v_mfma_f32_32x32x16_bf16 v[48:63], v[148:151], v[200:203], v[48:63]
	ds_read_b64_tr_b16 v[200:201], v159 offset:0x2200
	ds_read_b64_tr_b16 v[202:203], v159 offset:0x2a00
	s_waitcnt lgkmcnt(6)
	v_mfma_f32_32x32x16_bf16 v[48:63], v[152:155], v[204:207], v[48:63]
	ds_read_b64_tr_b16 v[204:205], v159 offset:0x3200
	ds_read_b64_tr_b16 v[206:207], v159 offset:0x3a00
	s_waitcnt lgkmcnt(6)
	v_mfma_f32_32x32x16_bf16 v[32:47], v[92:95], v[192:195], v[32:47]
	ds_read_b64_tr_b16 v[192:193], v159 offset:0x400
	ds_read_b64_tr_b16 v[194:195], v159 offset:0xc00
	s_waitcnt lgkmcnt(6)
	v_mfma_f32_32x32x16_bf16 v[32:47], v[144:147], v[196:199], v[32:47]
	ds_read_b64_tr_b16 v[196:197], v159 offset:0x1400
	ds_read_b64_tr_b16 v[198:199], v159 offset:0x1c00
	s_waitcnt lgkmcnt(6)
	v_mfma_f32_32x32x16_bf16 v[32:47], v[148:151], v[200:203], v[32:47]
	ds_read_b64_tr_b16 v[200:201], v159 offset:0x2400
	ds_read_b64_tr_b16 v[202:203], v159 offset:0x2c00
	s_waitcnt lgkmcnt(6)
	v_mfma_f32_32x32x16_bf16 v[32:47], v[152:155], v[204:207], v[32:47]
	ds_read_b64_tr_b16 v[204:205], v159 offset:0x3400
	ds_read_b64_tr_b16 v[206:207], v159 offset:0x3c00
	s_waitcnt lgkmcnt(6)
	v_mfma_f32_32x32x16_bf16 v[16:31], v[92:95], v[192:195], v[16:31]
	ds_read_b64_tr_b16 v[192:193], v159 offset:0x600
	ds_read_b64_tr_b16 v[194:195], v159 offset:0xe00
	s_waitcnt lgkmcnt(6)
	v_mfma_f32_32x32x16_bf16 v[16:31], v[144:147], v[196:199], v[16:31]
	ds_read_b64_tr_b16 v[196:197], v159 offset:0x1600
	ds_read_b64_tr_b16 v[198:199], v159 offset:0x1e00
	s_waitcnt lgkmcnt(6)
	v_mfma_f32_32x32x16_bf16 v[16:31], v[148:151], v[200:203], v[16:31]
	ds_read_b64_tr_b16 v[200:201], v159 offset:0x2600
	ds_read_b64_tr_b16 v[202:203], v159 offset:0x2e00
	s_waitcnt lgkmcnt(6)
	v_mfma_f32_32x32x16_bf16 v[16:31], v[152:155], v[204:207], v[16:31]
	ds_read_b64_tr_b16 v[204:205], v159 offset:0x3600
	ds_read_b64_tr_b16 v[206:207], v159 offset:0x3e00
	s_waitcnt lgkmcnt(6)
	v_mfma_f32_32x32x16_bf16 v[0:15], v[92:95], v[192:195], v[0:15]
	v_max_f32_e32 v88, v65, v65
	v_max_f32_e32 v91, v64, v64
	v_max_f32_e32 v88, v91, v88
	v_max3_f32 v88, v88, v66, v67
	v_max3_f32 v88, v88, v68, v69
	v_max3_f32 v88, v88, v70, v71
	v_max3_f32 v88, v88, v215, v214
	s_waitcnt lgkmcnt(4)
	v_mfma_f32_32x32x16_bf16 v[0:15], v[144:147], v[196:199], v[0:15]
	v_max3_f32 v88, v88, v213, v212
	v_max3_f32 v88, v88, v211, v210
	v_max3_f32 v88, v88, v209, v208
	v_max3_f32 v88, v88, v80, v81
	v_max3_f32 v88, v88, v82, v83
	v_max3_f32 v88, v88, v84, v85
	v_max3_f32 v88, v88, v86, v87
	s_waitcnt lgkmcnt(2)
	v_mfma_f32_32x32x16_bf16 v[0:15], v[148:151], v[200:203], v[0:15]
	v_max3_f32 v88, v88, v78, v79
	v_max3_f32 v88, v88, v76, v77
	v_max3_f32 v88, v88, v74, v75
	v_max3_f32 v88, v88, v72, v73
	v_mov_b32_e32 v91, v88
	s_nop 1
	v_permlane32_swap_b32_e32 v88, v91
	s_waitcnt lgkmcnt(0)
	v_mfma_f32_32x32x16_bf16 v[0:15], v[152:155], v[204:207], v[0:15]
	v_max_f32_e32 v91, v91, v91
	v_max_f32_e32 v88, v88, v88
	v_max_f32_e32 v91, v88, v91
	v_sub_f32_e32 v88, v91, v160
	v_cmp_ge_f32_e32 vcc, s45, v88
	v_mov_b32_e32 v88, 1.0
	s_cmp_eq_u64 vcc, exec
	s_cbranch_scc0 .LBB0_328
	v_cmp_gt_f32_e32 vcc, 1.0, v88
	s_cbranch_vccz .LBB0_326

; #define SBAR() __builtin_amdgcn_sched_barrier(0)
; #define ISSUE_K(j, stg) do { const long _k0 = TROW(j); const char* _kt = (const char*)Kh + _k0 * (LDK * 2); _Pragma("unroll") for (int _i = 0; _i < 3; ++_i) \
;     __builtin_amdgcn_global_load_lds((const unsigned*)(_kt + okk[_i]), (LAS unsigned*)(ldsL + A2_K + (stg) * SHM_K + (wid * 3 + _i) * 1024), 16, 0, 0); } while (0)
; #define ISSUE_V(j, stg) do { const long _k0 = TROW(j); const char* _vt = (const char*)Vh + _k0 * (LDV * 2); _Pragma("unroll") for (int _i = 0; _i < 2; ++_i) \
;     __builtin_amdgcn_global_load_lds((const unsigned*)(_vt + ovv[_i]), (LAS unsigned*)(ldsL + (stg) * SHM_V + (wid * 2 + _i) * 1024), 16, 0, 0); } while (0)
; __device__ __forceinline__ void finishSM(f32x16& p0, f32x16& p1, float alpha, float& l_reg, bf16x8& pa0, bf16x8& pa1, bf16x8& pa2, bf16x8& pa3) {
; #pragma unroll
;   for (int r = 0; r < 16; ++r) p1[r] = __builtin_amdgcn_exp2f(p1[r]);
;   float ps = 0;
; #pragma unroll
;   for (int r = 0; r < 16; ++r) ps += p0[r];
; #pragma unroll
;   for (int r = 0; r < 16; ++r) ps += p1[r];
;   { auto rr = __builtin_amdgcn_permlane32_swap(__float_as_uint(ps), __float_as_uint(ps), false, false);
;     ps = __uint_as_float(rr[0]) + __uint_as_float(rr[1]); }
;   l_reg = l_reg * alpha + ps;
;     ...
;   PK4(p0, 0, pa0); PK4(p0, 8, pa1); PK4(p1, 0, pa2); PK4(p1, 8, pa3);
;     ...
; }
; __device__ __forceinline__ void attn_body2(const bf16_t* __restrict__ Qb, const bf16_t* __restrict__ Kh, const bf16_t* __restrict__ Vh, ...
;     ...
;     ISSUE_K(j + 1, 0); ISSUE_V(j, 1);
;     SBAR(); qkt(pB0, pB1, K_lds + SHM_K, qr, qx, r32, hi, 0);
;     finishSM(pA0, pA1, alA, l_reg, pa0, pa1, pa2, pa3); SBAR();
;     pv_d0(o, vb0, pa0, pa1, pa2, pa3); partialSM(pB0, pB1, m_reg, mnB, alB);
.LattB_317:
	s_cmp_lt_u32 s12, s84
	s_cselect_b32 s38, 0, s84
	s_cselect_b32 s39, s2, s83
	s_lshl_b32 s38, s38, 6
	s_sub_i32 s38, s39, s38
	s_add_i32 s58, s52, s38
	s_mul_i32 s38, s58, 0xc00
	s_mul_hi_i32 s39, s58, 0xc00
	s_add_u32 s38, s30, s38
	s_addc_u32 s39, s31, s39
	s_mov_b32 m0, s95
	v_lshl_add_u64 v[64:65], s[38:39], 0, v[132:133]
	s_add_i32 s63, s12, -1
	global_load_lds_dwordx4 v[64:65], off
	v_lshl_add_u64 v[64:65], s[38:39], 0, v[130:131]
	s_mov_b32 m0, s96
	s_cmp_lt_u32 s63, s84
	global_load_lds_dwordx4 v[64:65], off
	v_lshl_add_u64 v[64:65], s[38:39], 0, v[136:137]
	s_cselect_b32 s38, 0, s84
	s_cselect_b32 s39, s2, s83
	s_lshl_b32 s38, s38, 6
	s_sub_i32 s38, s39, s38
	s_add_i32 s38, s52, s38
	s_sub_i32 s38, s38, 64
	s_ashr_i32 s39, s38, 31
	s_mov_b32 m0, s97
	s_lshl_b64 s[38:39], s[38:39], 11
	s_add_i32 s62, s3, 0x4000
	global_load_lds_dwordx4 v[64:65], off
	v_lshl_add_u64 v[64:65], v[140:141], 0, s[38:39]
	s_mov_b32 m0, s62
	s_add_i32 s56, s3, 0x4400
	global_load_lds_dwordx4 v[64:65], off
	v_lshl_add_u64 v[64:65], v[64:65], 0, s[22:23]
	s_mov_b32 m0, s56
	s_nop 0
	global_load_lds_dwordx4 v[64:65], off
	v_exp_f32_e32 v156, v156
	v_exp_f32_e32 v157, v157
	v_exp_f32_e32 v154, v154
	v_exp_f32_e32 v155, v155
	v_exp_f32_e32 v152, v152
	v_exp_f32_e32 v153, v153
	v_exp_f32_e32 v190, v150
	v_exp_f32_e32 v207, v151
	v_cvt_pk_bf16_f32 v150, v156, v157
	v_cvt_pk_bf16_f32 v151, v154, v155
	v_exp_f32_e32 v214, v142
	v_add_f32_e32 v142, 0, v199
	v_add_f32_e32 v142, v200, v142
	v_add_f32_e32 v142, v201, v142
	v_add_f32_e32 v142, v203, v142
	v_add_f32_e32 v142, v204, v142
	v_add_f32_e32 v142, v206, v142
	v_add_f32_e32 v142, v202, v142
	v_add_f32_e32 v142, v205, v142
	v_add_f32_e32 v142, v191, v142
	v_add_f32_e32 v142, v193, v142
	v_add_f32_e32 v142, v194, v142
	v_add_f32_e32 v142, v197, v142
	v_add_f32_e32 v142, v192, v142
	v_add_f32_e32 v142, v195, v142
	v_add_f32_e32 v142, v196, v142
	v_add_f32_e32 v142, v198, v142
	v_add_f32_e32 v142, v156, v142
	v_add_f32_e32 v142, v157, v142
	v_add_f32_e32 v142, v154, v142
	v_add_f32_e32 v142, v155, v142
	v_exp_f32_e32 v208, v148
	v_add_f32_e32 v142, v152, v142
	v_exp_f32_e32 v209, v149
	v_add_f32_e32 v142, v153, v142
	v_exp_f32_e32 v210, v146
	v_add_f32_e32 v142, v190, v142
	v_exp_f32_e32 v211, v147
	v_add_f32_e32 v142, v207, v142
	v_exp_f32_e32 v212, v144
	v_add_f32_e32 v142, v208, v142
	v_exp_f32_e32 v213, v145
	v_add_f32_e32 v142, v209, v142
	v_add_f32_e32 v142, v210, v142
	v_exp_f32_e32 v215, v143
	v_add_f32_e32 v142, v211, v142
	v_add_f32_e32 v142, v212, v142
	v_add_f32_e32 v142, v213, v142
	v_add_f32_e32 v142, v214, v142
	v_add_f32_e32 v188, v215, v142
	v_mov_b32_e32 v189, v188
	v_cvt_pk_bf16_f32 v142, v199, v200
	v_cvt_pk_bf16_f32 v144, v204, v206
	v_permlane32_swap_b32_e32 v188, v189
	v_cvt_pk_bf16_f32 v143, v201, v203
	v_cvt_pk_bf16_f32 v145, v202, v205
	v_permlane32_swap_b32_e32 v142, v144
	v_cvt_pk_bf16_f32 v146, v191, v193
	v_cvt_pk_bf16_f32 v147, v194, v197
	v_cvt_pk_bf16_f32 v148, v192, v195
	v_cvt_pk_bf16_f32 v149, v196, v198
	v_cvt_pk_bf16_f32 v152, v152, v153
	v_cvt_pk_bf16_f32 v153, v190, v207
	v_cvt_pk_bf16_f32 v154, v208, v209
	v_cvt_pk_bf16_f32 v155, v210, v211
	v_cvt_pk_bf16_f32 v156, v212, v213
	v_cvt_pk_bf16_f32 v157, v214, v215
	v_permlane32_swap_b32_e32 v143, v145
	v_permlane32_swap_b32_e32 v146, v148
	v_permlane32_swap_b32_e32 v147, v149
	v_permlane32_swap_b32_e32 v150, v152
	v_permlane32_swap_b32_e32 v151, v153
	v_permlane32_swap_b32_e32 v154, v156
	v_permlane32_swap_b32_e32 v155, v157
	ds_read_b64_tr_b16 v[190:191], v161 offset:0
	ds_read_b64_tr_b16 v[192:193], v161 offset:0x800
	ds_read_b64_tr_b16 v[194:195], v161 offset:0x1000
	ds_read_b64_tr_b16 v[196:197], v161 offset:0x1800
	ds_read_b64_tr_b16 v[198:199], v161 offset:0x2000
	ds_read_b64_tr_b16 v[200:201], v161 offset:0x2800
	ds_read_b64_tr_b16 v[202:203], v161 offset:0x3000
	ds_read_b64_tr_b16 v[204:205], v161 offset:0x3800
	s_waitcnt lgkmcnt(6)
	s_nop 0
	v_mfma_f32_32x32x16_bf16 v[48:63], v[142:145], v[190:193], v[48:63]
	ds_read_b64_tr_b16 v[190:191], v161 offset:0x200
	ds_read_b64_tr_b16 v[192:193], v161 offset:0xa00
	s_waitcnt lgkmcnt(6)
	v_mfma_f32_32x32x16_bf16 v[48:63], v[146:149], v[194:197], v[48:63]
	ds_read_b64_tr_b16 v[194:195], v161 offset:0x1200
	ds_read_b64_tr_b16 v[196:197], v161 offset:0x1a00
	s_waitcnt lgkmcnt(6)
	v_mfma_f32_32x32x16_bf16 v[48:63], v[150:153], v[198:201], v[48:63]
	ds_read_b64_tr_b16 v[198:199], v161 offset:0x2200
	ds_read_b64_tr_b16 v[200:201], v161 offset:0x2a00
	s_waitcnt lgkmcnt(6)
	v_mfma_f32_32x32x16_bf16 v[48:63], v[154:157], v[202:205], v[48:63]
	ds_read_b64_tr_b16 v[202:203], v161 offset:0x3200
	ds_read_b64_tr_b16 v[204:205], v161 offset:0x3a00
	s_waitcnt lgkmcnt(6)
	v_mfma_f32_32x32x16_bf16 v[32:47], v[142:145], v[190:193], v[32:47]
	ds_read_b64_tr_b16 v[190:191], v161 offset:0x400
	ds_read_b64_tr_b16 v[192:193], v161 offset:0xc00
	s_waitcnt lgkmcnt(6)
	v_mfma_f32_32x32x16_bf16 v[32:47], v[146:149], v[194:197], v[32:47]
	ds_read_b64_tr_b16 v[194:195], v161 offset:0x1400
	ds_read_b64_tr_b16 v[196:197], v161 offset:0x1c00
	s_waitcnt lgkmcnt(6)
	v_mfma_f32_32x32x16_bf16 v[32:47], v[150:153], v[198:201], v[32:47]
	ds_read_b64_tr_b16 v[198:199], v161 offset:0x2400
	ds_read_b64_tr_b16 v[200:201], v161 offset:0x2c00
	s_waitcnt lgkmcnt(6)
	v_mfma_f32_32x32x16_bf16 v[32:47], v[154:157], v[202:205], v[32:47]
	ds_read_b64_tr_b16 v[202:203], v161 offset:0x3400
	ds_read_b64_tr_b16 v[204:205], v161 offset:0x3c00
	s_waitcnt lgkmcnt(6)
	v_mfma_f32_32x32x16_bf16 v[16:31], v[142:145], v[190:193], v[16:31]
	ds_read_b64_tr_b16 v[190:191], v161 offset:0x600
	ds_read_b64_tr_b16 v[192:193], v161 offset:0xe00
	s_waitcnt lgkmcnt(6)
; #define SBAR() __builtin_amdgcn_sched_barrier(0)
; __device__ __forceinline__ void qkt(f32x16& p0, f32x16& p1, const char* Ks, const bf16x8* qr, const char* qx, int r32, int hi, int mode) {
;   p0 = f32x16{}; p1 = f32x16{};
; #pragma unroll
;   for (int d0 = 0; d0 < 12; ++d0) { const int cb = (d0 * 16 + hi * 8) * 2;
;     bf16x8 b0 = *reinterpret_cast<const bf16x8*>(Ks + KSWZ(r32, cb));
;     bf16x8 b1 = *reinterpret_cast<const bf16x8*>(Ks + KSWZ(32 + r32, cb));
;     const bf16x8 qf = d0 < 8 ? qr[d0 < 8 ? d0 : 0] : *reinterpret_cast<const bf16x8*>(qx + (d0 - 8) * 1024);
;     p0 = __builtin_amdgcn_mfma_f32_32x32x16_bf16(b0, qf, p0, 0, 0, 0);
;     p1 = __builtin_amdgcn_mfma_f32_32x32x16_bf16(b1, qf, p1, 0, 0, 0); }
; template <int D0> __device__ __forceinline__ void pv_one(f32x16& od, int vb, bf16x8 pa0, bf16x8 pa1, bf16x8 pa2, bf16x8 pa3) {
;   const s16x4 l0 = tr_read<v_rd_off(D0, 0, 0)>(vb), h0 = tr_read<v_rd_off(D0, 0, 1)>(vb), l1 = tr_read<v_rd_off(D0, 1, 0)>(vb), h1 = tr_read<v_rd_off(D0, 1, 1)>(vb);
;   const s16x4 l2 = tr_read<v_rd_off(D0, 2, 0)>(vb), h2 = tr_read<v_rd_off(D0, 2, 1)>(vb), l3 = tr_read<v_rd_off(D0, 3, 0)>(vb), h3 = tr_read<v_rd_off(D0, 3, 1)>(vb);
;   asm volatile("s_waitcnt lgkmcnt(0)" ::: "memory"); SBAR();
;     ...
;   od = __builtin_amdgcn_mfma_f32_32x32x16_bf16(pa0, PK(l0, h0), od, 0, 0, 0);
;   od = __builtin_amdgcn_mfma_f32_32x32x16_bf16(pa1, PK(l1, h1), od, 0, 0, 0);
;   od = __builtin_amdgcn_mfma_f32_32x32x16_bf16(pa2, PK(l2, h2), od, 0, 0, 0);
;   od = __builtin_amdgcn_mfma_f32_32x32x16_bf16(pa3, PK(l3, h3), od, 0, 0, 0);
;     ...
; }
; __device__ __forceinline__ void pv_d0(f32x16* o, int vb, bf16x8 pa0, bf16x8 pa1, bf16x8 pa2, bf16x8 pa3) {
;   pv_one<0>(o[0], vb, pa0, pa1, pa2, pa3); pv_one<1>(o[1], vb, pa0, pa1, pa2, pa3); pv_one<2>(o[2], vb, pa0, pa1, pa2, pa3); pv_one<3>(o[3], vb, pa0, pa1, pa2, pa3);
	v_mfma_f32_32x32x16_bf16 v[16:31], v[146:149], v[194:197], v[16:31]
	ds_read_b64_tr_b16 v[194:195], v161 offset:0x1600
	ds_read_b64_tr_b16 v[196:197], v161 offset:0x1e00
	s_waitcnt lgkmcnt(6)
	v_mfma_f32_32x32x16_bf16 v[16:31], v[150:153], v[198:201], v[16:31]
	ds_read_b64_tr_b16 v[198:199], v161 offset:0x2600
	ds_read_b64_tr_b16 v[200:201], v161 offset:0x2e00
	s_waitcnt lgkmcnt(6)
	v_mfma_f32_32x32x16_bf16 v[16:31], v[154:157], v[202:205], v[16:31]
	ds_read_b64_tr_b16 v[202:203], v161 offset:0x3600
	ds_read_b64_tr_b16 v[204:205], v161 offset:0x3e00
	s_waitcnt lgkmcnt(6)
	v_mfma_f32_32x32x16_bf16 v[0:15], v[142:145], v[190:193], v[0:15]
	s_waitcnt lgkmcnt(4)
	v_mfma_f32_32x32x16_bf16 v[0:15], v[146:149], v[194:197], v[0:15]
	s_waitcnt lgkmcnt(2)
	v_mfma_f32_32x32x16_bf16 v[0:15], v[150:153], v[198:201], v[0:15]
	s_waitcnt lgkmcnt(0)
	v_mfma_f32_32x32x16_bf16 v[0:15], v[154:157], v[202:205], v[0:15]
	ds_read_b128 v[64:67], v174 offset:49152
	ds_read_b128 v[68:71], v174 offset:61440
	ds_read_b128 v[208:211], v166 offset:49152
	ds_read_b128 v[212:215], v166 offset:61440
	ds_read_b128 v[176:179], v162 offset:49152
	ds_read_b128 v[180:183], v162 offset:61440
	s_waitcnt lgkmcnt(4)
	v_mfma_f32_32x32x16_bf16 v[80:95], v[64:67], v[96:99], 0
	v_mfma_f32_32x32x16_bf16 v[64:79], v[68:71], v[96:99], 0
	s_waitcnt lgkmcnt(2)
	v_mfma_f32_32x32x16_bf16 v[64:79], v[212:215], v[100:103], v[64:79]
	v_mfma_f32_32x32x16_bf16 v[80:95], v[208:211], v[100:103], v[80:95]
	ds_read_b128 v[208:211], v163 offset:49152
	ds_read_b128 v[212:215], v163 offset:61440
	s_waitcnt lgkmcnt(2)
	v_mfma_f32_32x32x16_bf16 v[64:79], v[180:183], v[104:107], v[64:79]
	v_mfma_f32_32x32x16_bf16 v[80:95], v[176:179], v[104:107], v[80:95]
	ds_read_b128 v[176:179], v164 offset:49152
	ds_read_b128 v[180:183], v164 offset:61440
	s_waitcnt lgkmcnt(2)
	v_mfma_f32_32x32x16_bf16 v[64:79], v[212:215], v[108:111], v[64:79]
	v_mfma_f32_32x32x16_bf16 v[80:95], v[208:211], v[108:111], v[80:95]
	ds_read_b128 v[208:211], v165 offset:49152
	ds_read_b128 v[212:215], v165 offset:61440
	s_waitcnt lgkmcnt(2)
	v_mfma_f32_32x32x16_bf16 v[64:79], v[180:183], v[112:115], v[64:79]
	v_mfma_f32_32x32x16_bf16 v[80:95], v[176:179], v[112:115], v[80:95]
	ds_read_b128 v[176:179], v167 offset:49152
	ds_read_b128 v[180:183], v167 offset:61440
	s_waitcnt lgkmcnt(2)
	v_mfma_f32_32x32x16_bf16 v[64:79], v[212:215], v[116:119], v[64:79]
	v_mfma_f32_32x32x16_bf16 v[80:95], v[208:211], v[116:119], v[80:95]
	ds_read_b128 v[208:211], v168 offset:49152
	ds_read_b128 v[212:215], v168 offset:61440
	s_waitcnt lgkmcnt(2)
	v_mfma_f32_32x32x16_bf16 v[64:79], v[180:183], v[120:123], v[64:79]
	v_mfma_f32_32x32x16_bf16 v[80:95], v[176:179], v[120:123], v[80:95]
	ds_read_b128 v[176:179], v169 offset:49152
	ds_read_b128 v[180:183], v169 offset:61440
	ds_read_b128 v[184:187], v173
	s_waitcnt lgkmcnt(3)
	v_mfma_f32_32x32x16_bf16 v[64:79], v[212:215], v[124:127], v[64:79]
	v_mfma_f32_32x32x16_bf16 v[80:95], v[208:211], v[124:127], v[80:95]
	ds_read_b128 v[208:211], v170 offset:49152
	ds_read_b128 v[212:215], v170 offset:61440
	ds_read_b128 v[216:219], v173 offset:1024
	s_waitcnt lgkmcnt(3)
	v_mfma_f32_32x32x16_bf16 v[64:79], v[180:183], v[184:187], v[64:79]
	v_mfma_f32_32x32x16_bf16 v[80:95], v[176:179], v[184:187], v[80:95]
	ds_read_b128 v[176:179], v171 offset:49152
	ds_read_b128 v[180:183], v171 offset:61440
	ds_read_b128 v[184:187], v173 offset:2048
	s_waitcnt lgkmcnt(3)
	v_mfma_f32_32x32x16_bf16 v[64:79], v[212:215], v[216:219], v[64:79]
	v_mfma_f32_32x32x16_bf16 v[80:95], v[208:211], v[216:219], v[80:95]
	ds_read_b128 v[208:211], v172 offset:49152
	ds_read_b128 v[212:215], v172 offset:61440
	ds_read_b128 v[216:219], v173 offset:3072
	s_waitcnt lgkmcnt(3)
	v_mfma_f32_32x32x16_bf16 v[64:79], v[180:183], v[184:187], v[64:79]
	v_mfma_f32_32x32x16_bf16 v[80:95], v[176:179], v[184:187], v[80:95]
	s_waitcnt lgkmcnt(0)
	v_mfma_f32_32x32x16_bf16 v[64:79], v[212:215], v[216:219], v[64:79]
	v_mfma_f32_32x32x16_bf16 v[80:95], v[208:211], v[216:219], v[80:95]
	s_nop 12
	v_max_f32_e32 v142, v81, v81
	v_max_f32_e32 v143, v80, v80
	v_max_f32_e32 v142, v143, v142
	v_max3_f32 v142, v142, v82, v83
	v_max3_f32 v142, v142, v84, v85
	v_max3_f32 v142, v142, v86, v87
	v_max3_f32 v142, v142, v88, v89
	v_max3_f32 v142, v142, v90, v91
	v_max3_f32 v142, v142, v92, v93
	v_max3_f32 v142, v142, v94, v95
	v_max3_f32 v142, v142, v64, v65
	v_max3_f32 v142, v142, v66, v67
	v_max3_f32 v142, v142, v68, v69
	v_max3_f32 v142, v142, v70, v71
	v_max3_f32 v142, v142, v72, v73
	v_max3_f32 v142, v142, v74, v75
	v_max3_f32 v142, v142, v76, v77
	v_max3_f32 v142, v142, v78, v79
	v_mov_b32_e32 v143, v142
	s_nop 1
	v_permlane32_swap_b32_e32 v142, v143
	v_max_f32_e32 v143, v143, v143
	v_max_f32_e32 v142, v142, v142
	v_max_f32_e32 v142, v142, v143
	v_sub_f32_e32 v143, v142, v160
	v_cmp_ge_f32_e32 vcc, s45, v143
	v_max_f32_e32 v143, v160, v160
	v_max_f32_e32 v142, v143, v142
	v_sub_f32_e32 v143, v160, v142
	v_mul_f32_e32 v143, 0x3dd53b94, v143
	v_exp_f32_e32 v143, v143
	s_cmp_eq_u64 vcc, exec
	s_cselect_b64 s[38:39], -1, 0
	v_cndmask_b32_e64 v190, v143, 1.0, s[38:39]
	v_cmp_gt_f32_e32 vcc, 1.0, v190
	s_cbranch_vccz .LattB_321
	s_and_saveexec_b64 s[60:61], s[36:37]
	ds_write_b32 v129, v190 offset:128
	s_or_b64 exec, exec, s[60:61]
	s_waitcnt lgkmcnt(0)
	v_add_u32_e32 v143, s87, v128
	ds_read_b128 v[144:147], v143 offset:224
	ds_read_b128 v[148:151], v143 offset:192
	ds_read_b128 v[152:155], v143 offset:160
	ds_read_b128 v[192:195], v143 offset:128
	s_waitcnt lgkmcnt(0)
	v_pk_mul_f32 v[60:61], v[60:61], v[144:145]
	v_pk_mul_f32 v[56:57], v[56:57], v[148:149]
	v_pk_mul_f32 v[52:53], v[52:53], v[152:153]
	v_pk_mul_f32 v[62:63], v[62:63], v[146:147]
	v_pk_mul_f32 v[58:59], v[58:59], v[150:151]
	v_pk_mul_f32 v[54:55], v[54:55], v[154:155]
	v_pk_mul_f32 v[50:51], v[50:51], v[194:195]
	v_pk_mul_f32 v[48:49], v[48:49], v[192:193]
	v_pk_mul_f32 v[44:45], v[44:45], v[144:145]
	v_pk_mul_f32 v[40:41], v[40:41], v[148:149]
	v_pk_mul_f32 v[36:37], v[36:37], v[152:153]
	v_pk_mul_f32 v[46:47], v[46:47], v[146:147]
	v_pk_mul_f32 v[42:43], v[42:43], v[150:151]
	v_pk_mul_f32 v[38:39], v[38:39], v[154:155]
	v_pk_mul_f32 v[34:35], v[34:35], v[194:195]
	v_pk_mul_f32 v[32:33], v[32:33], v[192:193]
	v_pk_mul_f32 v[28:29], v[28:29], v[144:145]
	v_pk_mul_f32 v[24:25], v[24:25], v[148:149]
	v_pk_mul_f32 v[20:21], v[20:21], v[152:153]
	v_pk_mul_f32 v[30:31], v[30:31], v[146:147]
	v_pk_mul_f32 v[26:27], v[26:27], v[150:151]
	v_pk_mul_f32 v[22:23], v[22:23], v[154:155]
	v_pk_mul_f32 v[18:19], v[18:19], v[194:195]
	v_pk_mul_f32 v[16:17], v[16:17], v[192:193]
	v_pk_mul_f32 v[12:13], v[12:13], v[144:145]
	v_pk_mul_f32 v[8:9], v[8:9], v[148:149]
	v_pk_mul_f32 v[4:5], v[4:5], v[152:153]
	v_pk_mul_f32 v[14:15], v[14:15], v[146:147]
	v_pk_mul_f32 v[10:11], v[10:11], v[150:151]
	v_pk_mul_f32 v[6:7], v[6:7], v[154:155]
	v_pk_mul_f32 v[2:3], v[2:3], v[194:195]
	v_pk_mul_f32 v[0:1], v[0:1], v[192:193]
; #define SBAR() __builtin_amdgcn_sched_barrier(0)
; #define RESC(a) do { if (__any((a) < 1.f)) { if (hi == 0) al_l[r32] = (a); asm volatile("s_waitcnt lgkmcnt(0)" ::: "memory"); \
;     for (int d = 0; d < 4; ++d) for (int r = 0; r < 16; ++r) o[d][r] *= al_l[crow(r, hi)]; } } while (0)
; #define ISSUE_K(j, stg) do { const long _k0 = TROW(j); const char* _kt = (const char*)Kh + _k0 * (LDK * 2); _Pragma("unroll") for (int _i = 0; _i < 3; ++_i) \
;     __builtin_amdgcn_global_load_lds((const unsigned*)(_kt + okk[_i]), (LAS unsigned*)(ldsL + A2_K + (stg) * SHM_K + (wid * 3 + _i) * 1024), 16, 0, 0); } while (0)
; #define ISSUE_V(j, stg) do { const long _k0 = TROW(j); const char* _vt = (const char*)Vh + _k0 * (LDV * 2); _Pragma("unroll") for (int _i = 0; _i < 2; ++_i) \
;     __builtin_amdgcn_global_load_lds((const unsigned*)(_vt + ovv[_i]), (LAS unsigned*)(ldsL + (stg) * SHM_V + (wid * 2 + _i) * 1024), 16, 0, 0); } while (0)
; #define WAITV(n) asm volatile("s_waitcnt vmcnt(" #n ")" ::: "memory")
; #define ABAR() do { asm volatile("s_waitcnt lgkmcnt(0)" ::: "memory"); __builtin_amdgcn_s_barrier(); asm volatile("" ::: "memory"); } while (0)
; __device__ __forceinline__ void finishSM(f32x16& p0, f32x16& p1, float alpha, float& l_reg, bf16x8& pa0, bf16x8& pa1, bf16x8& pa2, bf16x8& pa3) {
; #pragma unroll
;   for (int r = 0; r < 16; ++r) p1[r] = __builtin_amdgcn_exp2f(p1[r]);
;   float ps = 0;
; #pragma unroll
;   for (int r = 0; r < 16; ++r) ps += p0[r];
; #pragma unroll
;   for (int r = 0; r < 16; ++r) ps += p1[r];
;   { auto rr = __builtin_amdgcn_permlane32_swap(__float_as_uint(ps), __float_as_uint(ps), false, false);
;     ps = __uint_as_float(rr[0]) + __uint_as_float(rr[1]); }
;   l_reg = l_reg * alpha + ps;
;     ...
;   PK4(p0, 0, pa0); PK4(p0, 8, pa1); PK4(p1, 0, pa2); PK4(p1, 8, pa3);
;     ...
; }
; __device__ __forceinline__ void attn_body2(const bf16_t* __restrict__ Qb, const bf16_t* __restrict__ Kh, const bf16_t* __restrict__ Vh, ...
;     ...
;     RESC(alB); WAITV(0); ABAR();
;     ISSUE_K(j + 2, 1); ISSUE_V(j + 1, 0);
;     SBAR(); qkt(pA0, pA1, K_lds, qr, qx, r32, hi, (j + 1 == ntr) ? 1 : 0);
;     finishSM(pB0, pB1, alB, l_reg, pa0, pa1, pa2, pa3); SBAR();
.LattB_321:
	s_ashr_i32 s59, s58, 31
	s_add_i32 s63, s63, 2
	s_cmp_lt_u32 s63, s84
	v_cndmask_b32_e64 v160, v142, v160, s[38:39]
	s_cselect_b32 s38, 0, s84
	s_cselect_b32 s39, s2, s83
	s_lshl_b32 s38, s38, 6
	s_sub_i32 s38, s39, s38
	s_add_i32 s38, s52, s38
	s_add_i32 s38, s38, 64
	s_mul_hi_i32 s39, s38, 0xc00
	s_mulk_i32 s38, 0xc00
	s_add_u32 s38, s30, s38
	v_mul_f32_e32 v142, 0xbdd53b94, v160
	s_waitcnt vmcnt(0)
	s_addc_u32 s39, s31, s39
	v_fmamk_f32 v192, v64, 0x3dd53b94, v142
	v_fmamk_f32 v193, v65, 0x3dd53b94, v142
	s_waitcnt lgkmcnt(0)
	s_barrier
	v_lshl_add_u64 v[64:65], s[38:39], 0, v[132:133]
	s_mov_b32 m0, s94
	v_fmamk_f32 v80, v80, 0x3dd53b94, v142
	global_load_lds_dwordx4 v[64:65], off
	v_lshl_add_u64 v[64:65], s[38:39], 0, v[130:131]
	s_mov_b32 m0, s75
	v_fmamk_f32 v81, v81, 0x3dd53b94, v142
	global_load_lds_dwordx4 v[64:65], off
	v_lshl_add_u64 v[64:65], s[38:39], 0, v[136:137]
	s_mov_b32 m0, s76
	s_lshl_b64 s[38:39], s[58:59], 11
	global_load_lds_dwordx4 v[64:65], off
	v_lshl_add_u64 v[64:65], v[140:141], 0, s[38:39]
	s_mov_b32 m0, s3
	v_fmamk_f32 v82, v82, 0x3dd53b94, v142
	global_load_lds_dwordx4 v[64:65], off
	v_lshl_add_u64 v[64:65], v[64:65], 0, s[22:23]
	s_mov_b32 m0, s29
	v_fmamk_f32 v83, v83, 0x3dd53b94, v142
	global_load_lds_dwordx4 v[64:65], off
	v_fmamk_f32 v84, v84, 0x3dd53b94, v142
	v_fmamk_f32 v85, v85, 0x3dd53b94, v142
	v_fmamk_f32 v86, v86, 0x3dd53b94, v142
	v_fmamk_f32 v87, v87, 0x3dd53b94, v142
	v_fmamk_f32 v88, v88, 0x3dd53b94, v142
	v_fmamk_f32 v89, v89, 0x3dd53b94, v142
	v_fmamk_f32 v90, v90, 0x3dd53b94, v142
	v_fmamk_f32 v91, v91, 0x3dd53b94, v142
	v_fmamk_f32 v92, v92, 0x3dd53b94, v142
	v_fmamk_f32 v93, v93, 0x3dd53b94, v142
	v_fmamk_f32 v94, v94, 0x3dd53b94, v142
	v_fmamk_f32 v95, v95, 0x3dd53b94, v142
	v_fmamk_f32 v194, v66, 0x3dd53b94, v142
	v_fmamk_f32 v195, v67, 0x3dd53b94, v142
	v_fmamk_f32 v196, v68, 0x3dd53b94, v142
	v_fmamk_f32 v197, v69, 0x3dd53b94, v142
	v_fmamk_f32 v198, v70, 0x3dd53b94, v142
	v_fmamk_f32 v199, v71, 0x3dd53b94, v142
	v_fmamk_f32 v200, v72, 0x3dd53b94, v142
	v_fmamk_f32 v201, v73, 0x3dd53b94, v142
	v_fmamk_f32 v202, v74, 0x3dd53b94, v142
	v_fmamk_f32 v203, v75, 0x3dd53b94, v142
	v_fmamk_f32 v204, v76, 0x3dd53b94, v142
	v_fmamk_f32 v205, v77, 0x3dd53b94, v142
	v_fmamk_f32 v206, v78, 0x3dd53b94, v142
	v_fmamk_f32 v207, v79, 0x3dd53b94, v142
	v_exp_f32_e32 v151, v80
	v_exp_f32_e32 v152, v81
	v_exp_f32_e32 v153, v82
	v_exp_f32_e32 v154, v83
	v_exp_f32_e32 v155, v84
	v_exp_f32_e32 v156, v85
	v_exp_f32_e32 v157, v86
	v_exp_f32_e32 v191, v87
	v_exp_f32_e32 v143, v88
	v_exp_f32_e32 v144, v89
	v_exp_f32_e32 v145, v90
	v_exp_f32_e32 v146, v91
	v_exp_f32_e32 v147, v92
	v_exp_f32_e32 v148, v93
	v_exp_f32_e32 v149, v94
	v_exp_f32_e32 v150, v95
	v_add_f32_e32 v220, 0, v151
	v_add_f32_e32 v220, v152, v220
	v_add_f32_e32 v220, v153, v220
	v_add_f32_e32 v220, v154, v220
	v_add_f32_e32 v220, v155, v220
	v_add_f32_e32 v220, v156, v220
	v_add_f32_e32 v220, v157, v220
	v_add_f32_e32 v220, v191, v220
	v_add_f32_e32 v220, v143, v220
	v_add_f32_e32 v220, v144, v220
	v_add_f32_e32 v220, v145, v220
	v_add_f32_e32 v220, v146, v220
	v_exp_f32_e32 v88, v192
	v_add_f32_e32 v220, v147, v220
	v_exp_f32_e32 v91, v193
	v_add_f32_e32 v220, v148, v220
	v_exp_f32_e32 v192, v194
	v_add_f32_e32 v220, v149, v220
	v_exp_f32_e32 v193, v195
	v_add_f32_e32 v220, v150, v220
	v_exp_f32_e32 v194, v196
	v_add_f32_e32 v220, v88, v220
	v_exp_f32_e32 v195, v197
	v_add_f32_e32 v220, v91, v220
	v_exp_f32_e32 v196, v198
	v_add_f32_e32 v220, v192, v220
	v_exp_f32_e32 v197, v199
	v_add_f32_e32 v220, v193, v220
	v_exp_f32_e32 v198, v200
	v_add_f32_e32 v220, v194, v220
	v_exp_f32_e32 v199, v201
	v_add_f32_e32 v220, v195, v220
	v_exp_f32_e32 v200, v202
	v_add_f32_e32 v220, v196, v220
	v_exp_f32_e32 v201, v203
	v_add_f32_e32 v220, v197, v220
	v_exp_f32_e32 v202, v204
	v_add_f32_e32 v220, v198, v220
	v_exp_f32_e32 v203, v205
	v_add_f32_e32 v220, v199, v220
	v_exp_f32_e32 v204, v206
	v_add_f32_e32 v220, v200, v220
	v_exp_f32_e32 v205, v207
	v_add_f32_e32 v220, v201, v220
	v_add_f32_e32 v220, v202, v220
	v_add_f32_e32 v220, v203, v220
	v_add_f32_e32 v220, v204, v220
	v_add_f32_e32 v220, v205, v220
	v_mov_b32_e32 v221, v220
	s_nop 1
	v_permlane32_swap_b32_e32 v220, v221
	v_cvt_pk_bf16_f32 v92, v151, v152
	v_cvt_pk_bf16_f32 v93, v153, v154
	v_cvt_pk_bf16_f32 v94, v155, v156
	v_cvt_pk_bf16_f32 v95, v157, v191
	v_cvt_pk_bf16_f32 v144, v143, v144
	v_cvt_pk_bf16_f32 v145, v145, v146
	v_cvt_pk_bf16_f32 v146, v147, v148
	v_cvt_pk_bf16_f32 v147, v149, v150
	v_cvt_pk_bf16_f32 v148, v88, v91
	v_cvt_pk_bf16_f32 v149, v192, v193
	v_cvt_pk_bf16_f32 v150, v194, v195
	v_cvt_pk_bf16_f32 v151, v196, v197
	v_cvt_pk_bf16_f32 v152, v198, v199
	v_cvt_pk_bf16_f32 v153, v200, v201
	v_cvt_pk_bf16_f32 v154, v202, v203
	v_cvt_pk_bf16_f32 v155, v204, v205
	v_permlane32_swap_b32_e32 v92, v94
	v_permlane32_swap_b32_e32 v93, v95
	v_permlane32_swap_b32_e32 v144, v146
	v_permlane32_swap_b32_e32 v145, v147
	v_permlane32_swap_b32_e32 v148, v150
	v_permlane32_swap_b32_e32 v149, v151
	v_permlane32_swap_b32_e32 v152, v154
	v_permlane32_swap_b32_e32 v153, v155
	ds_read_b64_tr_b16 v[192:193], v159 offset:0
	ds_read_b64_tr_b16 v[194:195], v159 offset:0x800
	ds_read_b64_tr_b16 v[196:197], v159 offset:0x1000
	ds_read_b64_tr_b16 v[198:199], v159 offset:0x1800
	ds_read_b64_tr_b16 v[200:201], v159 offset:0x2000
	ds_read_b64_tr_b16 v[202:203], v159 offset:0x2800
	ds_read_b64_tr_b16 v[204:205], v159 offset:0x3000
	ds_read_b64_tr_b16 v[206:207], v159 offset:0x3800
	s_waitcnt lgkmcnt(6)
; #define SBAR() __builtin_amdgcn_sched_barrier(0)
; __device__ __forceinline__ void qkt(f32x16& p0, f32x16& p1, const char* Ks, const bf16x8* qr, const char* qx, int r32, int hi, int mode) {
;   p0 = f32x16{}; p1 = f32x16{};
; #pragma unroll
;   for (int d0 = 0; d0 < 12; ++d0) { const int cb = (d0 * 16 + hi * 8) * 2;
;     bf16x8 b0 = *reinterpret_cast<const bf16x8*>(Ks + KSWZ(r32, cb));
;     bf16x8 b1 = *reinterpret_cast<const bf16x8*>(Ks + KSWZ(32 + r32, cb));
;     const bf16x8 qf = d0 < 8 ? qr[d0 < 8 ? d0 : 0] : *reinterpret_cast<const bf16x8*>(qx + (d0 - 8) * 1024);
;     p0 = __builtin_amdgcn_mfma_f32_32x32x16_bf16(b0, qf, p0, 0, 0, 0);
;     p1 = __builtin_amdgcn_mfma_f32_32x32x16_bf16(b1, qf, p1, 0, 0, 0); }
; template <int D0> __device__ __forceinline__ void pv_one(f32x16& od, int vb, bf16x8 pa0, bf16x8 pa1, bf16x8 pa2, bf16x8 pa3) {
;   const s16x4 l0 = tr_read<v_rd_off(D0, 0, 0)>(vb), h0 = tr_read<v_rd_off(D0, 0, 1)>(vb), l1 = tr_read<v_rd_off(D0, 1, 0)>(vb), h1 = tr_read<v_rd_off(D0, 1, 1)>(vb);
;   const s16x4 l2 = tr_read<v_rd_off(D0, 2, 0)>(vb), h2 = tr_read<v_rd_off(D0, 2, 1)>(vb), l3 = tr_read<v_rd_off(D0, 3, 0)>(vb), h3 = tr_read<v_rd_off(D0, 3, 1)>(vb);
;   asm volatile("s_waitcnt lgkmcnt(0)" ::: "memory"); SBAR();
;     ...
;   od = __builtin_amdgcn_mfma_f32_32x32x16_bf16(pa0, PK(l0, h0), od, 0, 0, 0);
;   od = __builtin_amdgcn_mfma_f32_32x32x16_bf16(pa1, PK(l1, h1), od, 0, 0, 0);
;   od = __builtin_amdgcn_mfma_f32_32x32x16_bf16(pa2, PK(l2, h2), od, 0, 0, 0);
;   od = __builtin_amdgcn_mfma_f32_32x32x16_bf16(pa3, PK(l3, h3), od, 0, 0, 0);
;     ...
; }
; __device__ __forceinline__ void pv_d0(f32x16* o, int vb, bf16x8 pa0, bf16x8 pa1, bf16x8 pa2, bf16x8 pa3) {
;   pv_one<0>(o[0], vb, pa0, pa1, pa2, pa3); pv_one<1>(o[1], vb, pa0, pa1, pa2, pa3); pv_one<2>(o[2], vb, pa0, pa1, pa2, pa3); pv_one<3>(o[3], vb, pa0, pa1, pa2, pa3);
	s_nop 0
	v_mfma_f32_32x32x16_bf16 v[48:63], v[92:95], v[192:195], v[48:63]
	ds_read_b64_tr_b16 v[192:193], v159 offset:0x200
	ds_read_b64_tr_b16 v[194:195], v159 offset:0xa00
	s_waitcnt lgkmcnt(6)
	v_mfma_f32_32x32x16_bf16 v[48:63], v[144:147], v[196:199], v[48:63]
	ds_read_b64_tr_b16 v[196:197], v159 offset:0x1200
	ds_read_b64_tr_b16 v[198:199], v159 offset:0x1a00
	s_waitcnt lgkmcnt(6)
	v_mfma_f32_32x32x16_bf16 v[48:63], v[148:151], v[200:203], v[48:63]
	ds_read_b64_tr_b16 v[200:201], v159 offset:0x2200
	ds_read_b64_tr_b16 v[202:203], v159 offset:0x2a00
	s_waitcnt lgkmcnt(6)
	v_mfma_f32_32x32x16_bf16 v[48:63], v[152:155], v[204:207], v[48:63]
	ds_read_b64_tr_b16 v[204:205], v159 offset:0x3200
	ds_read_b64_tr_b16 v[206:207], v159 offset:0x3a00
	s_waitcnt lgkmcnt(6)
	v_mfma_f32_32x32x16_bf16 v[32:47], v[92:95], v[192:195], v[32:47]
	ds_read_b64_tr_b16 v[192:193], v159 offset:0x400
	ds_read_b64_tr_b16 v[194:195], v159 offset:0xc00
	s_waitcnt lgkmcnt(6)
	v_mfma_f32_32x32x16_bf16 v[32:47], v[144:147], v[196:199], v[32:47]
	ds_read_b64_tr_b16 v[196:197], v159 offset:0x1400
	ds_read_b64_tr_b16 v[198:199], v159 offset:0x1c00
	s_waitcnt lgkmcnt(6)
	v_mfma_f32_32x32x16_bf16 v[32:47], v[148:151], v[200:203], v[32:47]
	ds_read_b64_tr_b16 v[200:201], v159 offset:0x2400
	ds_read_b64_tr_b16 v[202:203], v159 offset:0x2c00
	s_waitcnt lgkmcnt(6)
	v_mfma_f32_32x32x16_bf16 v[32:47], v[152:155], v[204:207], v[32:47]
	ds_read_b64_tr_b16 v[204:205], v159 offset:0x3400
	ds_read_b64_tr_b16 v[206:207], v159 offset:0x3c00
	s_waitcnt lgkmcnt(6)
	v_mfma_f32_32x32x16_bf16 v[16:31], v[92:95], v[192:195], v[16:31]
	ds_read_b64_tr_b16 v[192:193], v159 offset:0x600
	ds_read_b64_tr_b16 v[194:195], v159 offset:0xe00
	s_waitcnt lgkmcnt(6)
	v_mfma_f32_32x32x16_bf16 v[16:31], v[144:147], v[196:199], v[16:31]
	ds_read_b64_tr_b16 v[196:197], v159 offset:0x1600
	ds_read_b64_tr_b16 v[198:199], v159 offset:0x1e00
	s_waitcnt lgkmcnt(6)
	v_mfma_f32_32x32x16_bf16 v[16:31], v[148:151], v[200:203], v[16:31]
	ds_read_b64_tr_b16 v[200:201], v159 offset:0x2600
	ds_read_b64_tr_b16 v[202:203], v159 offset:0x2e00
	s_waitcnt lgkmcnt(6)
	v_mfma_f32_32x32x16_bf16 v[16:31], v[152:155], v[204:207], v[16:31]
	ds_read_b64_tr_b16 v[204:205], v159 offset:0x3600
	ds_read_b64_tr_b16 v[206:207], v159 offset:0x3e00
	s_waitcnt lgkmcnt(6)
	v_mfma_f32_32x32x16_bf16 v[0:15], v[92:95], v[192:195], v[0:15]
	s_waitcnt lgkmcnt(4)
	v_mfma_f32_32x32x16_bf16 v[0:15], v[144:147], v[196:199], v[0:15]
	s_waitcnt lgkmcnt(2)
	v_mfma_f32_32x32x16_bf16 v[0:15], v[148:151], v[200:203], v[0:15]
	s_waitcnt lgkmcnt(0)
	v_mfma_f32_32x32x16_bf16 v[0:15], v[152:155], v[204:207], v[0:15]
	ds_read_b128 v[64:67], v174 offset:24576
	ds_read_b128 v[80:83], v174 offset:36864
	ds_read_b128 v[208:211], v166 offset:24576
	ds_read_b128 v[212:215], v166 offset:36864
	ds_read_b128 v[176:179], v162 offset:24576
	ds_read_b128 v[180:183], v162 offset:36864
	s_cmp_eq_u32 s12, s84
	s_cselect_b64 vcc, -1, 0
	s_waitcnt lgkmcnt(4)
	v_mfma_f32_32x32x16_bf16 v[64:79], v[64:67], v[96:99], 0
	v_mfma_f32_32x32x16_bf16 v[80:95], v[80:83], v[96:99], 0
	s_waitcnt lgkmcnt(2)
	v_mfma_f32_32x32x16_bf16 v[64:79], v[208:211], v[100:103], v[64:79]
	v_mfma_f32_32x32x16_bf16 v[80:95], v[212:215], v[100:103], v[80:95]
	ds_read_b128 v[208:211], v163 offset:24576
	ds_read_b128 v[212:215], v163 offset:36864
	s_waitcnt lgkmcnt(2)
	v_mfma_f32_32x32x16_bf16 v[64:79], v[176:179], v[104:107], v[64:79]
	v_mfma_f32_32x32x16_bf16 v[80:95], v[180:183], v[104:107], v[80:95]
	ds_read_b128 v[176:179], v164 offset:24576
	ds_read_b128 v[180:183], v164 offset:36864
	s_waitcnt lgkmcnt(2)
	v_mfma_f32_32x32x16_bf16 v[64:79], v[208:211], v[108:111], v[64:79]
	v_mfma_f32_32x32x16_bf16 v[80:95], v[212:215], v[108:111], v[80:95]
	ds_read_b128 v[208:211], v165 offset:24576
	ds_read_b128 v[212:215], v165 offset:36864
	s_waitcnt lgkmcnt(2)
; __device__ __forceinline__ void partialSM(f32x16& p0, f32x16& p1, float& m_reg, float& mn, float& alpha) {
;   constexpr float C = ATT_SCALE * 1.4426950408889634f;
;   float pmax = p0[0];
; #pragma unroll
;   for (int r = 1; r < 16; ++r) pmax = fmaxf(pmax, p0[r]);
; #pragma unroll
;   for (int r = 0; r < 16; ++r) pmax = fmaxf(pmax, p1[r]);
;   { auto rr = __builtin_amdgcn_permlane32_swap(__float_as_uint(pmax), __float_as_uint(pmax), false, false);
;     pmax = fmaxf(__uint_as_float(rr[0]), __uint_as_float(rr[1])); }
;   if (__builtin_expect(__all(pmax - m_reg <= ATT_THR / ATT_SCALE), 1)) { mn = m_reg; alpha = 1.f; }
;   else { mn = fmaxf(m_reg, pmax); alpha = __builtin_amdgcn_exp2f((m_reg - mn) * C); m_reg = mn; }
; __device__ __forceinline__ void qkt(f32x16& p0, f32x16& p1, const char* Ks, const bf16x8* qr, const char* qx, int r32, int hi, int mode) {
;     ...
;   if (mode != 0) {
;     constexpr float NEG = -1e30f;
; #pragma unroll
;     for (int r = 0; r < 16; ++r) p1[r] = NEG;
; #pragma unroll
;     for (int r = 8; r < 16; ++r) p0[r] = NEG;
;     if (mode == 2) {
; #pragma unroll
;       for (int r = 0; r < 8; ++r) p0[r] = NEG; }
;   }
	v_mfma_f32_32x32x16_bf16 v[64:79], v[176:179], v[112:115], v[64:79]
	v_mfma_f32_32x32x16_bf16 v[80:95], v[180:183], v[112:115], v[80:95]
	ds_read_b128 v[176:179], v167 offset:24576
	ds_read_b128 v[180:183], v167 offset:36864
	s_waitcnt lgkmcnt(2)
	v_mfma_f32_32x32x16_bf16 v[64:79], v[208:211], v[116:119], v[64:79]
	v_mfma_f32_32x32x16_bf16 v[80:95], v[212:215], v[116:119], v[80:95]
	ds_read_b128 v[208:211], v168 offset:24576
	ds_read_b128 v[212:215], v168 offset:36864
	s_waitcnt lgkmcnt(2)
	v_mfma_f32_32x32x16_bf16 v[64:79], v[176:179], v[120:123], v[64:79]
	v_mfma_f32_32x32x16_bf16 v[80:95], v[180:183], v[120:123], v[80:95]
	ds_read_b128 v[176:179], v169 offset:24576
	ds_read_b128 v[180:183], v169 offset:36864
	ds_read_b128 v[184:187], v173
	s_waitcnt lgkmcnt(3)
	v_mfma_f32_32x32x16_bf16 v[64:79], v[208:211], v[124:127], v[64:79]
	v_mfma_f32_32x32x16_bf16 v[80:95], v[212:215], v[124:127], v[80:95]
	ds_read_b128 v[208:211], v170 offset:24576
	ds_read_b128 v[212:215], v170 offset:36864
	ds_read_b128 v[216:219], v173 offset:1024
	s_waitcnt lgkmcnt(3)
	v_mfma_f32_32x32x16_bf16 v[64:79], v[176:179], v[184:187], v[64:79]
	v_mfma_f32_32x32x16_bf16 v[80:95], v[180:183], v[184:187], v[80:95]
	ds_read_b128 v[176:179], v171 offset:24576
	ds_read_b128 v[180:183], v171 offset:36864
	ds_read_b128 v[184:187], v173 offset:2048
	s_waitcnt lgkmcnt(3)
	v_mfma_f32_32x32x16_bf16 v[64:79], v[208:211], v[216:219], v[64:79]
	v_mfma_f32_32x32x16_bf16 v[80:95], v[212:215], v[216:219], v[80:95]
	ds_read_b128 v[208:211], v172 offset:24576
	ds_read_b128 v[212:215], v172 offset:36864
	ds_read_b128 v[216:219], v173 offset:3072
	s_waitcnt lgkmcnt(3)
	v_mfma_f32_32x32x16_bf16 v[64:79], v[176:179], v[184:187], v[64:79]
	v_mfma_f32_32x32x16_bf16 v[80:95], v[180:183], v[184:187], v[80:95]
	s_waitcnt lgkmcnt(0)
	v_mfma_f32_32x32x16_bf16 v[64:79], v[208:211], v[216:219], v[64:79]
	v_mfma_f32_32x32x16_bf16 v[80:95], v[212:215], v[216:219], v[80:95]
	s_nop 10
	v_cndmask_b32_e32 v208, v79, v229, vcc
	v_cndmask_b32_e32 v209, v78, v229, vcc
	v_cndmask_b32_e32 v210, v77, v229, vcc
	v_cndmask_b32_e32 v211, v76, v229, vcc
	v_cndmask_b32_e32 v212, v75, v229, vcc
	v_cndmask_b32_e32 v213, v74, v229, vcc
	v_cndmask_b32_e32 v214, v73, v229, vcc
	v_cndmask_b32_e32 v79, v89, v229, vcc
	v_cndmask_b32_e32 v78, v88, v229, vcc
	v_cndmask_b32_e32 v77, v91, v229, vcc
	v_cndmask_b32_e32 v76, v90, v229, vcc
	v_cndmask_b32_e32 v215, v72, v229, vcc
	v_cndmask_b32_e32 v73, v95, v229, vcc
	v_cndmask_b32_e32 v72, v94, v229, vcc
	v_cndmask_b32_e32 v75, v93, v229, vcc
	v_cndmask_b32_e32 v74, v92, v229, vcc
	v_cndmask_b32_e32 v87, v87, v229, vcc
	v_cndmask_b32_e32 v86, v86, v229, vcc
	v_cndmask_b32_e32 v85, v85, v229, vcc
	v_cndmask_b32_e32 v84, v84, v229, vcc
	v_cndmask_b32_e32 v83, v83, v229, vcc
	v_cndmask_b32_e32 v82, v82, v229, vcc
	v_cndmask_b32_e32 v81, v81, v229, vcc
	v_cndmask_b32_e32 v80, v80, v229, vcc
	v_max_f32_e32 v88, v65, v65
	v_max_f32_e32 v91, v64, v64
	v_max_f32_e32 v88, v91, v88
	v_max3_f32 v88, v88, v66, v67
	v_max3_f32 v88, v88, v68, v69
	v_max3_f32 v88, v88, v70, v71
	v_max3_f32 v88, v88, v215, v214
	v_max3_f32 v88, v88, v213, v212
	v_max3_f32 v88, v88, v211, v210
	v_max3_f32 v88, v88, v209, v208
	v_max3_f32 v88, v88, v80, v81
	v_max3_f32 v88, v88, v82, v83
	v_max3_f32 v88, v88, v84, v85
	v_max3_f32 v88, v88, v86, v87
	v_max3_f32 v88, v88, v78, v79
	v_max3_f32 v88, v88, v76, v77
	v_max3_f32 v88, v88, v74, v75
	v_max3_f32 v88, v88, v72, v73
	v_mov_b32_e32 v91, v88
	s_nop 1
	v_permlane32_swap_b32_e32 v88, v91
	v_max_f32_e32 v91, v91, v91
	v_max_f32_e32 v88, v88, v88
	v_max_f32_e32 v91, v88, v91
	v_sub_f32_e32 v88, v91, v160
	v_cmp_ge_f32_e32 vcc, s45, v88
	v_mov_b32_e32 v88, 1.0
	s_cmp_eq_u64 vcc, exec
	s_cbranch_scc0 .LattB_328
	v_cmp_gt_f32_e32 vcc, 1.0, v88
	s_cbranch_vccz .LattB_326

; #define RESC(a) do { if (__any((a) < 1.f)) { if (hi == 0) al_l[r32] = (a); asm volatile("s_waitcnt lgkmcnt(0)" ::: "memory"); \
;     for (int d = 0; d < 4; ++d) for (int r = 0; r < 16; ++r) o[d][r] *= al_l[crow(r, hi)]; } } while (0)
; #define WAITV(n) asm volatile("s_waitcnt vmcnt(" #n ")" ::: "memory")
; #define ABAR() do { asm volatile("s_waitcnt lgkmcnt(0)" ::: "memory"); __builtin_amdgcn_s_barrier(); asm volatile("" ::: "memory"); } while (0)
; #define RESC(a) do { if (__any((a) < 1.f)) { if (hi == 0) al_l[r32] = (a); asm volatile("s_waitcnt lgkmcnt(0)" ::: "memory"); \
;     for (int d = 0; d < 4; ++d) for (int r = 0; r < 16; ++r) o[d][r] *= al_l[crow(r, hi)]; } } while (0)
; __device__ __forceinline__ void partialSM(f32x16& p0, f32x16& p1, float& m_reg, float& mn, float& alpha) {
;     ...
;   if (__builtin_expect(__all(pmax - m_reg <= ATT_THR / ATT_SCALE), 1)) { mn = m_reg; alpha = 1.f; }
;   else { mn = fmaxf(m_reg, pmax); alpha = __builtin_amdgcn_exp2f((m_reg - mn) * C); m_reg = mn; }
;   const float mnC = -mn * C;
; #pragma unroll
;   for (int r = 0; r < 16; ++r) p0[r] = fmaf(p0[r], C, mnC);
; #pragma unroll
;   for (int r = 0; r < 16; ++r) p1[r] = fmaf(p1[r], C, mnC);
; #pragma unroll
;   for (int r = 0; r < 16; ++r) p0[r] = __builtin_amdgcn_exp2f(p0[r]);
; }
; __device__ __forceinline__ void finishSM(f32x16& p0, f32x16& p1, float alpha, float& l_reg, bf16x8& pa0, bf16x8& pa1, bf16x8& pa2, bf16x8& pa3) {
; #pragma unroll
;   for (int r = 0; r < 16; ++r) p1[r] = __builtin_amdgcn_exp2f(p1[r]);
;   float ps = 0;
; #pragma unroll
;   for (int r = 0; r < 16; ++r) ps += p0[r];
; #pragma unroll
;   for (int r = 0; r < 16; ++r) ps += p1[r];
;   { auto rr = __builtin_amdgcn_permlane32_swap(__float_as_uint(ps), __float_as_uint(ps), false, false);
;     ps = __uint_as_float(rr[0]) + __uint_as_float(rr[1]); }
;   l_reg = l_reg * alpha + ps;
; __device__ __forceinline__ void attn_body2(const bf16_t* __restrict__ Qb, const bf16_t* __restrict__ Kh, const bf16_t* __restrict__ Vh, ...
;     ...
;     pv_d0(o, vb0 + SHM_V, pa0, pa1, pa2, pa3); partialSM(pA0, pA1, m_reg, mnA, alA);
;     RESC(alA); WAITV(0); ABAR();
;   }
.LattB_326:
	v_mov_b32_e32 v198, v142
	v_fmamk_f32 v64, v64, 0x3dd53b94, v142
	v_fmamk_f32 v65, v65, 0x3dd53b94, v142
	v_fmamk_f32 v66, v66, 0x3dd53b94, v142
	v_fmamk_f32 v67, v67, 0x3dd53b94, v142
	v_fmamk_f32 v68, v68, 0x3dd53b94, v142
	v_fmamk_f32 v69, v69, 0x3dd53b94, v142
	v_fmamk_f32 v70, v70, 0x3dd53b94, v142
	v_fmamk_f32 v71, v71, 0x3dd53b94, v142
	v_fmamk_f32 v91, v215, 0x3dd53b94, v142
	v_fmamk_f32 v92, v214, 0x3dd53b94, v142
	v_fmamk_f32 v93, v213, 0x3dd53b94, v142
	v_fmamk_f32 v94, v212, 0x3dd53b94, v142
	v_fmamk_f32 v95, v211, 0x3dd53b94, v142
	v_fmamk_f32 v195, v210, 0x3dd53b94, v142
	v_fmamk_f32 v196, v209, 0x3dd53b94, v142
	v_fmac_f32_e32 v198, 0x3dd53b94, v208
	v_exp_f32_e32 v199, v64
	v_exp_f32_e32 v200, v65
	v_exp_f32_e32 v201, v66
	v_exp_f32_e32 v203, v67
	v_exp_f32_e32 v204, v68
	v_exp_f32_e32 v206, v69
	v_exp_f32_e32 v202, v70
	v_exp_f32_e32 v205, v71
	v_exp_f32_e32 v191, v91
	v_exp_f32_e32 v193, v92
	v_exp_f32_e32 v194, v93
	v_exp_f32_e32 v197, v94
	v_exp_f32_e32 v192, v95
	v_exp_f32_e32 v195, v195
	v_exp_f32_e32 v196, v196
	v_exp_f32_e32 v198, v198
	s_waitcnt vmcnt(0)
	v_add_f32_e32 v64, v188, v189
	s_waitcnt lgkmcnt(0)
	s_barrier
	v_fmac_f32_e32 v64, v175, v158
	v_add_f32_e32 v158, v220, v221
	s_addk_i32 s52, 0x80
	s_add_i32 s38, s12, 1
	s_add_i32 s12, s12, 2
	v_pk_fma_f32 v[156:157], v[80:81], s[18:19], v[142:143] op_sel_hi:[1,0,0]
	v_pk_fma_f32 v[154:155], v[82:83], s[18:19], v[142:143] op_sel_hi:[1,0,0]
	v_pk_fma_f32 v[152:153], v[84:85], s[18:19], v[142:143] op_sel_hi:[1,0,0]
	v_pk_fma_f32 v[150:151], v[86:87], s[18:19], v[142:143] op_sel_hi:[1,0,0]
	v_pk_fma_f32 v[148:149], v[78:79], s[18:19], v[142:143] op_sel_hi:[1,0,0]
	v_pk_fma_f32 v[146:147], v[76:77], s[18:19], v[142:143] op_sel_hi:[1,0,0]
	v_pk_fma_f32 v[144:145], v[74:75], s[18:19], v[142:143] op_sel_hi:[1,0,0]
	v_pk_fma_f32 v[142:143], v[72:73], s[18:19], v[142:143] op_sel_hi:[1,0,0]
	v_fmac_f32_e32 v158, v64, v190
	s_cmp_le_u32 s38, s84
	s_cbranch_scc0 .LBB0_329
	v_mov_b32_e32 v175, v88
	s_branch .LattB_317

; __device__ __forceinline__ float bf2f(bf16_t b) { return __uint_as_float(((unsigned)b) << 16); }
; __device__ __forceinline__ float wave_sum(float v) { for (int o = 32; o >= 1; o >>= 1) v += __shfl_xor(v, o); return v; }
;     ...
;   for (int r = gw; r < G.RG; r += nw) {
;     int pos; if (r < NREAL) pos = 16 + (r % G.Ls); else pos = (r - NREAL) & 255;
;     float sn, cs; sincosf((float)pos * inv, &sn, &cs);
;     const float kr = bf2f(b4[(size_t)r * 256 + lane]);
;     for (int h = 0; h < 8; ++h) {
;       { const bf16_t* s = knr + (size_t)r * 1024 + h * 128; float e0 = bf2f(s[lane]), e1 = bf2f(s[64 + lane]), e2 = kr;
;         float ss = wave_sum(e0 * e0 + e1 * e1 + e2 * e2); const float rs = rsqrtf(ss * (1.f / 192.f) + EPS);
;         e0 *= rs * kn0; e1 *= rs * kn1; e2 *= rs * kn2; const float pr = __shfl_xor(e2, 32);
.LBB0_431:
	s_or_b64 exec, exec, s[0:1]
	v_lshlrev_b64 v[24:25], 9, v[0:1]
	v_lshl_add_u64 v[24:25], v[2:3], 0, v[24:25]
	global_load_ushort v23, v[24:25], off
	global_load_ushort v41, v[4:5], off offset:-128
	global_load_ushort v40, v[4:5], off offset:-256
	global_load_ushort v43, v[4:5], off offset:128
	global_load_ushort v42, v[4:5], off offset:0
	global_load_ushort v45, v[4:5], off offset:384
	global_load_ushort v44, v[4:5], off offset:256
	global_load_ushort v47, v[4:5], off offset:640
	global_load_ushort v46, v[4:5], off offset:512
	global_load_ushort v49, v[4:5], off offset:896
	global_load_ushort v48, v[4:5], off offset:768
	global_load_ushort v51, v[4:5], off offset:1152
	global_load_ushort v50, v[4:5], off offset:1024
	global_load_ushort v53, v[4:5], off offset:1408
	global_load_ushort v52, v[4:5], off offset:1280
	global_load_ushort v55, v[4:5], off offset:1664
	global_load_ushort v54, v[4:5], off offset:1536
	v_mul_f32_e32 v1, v21, v21
	v_fmamk_f32 v25, v1, 0xb94c1982, v226
	v_fmamk_f32 v26, v1, 0x37d75334, v227
	v_fmaak_f32 v25, v1, v25, 0xbe2aaa9d
	v_fmaak_f32 v26, v1, v26, 0x3d2aabf7
	v_lshlrev_b32_e32 v24, 30, v22
	v_and_b32_e32 v22, 1, v22
	v_mul_f32_e32 v25, v1, v25
	v_fmaak_f32 v26, v1, v26, 0xbf000004
	v_fmac_f32_e32 v21, v21, v25
	v_fma_f32 v1, v1, v26, 1.0
	v_cmp_eq_u32_e64 s[0:1], 0, v22
	v_xor_b32_e32 v9, v9, v8
	v_and_b32_e32 v27, 0x80000000, v24
	v_cndmask_b32_e64 v22, v1, v21, s[0:1]
	v_xor_b32_e32 v21, 0x80000000, v21
	v_xor_b32_e32 v9, v9, v22
	v_cndmask_b32_e64 v1, v21, v1, s[0:1]
	v_xor_b32_e32 v9, v9, v27
	v_bitop3_b32 v1, v1, v24, s31 bitop3:0x78
	v_cmp_class_f32_e64 s[0:1], v8, s52
	s_mov_b64 s[26:27], 0
	s_waitcnt vmcnt(0)
	v_lshlrev_b32_e32 v22, 16, v23
	v_cndmask_b32_e64 v1, v240, v1, s[0:1]
	v_cndmask_b32_e64 v21, v240, v9, s[0:1]
	v_mul_f32_e32 v23, v22, v22
	v_mov_b64_e32 v[8:9], v[6:7]
	v_lshlrev_b32_e32 v41, 16, v41
	v_lshlrev_b32_e32 v40, 16, v40
	v_lshlrev_b32_e32 v43, 16, v43
	v_lshlrev_b32_e32 v42, 16, v42
	v_lshlrev_b32_e32 v45, 16, v45
	v_lshlrev_b32_e32 v44, 16, v44
	v_lshlrev_b32_e32 v47, 16, v47
	v_lshlrev_b32_e32 v46, 16, v46
	v_lshlrev_b32_e32 v49, 16, v49
	v_lshlrev_b32_e32 v48, 16, v48
	v_lshlrev_b32_e32 v51, 16, v51
	v_lshlrev_b32_e32 v50, 16, v50
	v_lshlrev_b32_e32 v53, 16, v53
	v_lshlrev_b32_e32 v52, 16, v52
	v_lshlrev_b32_e32 v55, 16, v55
	v_lshlrev_b32_e32 v54, 16, v54
	v_mul_f32_e32 v56, v40, v40
	v_mul_f32_e32 v64, v41, v41
	v_mul_f32_e32 v57, v42, v42
	v_mul_f32_e32 v65, v43, v43
	v_mul_f32_e32 v58, v44, v44
	v_mul_f32_e32 v66, v45, v45
	v_mul_f32_e32 v59, v46, v46
	v_mul_f32_e32 v67, v47, v47
	v_mul_f32_e32 v60, v48, v48
	v_mul_f32_e32 v68, v49, v49
	v_mul_f32_e32 v61, v50, v50
	v_mul_f32_e32 v69, v51, v51
	v_mul_f32_e32 v62, v52, v52
	v_mul_f32_e32 v70, v53, v53
	v_mul_f32_e32 v63, v54, v54
	v_mul_f32_e32 v71, v55, v55
	v_add_f32_e32 v56, v56, v64
	v_add_f32_e32 v57, v57, v65
	v_add_f32_e32 v58, v58, v66
	v_add_f32_e32 v59, v59, v67
	v_add_f32_e32 v60, v60, v68
	v_add_f32_e32 v61, v61, v69
	v_add_f32_e32 v62, v62, v70
	v_add_f32_e32 v63, v63, v71
	v_add_f32_e32 v56, v23, v56
	v_add_f32_e32 v57, v23, v57
	v_add_f32_e32 v58, v23, v58
	v_add_f32_e32 v59, v23, v59
	v_add_f32_e32 v60, v23, v60
	v_add_f32_e32 v61, v23, v61
	v_add_f32_e32 v62, v23, v62
	v_add_f32_e32 v63, v23, v63
	ds_bpermute_b32 v64, v14, v56
	ds_bpermute_b32 v65, v14, v57
	ds_bpermute_b32 v66, v14, v58
	ds_bpermute_b32 v67, v14, v59
	ds_bpermute_b32 v68, v14, v60
	ds_bpermute_b32 v69, v14, v61
	ds_bpermute_b32 v70, v14, v62
	ds_bpermute_b32 v71, v14, v63
	s_waitcnt lgkmcnt(0)
	v_add_f32_e32 v56, v56, v64
	v_add_f32_e32 v57, v57, v65
	v_add_f32_e32 v58, v58, v66
	v_add_f32_e32 v59, v59, v67
	v_add_f32_e32 v60, v60, v68
	v_add_f32_e32 v61, v61, v69
	v_add_f32_e32 v62, v62, v70
	v_add_f32_e32 v63, v63, v71
	ds_bpermute_b32 v64, v15, v56
	ds_bpermute_b32 v65, v15, v57
	ds_bpermute_b32 v66, v15, v58
	ds_bpermute_b32 v67, v15, v59
	ds_bpermute_b32 v68, v15, v60
	ds_bpermute_b32 v69, v15, v61
	ds_bpermute_b32 v70, v15, v62
	ds_bpermute_b32 v71, v15, v63
	s_waitcnt lgkmcnt(0)
	v_add_f32_e32 v56, v56, v64
	v_add_f32_e32 v57, v57, v65
	v_add_f32_e32 v58, v58, v66
	v_add_f32_e32 v59, v59, v67
	v_add_f32_e32 v60, v60, v68
	v_add_f32_e32 v61, v61, v69
	v_add_f32_e32 v62, v62, v70
	v_add_f32_e32 v63, v63, v71
	ds_bpermute_b32 v64, v16, v56
	ds_bpermute_b32 v65, v16, v57
	ds_bpermute_b32 v66, v16, v58
	ds_bpermute_b32 v67, v16, v59
	ds_bpermute_b32 v68, v16, v60
	ds_bpermute_b32 v69, v16, v61
	ds_bpermute_b32 v70, v16, v62
	ds_bpermute_b32 v71, v16, v63
	s_waitcnt lgkmcnt(0)
	v_add_f32_e32 v56, v56, v64
	v_add_f32_e32 v57, v57, v65
	v_add_f32_e32 v58, v58, v66
	v_add_f32_e32 v59, v59, v67
	v_add_f32_e32 v60, v60, v68
	v_add_f32_e32 v61, v61, v69
	v_add_f32_e32 v62, v62, v70
	v_add_f32_e32 v63, v63, v71
	ds_bpermute_b32 v64, v17, v56
	ds_bpermute_b32 v65, v17, v57
	ds_bpermute_b32 v66, v17, v58
	ds_bpermute_b32 v67, v17, v59
	ds_bpermute_b32 v68, v17, v60
	ds_bpermute_b32 v69, v17, v61
	ds_bpermute_b32 v70, v17, v62
	ds_bpermute_b32 v71, v17, v63
	s_waitcnt lgkmcnt(0)
	v_add_f32_e32 v56, v56, v64
	v_add_f32_e32 v57, v57, v65
	v_add_f32_e32 v58, v58, v66
	v_add_f32_e32 v59, v59, v67
	v_add_f32_e32 v60, v60, v68
	v_add_f32_e32 v61, v61, v69
	v_add_f32_e32 v62, v62, v70
	v_add_f32_e32 v63, v63, v71
	ds_bpermute_b32 v64, v18, v56
	ds_bpermute_b32 v65, v18, v57
	ds_bpermute_b32 v66, v18, v58
	ds_bpermute_b32 v67, v18, v59
	ds_bpermute_b32 v68, v18, v60
	ds_bpermute_b32 v69, v18, v61
	ds_bpermute_b32 v70, v18, v62
	ds_bpermute_b32 v71, v18, v63
	s_waitcnt lgkmcnt(0)
; __device__ __forceinline__ bf16_t f2bf(float f) { return (bf16_t)(cvtpk(f, 0.f) & 0xffffu); }
; __device__ __forceinline__ float bf2f(bf16_t b) { return __uint_as_float(((unsigned)b) << 16); }
; __device__ __forceinline__ float wave_sum(float v) { for (int o = 32; o >= 1; o >>= 1) v += __shfl_xor(v, o); return v; }
;     ...
;       { const bf16_t* s = knr + (size_t)r * 1024 + h * 128; float e0 = bf2f(s[lane]), e1 = bf2f(s[64 + lane]), e2 = kr;
;         float ss = wave_sum(e0 * e0 + e1 * e1 + e2 * e2); const float rs = rsqrtf(ss * (1.f / 192.f) + EPS);
;         e0 *= rs * kn0; e1 *= rs * kn1; e2 *= rs * kn2; const float pr = __shfl_xor(e2, 32);
;         const float o2 = lane < 32 ? e2 * cs - pr * sn : e2 * cs + pr * sn;
;         bf16_t* d = Kb + (size_t)r * 1536 + h * 192; d[lane] = f2bf(e0); d[64 + lane] = f2bf(e1); d[128 + lane] = f2bf(o2); }
	v_add_f32_e32 v56, v56, v64
	v_add_f32_e32 v57, v57, v65
	v_add_f32_e32 v58, v58, v66
	v_add_f32_e32 v59, v59, v67
	v_add_f32_e32 v60, v60, v68
	v_add_f32_e32 v61, v61, v69
	v_add_f32_e32 v62, v62, v70
	v_add_f32_e32 v63, v63, v71
	ds_bpermute_b32 v64, v19, v56
	ds_bpermute_b32 v65, v19, v57
	ds_bpermute_b32 v66, v19, v58
	ds_bpermute_b32 v67, v19, v59
	ds_bpermute_b32 v68, v19, v60
	ds_bpermute_b32 v69, v19, v61
	ds_bpermute_b32 v70, v19, v62
	ds_bpermute_b32 v71, v19, v63
	s_waitcnt lgkmcnt(0)
	v_add_f32_e32 v56, v56, v64
	v_add_f32_e32 v57, v57, v65
	v_add_f32_e32 v58, v58, v66
	v_add_f32_e32 v59, v59, v67
	v_add_f32_e32 v60, v60, v68
	v_add_f32_e32 v61, v61, v69
	v_add_f32_e32 v62, v62, v70
	v_add_f32_e32 v63, v63, v71
	v_fmamk_f32 v56, v56, 0x3baaaaab, v134
	v_fmamk_f32 v57, v57, 0x3baaaaab, v134
	v_fmamk_f32 v58, v58, 0x3baaaaab, v134
	v_fmamk_f32 v59, v59, 0x3baaaaab, v134
	v_fmamk_f32 v60, v60, 0x3baaaaab, v134
	v_fmamk_f32 v61, v61, 0x3baaaaab, v134
	v_fmamk_f32 v62, v62, 0x3baaaaab, v134
	v_fmamk_f32 v63, v63, 0x3baaaaab, v134
	v_mul_f32_e32 v64, 0x4b800000, v56
	v_mul_f32_e32 v65, 0x4b800000, v57
	v_mul_f32_e32 v66, 0x4b800000, v58
	v_mul_f32_e32 v67, 0x4b800000, v59
	v_mul_f32_e32 v68, 0x4b800000, v60
	v_mul_f32_e32 v69, 0x4b800000, v61
	v_mul_f32_e32 v70, 0x4b800000, v62
	v_mul_f32_e32 v71, 0x4b800000, v63
	v_cmp_gt_f32_e64 s[28:29], s93, v56
	v_cmp_gt_f32_e64 s[68:69], s93, v57
	v_cmp_gt_f32_e64 s[70:71], s93, v58
	v_cmp_gt_f32_e64 s[72:73], s93, v59
	v_cmp_gt_f32_e64 s[76:77], s93, v60
	v_cmp_gt_f32_e64 s[78:79], s93, v61
	v_cmp_gt_f32_e64 s[84:85], s93, v62
	v_cmp_gt_f32_e64 s[86:87], s93, v63
	v_cndmask_b32_e64 v56, v56, v64, s[28:29]
	v_cndmask_b32_e64 v57, v57, v65, s[68:69]
	v_cndmask_b32_e64 v58, v58, v66, s[70:71]
	v_cndmask_b32_e64 v59, v59, v67, s[72:73]
	v_cndmask_b32_e64 v60, v60, v68, s[76:77]
	v_cndmask_b32_e64 v61, v61, v69, s[78:79]
	v_cndmask_b32_e64 v62, v62, v70, s[84:85]
	v_cndmask_b32_e64 v63, v63, v71, s[86:87]
	v_rsq_f32_e32 v56, v56
	v_rsq_f32_e32 v57, v57
	v_rsq_f32_e32 v58, v58
	v_rsq_f32_e32 v59, v59
	v_rsq_f32_e32 v60, v60
	v_rsq_f32_e32 v61, v61
	v_rsq_f32_e32 v62, v62
	v_rsq_f32_e32 v63, v63
	v_mul_f32_e32 v64, 0x45800000, v56
	v_mul_f32_e32 v65, 0x45800000, v57
	v_mul_f32_e32 v66, 0x45800000, v58
	v_mul_f32_e32 v67, 0x45800000, v59
	v_mul_f32_e32 v68, 0x45800000, v60
	v_mul_f32_e32 v69, 0x45800000, v61
	v_mul_f32_e32 v70, 0x45800000, v62
	v_mul_f32_e32 v71, 0x45800000, v63
	v_cndmask_b32_e64 v56, v56, v64, s[28:29]
	v_cndmask_b32_e64 v57, v57, v65, s[68:69]
	v_cndmask_b32_e64 v58, v58, v66, s[70:71]
	v_cndmask_b32_e64 v59, v59, v67, s[72:73]
	v_cndmask_b32_e64 v60, v60, v68, s[76:77]
	v_cndmask_b32_e64 v61, v61, v69, s[78:79]
	v_cndmask_b32_e64 v62, v62, v70, s[84:85]
	v_cndmask_b32_e64 v63, v63, v71, s[86:87]
	v_mul_f32_e32 v64, v12, v56
	v_mul_f32_e32 v65, v12, v57
	v_mul_f32_e32 v66, v12, v58
	v_mul_f32_e32 v67, v12, v59
	v_mul_f32_e32 v68, v12, v60
	v_mul_f32_e32 v69, v12, v61
	v_mul_f32_e32 v70, v12, v62
	v_mul_f32_e32 v71, v12, v63
	v_mul_f32_e32 v64, v64, v22
	v_mul_f32_e32 v65, v65, v22
	v_mul_f32_e32 v66, v66, v22
	v_mul_f32_e32 v67, v67, v22
	v_mul_f32_e32 v68, v68, v22
	v_mul_f32_e32 v69, v69, v22
	v_mul_f32_e32 v70, v70, v22
	v_mul_f32_e32 v71, v71, v22
	ds_bpermute_b32 v72, v14, v64
	ds_bpermute_b32 v73, v14, v65
	ds_bpermute_b32 v74, v14, v66
	ds_bpermute_b32 v75, v14, v67
	ds_bpermute_b32 v76, v14, v68
	ds_bpermute_b32 v77, v14, v69
	ds_bpermute_b32 v78, v14, v70
	ds_bpermute_b32 v79, v14, v71
	v_mul_f32_e32 v36, v10, v56
	v_mul_f32_e32 v37, v11, v56
	v_mul_f32_e32 v40, v36, v40
	v_mul_f32_e32 v41, v37, v41
	v_cvt_pk_bf16_f32 v40, v40, s0
	v_cvt_pk_bf16_f32 v41, v41, s0
	global_store_short v[8:9], v40, off offset:-384
	global_store_short v[8:9], v41, off offset:-256
	v_mul_f32_e32 v36, v10, v57
	v_mul_f32_e32 v37, v11, v57
	v_mul_f32_e32 v42, v36, v42
	v_mul_f32_e32 v43, v37, v43
	v_cvt_pk_bf16_f32 v42, v42, s0
	v_cvt_pk_bf16_f32 v43, v43, s0
	global_store_short v[8:9], v42, off offset:0
	global_store_short v[8:9], v43, off offset:128
	v_mul_f32_e32 v36, v10, v58
	v_mul_f32_e32 v37, v11, v58
	v_mul_f32_e32 v44, v36, v44
	v_mul_f32_e32 v45, v37, v45
	v_cvt_pk_bf16_f32 v44, v44, s0
	v_cvt_pk_bf16_f32 v45, v45, s0
	global_store_short v[8:9], v44, off offset:384
	global_store_short v[8:9], v45, off offset:512
	v_mul_f32_e32 v36, v10, v59
	v_mul_f32_e32 v37, v11, v59
	v_mul_f32_e32 v46, v36, v46
	v_mul_f32_e32 v47, v37, v47
	v_cvt_pk_bf16_f32 v46, v46, s0
	v_cvt_pk_bf16_f32 v47, v47, s0
	global_store_short v[8:9], v46, off offset:768
	global_store_short v[8:9], v47, off offset:896
	v_mul_f32_e32 v36, v10, v60
	v_mul_f32_e32 v37, v11, v60
	v_mul_f32_e32 v48, v36, v48
	v_mul_f32_e32 v49, v37, v49
	v_cvt_pk_bf16_f32 v48, v48, s0
	v_cvt_pk_bf16_f32 v49, v49, s0
	global_store_short v[8:9], v48, off offset:1152
	global_store_short v[8:9], v49, off offset:1280
	v_mul_f32_e32 v36, v10, v61
	v_mul_f32_e32 v37, v11, v61
	v_mul_f32_e32 v50, v36, v50
	v_mul_f32_e32 v51, v37, v51
	v_cvt_pk_bf16_f32 v50, v50, s0
	v_cvt_pk_bf16_f32 v51, v51, s0
	global_store_short v[8:9], v50, off offset:1536
	global_store_short v[8:9], v51, off offset:1664
	v_mul_f32_e32 v36, v10, v62
	v_mul_f32_e32 v37, v11, v62
	v_mul_f32_e32 v52, v36, v52
	v_mul_f32_e32 v53, v37, v53
	v_cvt_pk_bf16_f32 v52, v52, s0
	v_cvt_pk_bf16_f32 v53, v53, s0
	global_store_short v[8:9], v52, off offset:1920
	global_store_short v[8:9], v53, off offset:2048
	v_mul_f32_e32 v36, v10, v63
	v_mul_f32_e32 v37, v11, v63
	v_mul_f32_e32 v54, v36, v54
	v_mul_f32_e32 v55, v37, v55
	v_cvt_pk_bf16_f32 v54, v54, s0
	v_cvt_pk_bf16_f32 v55, v55, s0
	global_store_short v[8:9], v54, off offset:2304
	global_store_short v[8:9], v55, off offset:2432
	s_waitcnt lgkmcnt(0)
; __device__ __forceinline__ bf16_t f2bf(float f) { return (bf16_t)(cvtpk(f, 0.f) & 0xffffu); }
;     ...
;         e0 *= rs * kn0; e1 *= rs * kn1; e2 *= rs * kn2; const float pr = __shfl_xor(e2, 32);
;         const float o2 = lane < 32 ? e2 * cs - pr * sn : e2 * cs + pr * sn;
;         bf16_t* d = Kb + (size_t)r * 1536 + h * 192; d[lane] = f2bf(e0); d[64 + lane] = f2bf(e1); d[128 + lane] = f2bf(o2); }
	v_mul_f32_e32 v72, v21, v72
	v_mul_f32_e32 v73, v21, v73
	v_mul_f32_e32 v74, v21, v74
	v_mul_f32_e32 v75, v21, v75
	v_mul_f32_e32 v76, v21, v76
	v_mul_f32_e32 v77, v21, v77
	v_mul_f32_e32 v78, v21, v78
	v_mul_f32_e32 v79, v21, v79
	v_cndmask_b32_e64 v72, v72, -v72, vcc
	v_cndmask_b32_e64 v73, v73, -v73, vcc
	v_cndmask_b32_e64 v74, v74, -v74, vcc
	v_cndmask_b32_e64 v75, v75, -v75, vcc
	v_cndmask_b32_e64 v76, v76, -v76, vcc
	v_cndmask_b32_e64 v77, v77, -v77, vcc
	v_cndmask_b32_e64 v78, v78, -v78, vcc
	v_cndmask_b32_e64 v79, v79, -v79, vcc
	v_fmac_f32_e32 v72, v1, v64
	v_fmac_f32_e32 v73, v1, v65
	v_fmac_f32_e32 v74, v1, v66
	v_fmac_f32_e32 v75, v1, v67
	v_fmac_f32_e32 v76, v1, v68
	v_fmac_f32_e32 v77, v1, v69
	v_fmac_f32_e32 v78, v1, v70
	v_fmac_f32_e32 v79, v1, v71
	v_cvt_pk_bf16_f32 v72, v72, s0
	global_store_short v[8:9], v72, off offset:-128
	v_cvt_pk_bf16_f32 v73, v73, s0
	global_store_short v[8:9], v73, off offset:256
	v_cvt_pk_bf16_f32 v74, v74, s0
	global_store_short v[8:9], v74, off offset:640
	v_cvt_pk_bf16_f32 v75, v75, s0
	global_store_short v[8:9], v75, off offset:1024
	v_cvt_pk_bf16_f32 v76, v76, s0
	global_store_short v[8:9], v76, off offset:1408
	v_cvt_pk_bf16_f32 v77, v77, s0
	global_store_short v[8:9], v77, off offset:1792
	v_cvt_pk_bf16_f32 v78, v78, s0
	global_store_short v[8:9], v78, off offset:2176
	v_cvt_pk_bf16_f32 v79, v79, s0
	global_store_short v[8:9], v79, off offset:2560
	s_movk_i32 s26, 0x800
	s_cmpk_eq_i32 s26, 0x800
	v_readlane_b32 s0, v254, 15
	v_add_u32_e32 v0, s30, v0
	v_readlane_b32 s1, v254, 16
	v_lshl_add_u64 v[6:7], v[6:7], 0, s[42:43]
	s_nop 0
	v_lshl_add_u64 v[4:5], v[4:5], 0, s[0:1]
	v_cmp_le_i32_e64 s[0:1], s50, v0
	s_or_b64 s[24:25], s[0:1], s[24:25]
	s_andn2_b64 exec, exec, s[24:25]
	s_cbranch_execnz .LBB0_423
